# K-loop trims: no setprio, no redundant lgkmcnt wait at MFMA segment start, LDS-DMA address register used directly (v_mov dropped), merged vmcnt+lgkmcnt waits, hazard nops dropped where another instruc
# speedup vs baseline: 1.0038x; 1.0038x over previous
.LBB0_515:
	v_add_u32_e32 v130, 0x10000, v133
	ds_read_b128 v[136:139], v130
	ds_read_b128 v[140:143], v130 offset:1024
	ds_read_b128 v[144:147], v130 offset:2048
	ds_read_b128 v[148:151], v130 offset:3072
	v_add_u32_e32 v130, 0x14000, v133
	ds_read_b128 v[152:155], v130
	ds_read_b128 v[156:159], v130 offset:1024
	ds_read_b128 v[160:163], v130 offset:2048
	ds_read_b128 v[164:167], v130 offset:3072
	s_cmp_eq_u32 s72, 28
	s_cselect_b32 s18, s60, s64
	s_cselect_b32 s19, s13, s66
	s_cselect_b32 s22, s62, s68
	s_cselect_b32 s23, s11, s70
	s_add_u32 s20, s18, 0x80
	s_addc_u32 s21, s19, 0
	s_add_u32 s74, s64, 0x7ff80
	s_addc_u32 s75, s66, 0
	s_mov_b32 m0, s50
	ds_read_b128 v[168:171], v134
	ds_read_b128 v[172:175], v134 offset:1024
	ds_read_b128 v[176:179], v134 offset:2048
	ds_read_b128 v[180:183], v134 offset:3072
	ds_read_b128 v[184:187], v134 offset:4096
	ds_read_b128 v[188:191], v134 offset:5120
	ds_read_b128 v[192:195], v134 offset:6144
	ds_read_b128 v[196:199], v134 offset:7168
	global_load_lds_dwordx4 v0, s[74:75]
	s_add_u32 s74, s64, 0xbff80
	s_addc_u32 s75, s66, 0
	s_mov_b32 m0, s51
	s_nop 0
	global_load_lds_dwordx4 v0, s[74:75]
	s_waitcnt vmcnt(8) lgkmcnt(0)
	s_barrier
	v_mfma_f32_16x16x32_bf16 v[122:125], v[136:139], v[168:171], v[122:125]
	v_mfma_f32_16x16x32_bf16 v[114:117], v[144:147], v[168:171], v[114:117]
	v_mfma_f32_16x16x32_bf16 v[106:109], v[136:139], v[176:179], v[106:109]
	v_mfma_f32_16x16x32_bf16 v[98:101], v[144:147], v[176:179], v[98:101]
	v_mfma_f32_16x16x32_bf16 v[90:93], v[136:139], v[184:187], v[90:93]
	v_mfma_f32_16x16x32_bf16 v[82:85], v[144:147], v[184:187], v[82:85]
	v_mfma_f32_16x16x32_bf16 v[74:77], v[136:139], v[192:195], v[74:77]
	v_mfma_f32_16x16x32_bf16 v[66:69], v[144:147], v[192:195], v[66:69]
	v_mfma_f32_16x16x32_bf16 v[122:125], v[140:143], v[172:175], v[122:125]
	v_mfma_f32_16x16x32_bf16 v[114:117], v[148:151], v[172:175], v[114:117]
	v_mfma_f32_16x16x32_bf16 v[106:109], v[140:143], v[180:183], v[106:109]
	v_mfma_f32_16x16x32_bf16 v[98:101], v[148:151], v[180:183], v[98:101]
	v_mfma_f32_16x16x32_bf16 v[90:93], v[140:143], v[188:191], v[90:93]
	v_mfma_f32_16x16x32_bf16 v[82:85], v[148:151], v[188:191], v[82:85]
	v_mfma_f32_16x16x32_bf16 v[74:77], v[140:143], v[196:199], v[74:77]
	v_mfma_f32_16x16x32_bf16 v[66:69], v[148:151], v[196:199], v[66:69]
	v_mfma_f32_16x16x32_bf16 v[126:129], v[152:155], v[168:171], v[126:129]
	v_mfma_f32_16x16x32_bf16 v[118:121], v[160:163], v[168:171], v[118:121]
	v_mfma_f32_16x16x32_bf16 v[110:113], v[152:155], v[176:179], v[110:113]
	v_mfma_f32_16x16x32_bf16 v[102:105], v[160:163], v[176:179], v[102:105]
	v_mfma_f32_16x16x32_bf16 v[94:97], v[152:155], v[184:187], v[94:97]
	v_mfma_f32_16x16x32_bf16 v[86:89], v[160:163], v[184:187], v[86:89]
	v_mfma_f32_16x16x32_bf16 v[78:81], v[152:155], v[192:195], v[78:81]
	v_mfma_f32_16x16x32_bf16 v[70:73], v[160:163], v[192:195], v[70:73]
	v_mfma_f32_16x16x32_bf16 v[126:129], v[156:159], v[172:175], v[126:129]
	v_mfma_f32_16x16x32_bf16 v[118:121], v[164:167], v[172:175], v[118:121]
	v_mfma_f32_16x16x32_bf16 v[110:113], v[156:159], v[180:183], v[110:113]
	v_mfma_f32_16x16x32_bf16 v[102:105], v[164:167], v[180:183], v[102:105]
	v_mfma_f32_16x16x32_bf16 v[94:97], v[156:159], v[188:191], v[94:97]
	v_mfma_f32_16x16x32_bf16 v[86:89], v[164:167], v[188:191], v[86:89]
	v_mfma_f32_16x16x32_bf16 v[78:81], v[156:159], v[196:199], v[78:81]
	v_mfma_f32_16x16x32_bf16 v[70:73], v[164:167], v[196:199], v[70:73]
	s_barrier
	s_mov_b64 s[74:75], s[22:23]
	s_mov_b32 m0, s27
	ds_read_b128 v[168:171], v134 offset:16384
	ds_read_b128 v[172:175], v134 offset:17408
	ds_read_b128 v[176:179], v134 offset:18432
	ds_read_b128 v[180:183], v134 offset:19456
	ds_read_b128 v[184:187], v134 offset:20480
	ds_read_b128 v[188:191], v134 offset:21504
	ds_read_b128 v[192:195], v134 offset:22528
	ds_read_b128 v[196:199], v134 offset:23552
	global_load_lds_dwordx4 v132, s[74:75]
	s_add_u32 s74, s22, 0x40000
	s_addc_u32 s75, s23, 0
	s_mov_b32 m0, s28
	s_nop 0
	global_load_lds_dwordx4 v132, s[74:75]
	s_add_u32 s74, s22, 0x80000
	s_addc_u32 s75, s23, 0
	s_mov_b32 m0, s29
	s_nop 0
	global_load_lds_dwordx4 v132, s[74:75]
	s_add_u32 s74, s22, 0xc0000
	s_addc_u32 s75, s23, 0
	s_mov_b32 m0, s30
	s_nop 0
	global_load_lds_dwordx4 v132, s[74:75]
	s_mov_b64 s[74:75], s[18:19]
	s_mov_b32 m0, s26
	s_nop 0
	global_load_lds_dwordx4 v0, s[74:75]
	s_add_u32 s74, s18, 0x40000
	s_addc_u32 s75, s19, 0
	s_mov_b32 m0, s31
	s_nop 0
	global_load_lds_dwordx4 v0, s[74:75]
	s_waitcnt vmcnt(8) lgkmcnt(0)
	s_barrier
	v_mfma_f32_16x16x32_bf16 v[58:61], v[136:139], v[168:171], v[58:61]
	v_mfma_f32_16x16x32_bf16 v[50:53], v[144:147], v[168:171], v[50:53]
	v_mfma_f32_16x16x32_bf16 v[42:45], v[136:139], v[176:179], v[42:45]
	v_mfma_f32_16x16x32_bf16 v[34:37], v[144:147], v[176:179], v[34:37]
	v_mfma_f32_16x16x32_bf16 v[26:29], v[136:139], v[184:187], v[26:29]
	v_mfma_f32_16x16x32_bf16 v[18:21], v[144:147], v[184:187], v[18:21]
	v_mfma_f32_16x16x32_bf16 v[10:13], v[136:139], v[192:195], v[10:13]
	v_mfma_f32_16x16x32_bf16 v[2:5], v[144:147], v[192:195], v[2:5]
	v_mfma_f32_16x16x32_bf16 v[58:61], v[140:143], v[172:175], v[58:61]
	v_mfma_f32_16x16x32_bf16 v[50:53], v[148:151], v[172:175], v[50:53]
	v_mfma_f32_16x16x32_bf16 v[42:45], v[140:143], v[180:183], v[42:45]
	v_mfma_f32_16x16x32_bf16 v[34:37], v[148:151], v[180:183], v[34:37]
	v_mfma_f32_16x16x32_bf16 v[26:29], v[140:143], v[188:191], v[26:29]
	v_mfma_f32_16x16x32_bf16 v[18:21], v[148:151], v[188:191], v[18:21]
	v_mfma_f32_16x16x32_bf16 v[10:13], v[140:143], v[196:199], v[10:13]
	v_mfma_f32_16x16x32_bf16 v[2:5], v[148:151], v[196:199], v[2:5]
	v_mfma_f32_16x16x32_bf16 v[62:65], v[152:155], v[168:171], v[62:65]
	v_mfma_f32_16x16x32_bf16 v[54:57], v[160:163], v[168:171], v[54:57]
	v_mfma_f32_16x16x32_bf16 v[46:49], v[152:155], v[176:179], v[46:49]
	v_mfma_f32_16x16x32_bf16 v[38:41], v[160:163], v[176:179], v[38:41]
	v_mfma_f32_16x16x32_bf16 v[30:33], v[152:155], v[184:187], v[30:33]
	v_mfma_f32_16x16x32_bf16 v[22:25], v[160:163], v[184:187], v[22:25]
	v_mfma_f32_16x16x32_bf16 v[14:17], v[152:155], v[192:195], v[14:17]
	v_mfma_f32_16x16x32_bf16 v[6:9], v[160:163], v[192:195], v[6:9]
	v_mfma_f32_16x16x32_bf16 v[62:65], v[156:159], v[172:175], v[62:65]
	v_mfma_f32_16x16x32_bf16 v[54:57], v[164:167], v[172:175], v[54:57]
	v_mfma_f32_16x16x32_bf16 v[46:49], v[156:159], v[180:183], v[46:49]
	v_mfma_f32_16x16x32_bf16 v[38:41], v[164:167], v[180:183], v[38:41]
	v_mfma_f32_16x16x32_bf16 v[30:33], v[156:159], v[188:191], v[30:33]
	v_mfma_f32_16x16x32_bf16 v[22:25], v[164:167], v[188:191], v[22:25]
	v_mfma_f32_16x16x32_bf16 v[14:17], v[156:159], v[196:199], v[14:17]
	v_mfma_f32_16x16x32_bf16 v[6:9], v[164:167], v[196:199], v[6:9]
	s_barrier
	v_add_u32_e32 v130, 0x18000, v133
	ds_read_b128 v[136:139], v130
	ds_read_b128 v[140:143], v130 offset:1024
	ds_read_b128 v[144:147], v130 offset:2048
	ds_read_b128 v[148:151], v130 offset:3072
	v_add_u32_e32 v130, 0x1c000, v133
	ds_read_b128 v[152:155], v130
	ds_read_b128 v[156:159], v130 offset:1024
	ds_read_b128 v[160:163], v130 offset:2048
	ds_read_b128 v[164:167], v130 offset:3072
	s_add_u32 s74, s18, 0x80000
	s_addc_u32 s75, s19, 0
	s_mov_b32 m0, s34
	ds_read_b128 v[168:171], v134 offset:32768
	ds_read_b128 v[172:175], v134 offset:33792
	ds_read_b128 v[176:179], v134 offset:34816
	ds_read_b128 v[180:183], v134 offset:35840
	ds_read_b128 v[184:187], v134 offset:36864
	ds_read_b128 v[188:191], v134 offset:37888
	ds_read_b128 v[192:195], v134 offset:38912
	ds_read_b128 v[196:199], v134 offset:39936
	global_load_lds_dwordx4 v0, s[74:75]
	s_add_u32 s74, s18, 0xc0000
	s_addc_u32 s75, s19, 0
	s_mov_b32 m0, s35
	s_nop 0
	global_load_lds_dwordx4 v0, s[74:75]
	s_waitcnt vmcnt(8) lgkmcnt(0)
	s_barrier
	v_mfma_f32_16x16x32_bf16 v[122:125], v[136:139], v[168:171], v[122:125]
	v_mfma_f32_16x16x32_bf16 v[114:117], v[144:147], v[168:171], v[114:117]
	v_mfma_f32_16x16x32_bf16 v[106:109], v[136:139], v[176:179], v[106:109]
	v_mfma_f32_16x16x32_bf16 v[98:101], v[144:147], v[176:179], v[98:101]
	v_mfma_f32_16x16x32_bf16 v[90:93], v[136:139], v[184:187], v[90:93]
	v_mfma_f32_16x16x32_bf16 v[82:85], v[144:147], v[184:187], v[82:85]
	v_mfma_f32_16x16x32_bf16 v[74:77], v[136:139], v[192:195], v[74:77]
	v_mfma_f32_16x16x32_bf16 v[66:69], v[144:147], v[192:195], v[66:69]
	v_mfma_f32_16x16x32_bf16 v[122:125], v[140:143], v[172:175], v[122:125]
	v_mfma_f32_16x16x32_bf16 v[114:117], v[148:151], v[172:175], v[114:117]
	v_mfma_f32_16x16x32_bf16 v[106:109], v[140:143], v[180:183], v[106:109]
	v_mfma_f32_16x16x32_bf16 v[98:101], v[148:151], v[180:183], v[98:101]
	v_mfma_f32_16x16x32_bf16 v[90:93], v[140:143], v[188:191], v[90:93]
	v_mfma_f32_16x16x32_bf16 v[82:85], v[148:151], v[188:191], v[82:85]
	v_mfma_f32_16x16x32_bf16 v[74:77], v[140:143], v[196:199], v[74:77]
	v_mfma_f32_16x16x32_bf16 v[66:69], v[148:151], v[196:199], v[66:69]
	v_mfma_f32_16x16x32_bf16 v[126:129], v[152:155], v[168:171], v[126:129]
	v_mfma_f32_16x16x32_bf16 v[118:121], v[160:163], v[168:171], v[118:121]
	v_mfma_f32_16x16x32_bf16 v[110:113], v[152:155], v[176:179], v[110:113]
	v_mfma_f32_16x16x32_bf16 v[102:105], v[160:163], v[176:179], v[102:105]
	v_mfma_f32_16x16x32_bf16 v[94:97], v[152:155], v[184:187], v[94:97]
	v_mfma_f32_16x16x32_bf16 v[86:89], v[160:163], v[184:187], v[86:89]
	v_mfma_f32_16x16x32_bf16 v[78:81], v[152:155], v[192:195], v[78:81]
	v_mfma_f32_16x16x32_bf16 v[70:73], v[160:163], v[192:195], v[70:73]
	v_mfma_f32_16x16x32_bf16 v[126:129], v[156:159], v[172:175], v[126:129]
	v_mfma_f32_16x16x32_bf16 v[118:121], v[164:167], v[172:175], v[118:121]
	v_mfma_f32_16x16x32_bf16 v[110:113], v[156:159], v[180:183], v[110:113]
	v_mfma_f32_16x16x32_bf16 v[102:105], v[164:167], v[180:183], v[102:105]
	v_mfma_f32_16x16x32_bf16 v[94:97], v[156:159], v[188:191], v[94:97]
	v_mfma_f32_16x16x32_bf16 v[86:89], v[164:167], v[188:191], v[86:89]
	v_mfma_f32_16x16x32_bf16 v[78:81], v[156:159], v[196:199], v[78:81]
	v_mfma_f32_16x16x32_bf16 v[70:73], v[164:167], v[196:199], v[70:73]
	s_barrier
	s_add_u32 s74, s22, 0x80
	s_addc_u32 s75, s23, 0
	s_mov_b32 m0, s38
	ds_read_b128 v[168:171], v134 offset:49152
	ds_read_b128 v[172:175], v134 offset:50176
	ds_read_b128 v[176:179], v134 offset:51200
	ds_read_b128 v[180:183], v134 offset:52224
	ds_read_b128 v[184:187], v134 offset:53248
	ds_read_b128 v[188:191], v134 offset:54272
	ds_read_b128 v[192:195], v134 offset:55296
	ds_read_b128 v[196:199], v134 offset:56320
	global_load_lds_dwordx4 v132, s[74:75]
	s_add_u32 s74, s22, 0x40080
	s_addc_u32 s75, s23, 0
	s_mov_b32 m0, s39
	s_nop 0
	global_load_lds_dwordx4 v132, s[74:75]
	s_add_u32 s74, s22, 0x80080
	s_addc_u32 s75, s23, 0
	s_mov_b32 m0, s42
	s_add_u32 s22, s22, 0xc0080
	global_load_lds_dwordx4 v132, s[74:75]
	s_addc_u32 s23, s23, 0
	s_mov_b32 m0, s43
	s_add_u32 s18, s18, 0x40080
	global_load_lds_dwordx4 v132, s[22:23]
	s_mov_b32 m0, s40
	s_addc_u32 s19, s19, 0
	global_load_lds_dwordx4 v0, s[20:21]
	s_mov_b32 m0, s41
	s_nop 0
	global_load_lds_dwordx4 v0, s[18:19]
	s_waitcnt vmcnt(8) lgkmcnt(0)
	s_barrier
	v_mfma_f32_16x16x32_bf16 v[58:61], v[136:139], v[168:171], v[58:61]
	v_mfma_f32_16x16x32_bf16 v[50:53], v[144:147], v[168:171], v[50:53]
	v_mfma_f32_16x16x32_bf16 v[42:45], v[136:139], v[176:179], v[42:45]
	v_mfma_f32_16x16x32_bf16 v[34:37], v[144:147], v[176:179], v[34:37]
	v_mfma_f32_16x16x32_bf16 v[26:29], v[136:139], v[184:187], v[26:29]
	v_mfma_f32_16x16x32_bf16 v[18:21], v[144:147], v[184:187], v[18:21]
	v_mfma_f32_16x16x32_bf16 v[10:13], v[136:139], v[192:195], v[10:13]
	v_mfma_f32_16x16x32_bf16 v[2:5], v[144:147], v[192:195], v[2:5]
	v_mfma_f32_16x16x32_bf16 v[58:61], v[140:143], v[172:175], v[58:61]
	v_mfma_f32_16x16x32_bf16 v[50:53], v[148:151], v[172:175], v[50:53]
	v_mfma_f32_16x16x32_bf16 v[42:45], v[140:143], v[180:183], v[42:45]
	v_mfma_f32_16x16x32_bf16 v[34:37], v[148:151], v[180:183], v[34:37]
	v_mfma_f32_16x16x32_bf16 v[26:29], v[140:143], v[188:191], v[26:29]
	v_mfma_f32_16x16x32_bf16 v[18:21], v[148:151], v[188:191], v[18:21]
	v_mfma_f32_16x16x32_bf16 v[10:13], v[140:143], v[196:199], v[10:13]
	v_mfma_f32_16x16x32_bf16 v[2:5], v[148:151], v[196:199], v[2:5]
	v_mfma_f32_16x16x32_bf16 v[62:65], v[152:155], v[168:171], v[62:65]
	v_mfma_f32_16x16x32_bf16 v[54:57], v[160:163], v[168:171], v[54:57]
	v_mfma_f32_16x16x32_bf16 v[46:49], v[152:155], v[176:179], v[46:49]
	v_mfma_f32_16x16x32_bf16 v[38:41], v[160:163], v[176:179], v[38:41]
	v_mfma_f32_16x16x32_bf16 v[30:33], v[152:155], v[184:187], v[30:33]
	v_mfma_f32_16x16x32_bf16 v[22:25], v[160:163], v[184:187], v[22:25]
	v_mfma_f32_16x16x32_bf16 v[14:17], v[152:155], v[192:195], v[14:17]
	v_mfma_f32_16x16x32_bf16 v[6:9], v[160:163], v[192:195], v[6:9]
	v_mfma_f32_16x16x32_bf16 v[62:65], v[156:159], v[172:175], v[62:65]
	v_mfma_f32_16x16x32_bf16 v[54:57], v[164:167], v[172:175], v[54:57]
	v_mfma_f32_16x16x32_bf16 v[46:49], v[156:159], v[180:183], v[46:49]
	v_mfma_f32_16x16x32_bf16 v[38:41], v[164:167], v[180:183], v[38:41]
	v_mfma_f32_16x16x32_bf16 v[30:33], v[156:159], v[188:191], v[30:33]
	v_mfma_f32_16x16x32_bf16 v[22:25], v[164:167], v[188:191], v[22:25]
	v_mfma_f32_16x16x32_bf16 v[14:17], v[156:159], v[196:199], v[14:17]
	v_mfma_f32_16x16x32_bf16 v[6:9], v[164:167], v[196:199], v[6:9]
	s_barrier
	s_add_i32 s72, s72, 2
	s_add_u32 s64, s64, 0x100
	s_addc_u32 s66, s66, 0
	s_add_u32 s68, s68, 0x100
	s_addc_u32 s70, s70, 0
	s_cmp_gt_u32 s72, 29
	s_cbranch_scc0 .LBB0_515
	s_and_b64 vcc, exec, s[8:9]
	s_cbranch_vccz .LBB0_518
	s_barrier

.LBB0_650:
	v_add_u32_e32 v174, 0x14000, v223
	v_add_u32_e32 v190, 0x18000, v223
	ds_read_b128 v[162:165], v174
	ds_read_b128 v[166:169], v174 offset:1024
	ds_read_b128 v[170:173], v174 offset:2048
	ds_read_b128 v[174:177], v174 offset:3072
	ds_read_b128 v[178:181], v190
	ds_read_b128 v[182:185], v190 offset:1024
	ds_read_b128 v[186:189], v190 offset:2048
	ds_read_b128 v[190:193], v190 offset:3072
	s_add_u32 s6, s4, 0xffe52080
	s_addc_u32 s7, s5, -1
	s_cmpk_eq_i32 s84, 0x52
	s_cselect_b32 s6, s22, s6
	s_cselect_b32 s7, s23, s7
	s_cselect_b32 s12, s24, s70
	s_cselect_b32 s13, s25, s72
	s_add_u32 s10, s6, 0x80
	s_addc_u32 s11, s7, 0
	s_mov_b64 s[74:75], s[4:5]
	ds_read_b128 v[194:197], v221
	ds_read_b128 v[198:201], v221 offset:1024
	ds_read_b128 v[202:205], v221 offset:2048
	ds_read_b128 v[206:209], v221 offset:3072
	ds_read_b128 v[210:213], v221 offset:4096
	ds_read_b128 v[214:217], v221 offset:5120
	ds_read_b128 v[228:231], v221 offset:6144
	ds_read_b128 v[238:241], v221 offset:7168
	ds_read_b128 v[242:245], v221 offset:8192
	ds_read_b128 v[246:249], v221 offset:9216
	s_add_i32 m0, s28, 0xf000
	s_nop 0
	global_load_lds_dwordx4 v0, s[74:75]
	s_add_u32 s74, s4, 0xac000
	s_addc_u32 s75, s5, 0
	s_mov_b32 m0, s58
	s_nop 0
	global_load_lds_dwordx4 v0, s[74:75]
	s_waitcnt vmcnt(8) lgkmcnt(0)
	s_barrier
	v_mfma_f32_16x16x32_bf16 v[158:161], v[162:165], v[194:197], v[158:161]
	v_mfma_f32_16x16x32_bf16 v[154:157], v[170:173], v[194:197], v[154:157]
	v_mfma_f32_16x16x32_bf16 v[142:145], v[162:165], v[202:205], v[142:145]
	v_mfma_f32_16x16x32_bf16 v[138:141], v[170:173], v[202:205], v[138:141]
	v_mfma_f32_16x16x32_bf16 v[126:129], v[162:165], v[210:213], v[126:129]
	v_mfma_f32_16x16x32_bf16 v[122:125], v[170:173], v[210:213], v[122:125]
	v_mfma_f32_16x16x32_bf16 v[110:113], v[162:165], v[228:231], v[110:113]
	v_mfma_f32_16x16x32_bf16 v[106:109], v[170:173], v[228:231], v[106:109]
	v_mfma_f32_16x16x32_bf16 v[94:97], v[162:165], v[242:245], v[94:97]
	v_mfma_f32_16x16x32_bf16 v[90:93], v[170:173], v[242:245], v[90:93]
	v_mfma_f32_16x16x32_bf16 v[158:161], v[166:169], v[198:201], v[158:161]
	v_mfma_f32_16x16x32_bf16 v[154:157], v[174:177], v[198:201], v[154:157]
	v_mfma_f32_16x16x32_bf16 v[142:145], v[166:169], v[206:209], v[142:145]
	v_mfma_f32_16x16x32_bf16 v[138:141], v[174:177], v[206:209], v[138:141]
	v_mfma_f32_16x16x32_bf16 v[126:129], v[166:169], v[214:217], v[126:129]
	v_mfma_f32_16x16x32_bf16 v[122:125], v[174:177], v[214:217], v[122:125]
	v_mfma_f32_16x16x32_bf16 v[110:113], v[166:169], v[238:241], v[110:113]
	v_mfma_f32_16x16x32_bf16 v[106:109], v[174:177], v[238:241], v[106:109]
	v_mfma_f32_16x16x32_bf16 v[94:97], v[166:169], v[246:249], v[94:97]
	v_mfma_f32_16x16x32_bf16 v[90:93], v[174:177], v[246:249], v[90:93]
	v_mfma_f32_16x16x32_bf16 v[150:153], v[178:181], v[194:197], v[150:153]
	v_mfma_f32_16x16x32_bf16 v[146:149], v[186:189], v[194:197], v[146:149]
	v_mfma_f32_16x16x32_bf16 v[134:137], v[178:181], v[202:205], v[134:137]
	v_mfma_f32_16x16x32_bf16 v[130:133], v[186:189], v[202:205], v[130:133]
	v_mfma_f32_16x16x32_bf16 v[118:121], v[178:181], v[210:213], v[118:121]
	v_mfma_f32_16x16x32_bf16 v[114:117], v[186:189], v[210:213], v[114:117]
	v_mfma_f32_16x16x32_bf16 v[102:105], v[178:181], v[228:231], v[102:105]
	v_mfma_f32_16x16x32_bf16 v[98:101], v[186:189], v[228:231], v[98:101]
	v_mfma_f32_16x16x32_bf16 v[86:89], v[178:181], v[242:245], v[86:89]
	v_mfma_f32_16x16x32_bf16 v[82:85], v[186:189], v[242:245], v[82:85]
	v_mfma_f32_16x16x32_bf16 v[150:153], v[182:185], v[198:201], v[150:153]
	v_mfma_f32_16x16x32_bf16 v[146:149], v[190:193], v[198:201], v[146:149]
	v_mfma_f32_16x16x32_bf16 v[134:137], v[182:185], v[206:209], v[134:137]
	v_mfma_f32_16x16x32_bf16 v[130:133], v[190:193], v[206:209], v[130:133]
	v_mfma_f32_16x16x32_bf16 v[118:121], v[182:185], v[214:217], v[118:121]
	v_mfma_f32_16x16x32_bf16 v[114:117], v[190:193], v[214:217], v[114:117]
	v_mfma_f32_16x16x32_bf16 v[102:105], v[182:185], v[238:241], v[102:105]
	v_mfma_f32_16x16x32_bf16 v[98:101], v[190:193], v[238:241], v[98:101]
	v_mfma_f32_16x16x32_bf16 v[86:89], v[182:185], v[246:249], v[86:89]
	v_mfma_f32_16x16x32_bf16 v[82:85], v[190:193], v[246:249], v[82:85]
	s_barrier
	s_mov_b64 s[74:75], s[12:13]
	s_mov_b32 m0, s29
	ds_read_b128 v[194:197], v221 offset:20480
	ds_read_b128 v[198:201], v221 offset:21504
	ds_read_b128 v[202:205], v221 offset:22528
	ds_read_b128 v[206:209], v221 offset:23552
	ds_read_b128 v[210:213], v221 offset:24576
	ds_read_b128 v[214:217], v221 offset:25600
	ds_read_b128 v[228:231], v221 offset:26624
	ds_read_b128 v[238:241], v221 offset:27648
	ds_read_b128 v[242:245], v221 offset:28672
	ds_read_b128 v[246:249], v221 offset:29696
	global_load_lds_dwordx4 v220, s[74:75]
	s_add_u32 s74, s12, 0xac000
	s_addc_u32 s75, s13, 0
	s_mov_b32 m0, s30
	s_nop 0
	global_load_lds_dwordx4 v220, s[74:75]
	s_add_u32 s74, s12, 0x158000
	s_addc_u32 s75, s13, 0
	s_mov_b32 m0, s31
	s_nop 0
	global_load_lds_dwordx4 v220, s[74:75]
	s_add_u32 s74, s12, 0x204000
	s_addc_u32 s75, s13, 0
	s_mov_b32 m0, s34
	s_nop 0
	global_load_lds_dwordx4 v220, s[74:75]
	s_mov_b64 s[74:75], s[6:7]
	s_mov_b32 m0, s28
	s_nop 0
	global_load_lds_dwordx4 v0, s[74:75]
	s_add_u32 s74, s6, 0xac000
	s_addc_u32 s75, s7, 0
	s_mov_b32 m0, s35
	s_nop 0
	global_load_lds_dwordx4 v0, s[74:75]
	s_waitcnt vmcnt(8) lgkmcnt(0)
	s_barrier
	v_mfma_f32_16x16x32_bf16 v[78:81], v[162:165], v[194:197], v[78:81]
	v_mfma_f32_16x16x32_bf16 v[74:77], v[170:173], v[194:197], v[74:77]
	v_mfma_f32_16x16x32_bf16 v[62:65], v[162:165], v[202:205], v[62:65]
	v_mfma_f32_16x16x32_bf16 v[58:61], v[170:173], v[202:205], v[58:61]
	v_mfma_f32_16x16x32_bf16 v[46:49], v[162:165], v[210:213], v[46:49]
	v_mfma_f32_16x16x32_bf16 v[42:45], v[170:173], v[210:213], v[42:45]
	v_mfma_f32_16x16x32_bf16 v[30:33], v[162:165], v[228:231], v[30:33]
	v_mfma_f32_16x16x32_bf16 v[26:29], v[170:173], v[228:231], v[26:29]
	v_mfma_f32_16x16x32_bf16 v[14:17], v[162:165], v[242:245], v[14:17]
	v_mfma_f32_16x16x32_bf16 v[10:13], v[170:173], v[242:245], v[10:13]
	v_mfma_f32_16x16x32_bf16 v[78:81], v[166:169], v[198:201], v[78:81]
	v_mfma_f32_16x16x32_bf16 v[74:77], v[174:177], v[198:201], v[74:77]
	v_mfma_f32_16x16x32_bf16 v[62:65], v[166:169], v[206:209], v[62:65]
	v_mfma_f32_16x16x32_bf16 v[58:61], v[174:177], v[206:209], v[58:61]
	v_mfma_f32_16x16x32_bf16 v[46:49], v[166:169], v[214:217], v[46:49]
	v_mfma_f32_16x16x32_bf16 v[42:45], v[174:177], v[214:217], v[42:45]
	v_mfma_f32_16x16x32_bf16 v[30:33], v[166:169], v[238:241], v[30:33]
	v_mfma_f32_16x16x32_bf16 v[26:29], v[174:177], v[238:241], v[26:29]
	v_mfma_f32_16x16x32_bf16 v[14:17], v[166:169], v[246:249], v[14:17]
	v_mfma_f32_16x16x32_bf16 v[10:13], v[174:177], v[246:249], v[10:13]
	v_mfma_f32_16x16x32_bf16 v[70:73], v[178:181], v[194:197], v[70:73]
	v_mfma_f32_16x16x32_bf16 v[66:69], v[186:189], v[194:197], v[66:69]
	v_mfma_f32_16x16x32_bf16 v[54:57], v[178:181], v[202:205], v[54:57]
	v_mfma_f32_16x16x32_bf16 v[50:53], v[186:189], v[202:205], v[50:53]
	v_mfma_f32_16x16x32_bf16 v[38:41], v[178:181], v[210:213], v[38:41]
	v_mfma_f32_16x16x32_bf16 v[34:37], v[186:189], v[210:213], v[34:37]
	v_mfma_f32_16x16x32_bf16 v[22:25], v[178:181], v[228:231], v[22:25]
	v_mfma_f32_16x16x32_bf16 v[18:21], v[186:189], v[228:231], v[18:21]
	v_mfma_f32_16x16x32_bf16 v[6:9], v[178:181], v[242:245], v[6:9]
	v_mfma_f32_16x16x32_bf16 v[2:5], v[186:189], v[242:245], v[2:5]
	v_mfma_f32_16x16x32_bf16 v[70:73], v[182:185], v[198:201], v[70:73]
	v_mfma_f32_16x16x32_bf16 v[66:69], v[190:193], v[198:201], v[66:69]
	v_mfma_f32_16x16x32_bf16 v[54:57], v[182:185], v[206:209], v[54:57]
	v_mfma_f32_16x16x32_bf16 v[50:53], v[190:193], v[206:209], v[50:53]
	v_mfma_f32_16x16x32_bf16 v[38:41], v[182:185], v[214:217], v[38:41]
	v_mfma_f32_16x16x32_bf16 v[34:37], v[190:193], v[214:217], v[34:37]
	v_mfma_f32_16x16x32_bf16 v[22:25], v[182:185], v[238:241], v[22:25]
	v_mfma_f32_16x16x32_bf16 v[18:21], v[190:193], v[238:241], v[18:21]
	v_mfma_f32_16x16x32_bf16 v[6:9], v[182:185], v[246:249], v[6:9]
	v_mfma_f32_16x16x32_bf16 v[2:5], v[190:193], v[246:249], v[2:5]
	s_barrier
	v_add_u32_e32 v174, 0x1c000, v223
	v_add_u32_e32 v190, 0x20000, v223
	ds_read_b128 v[162:165], v174
	ds_read_b128 v[166:169], v174 offset:1024
	ds_read_b128 v[170:173], v174 offset:2048
	ds_read_b128 v[174:177], v174 offset:3072
	ds_read_b128 v[178:181], v190
	ds_read_b128 v[182:185], v190 offset:1024
	ds_read_b128 v[186:189], v190 offset:2048
	ds_read_b128 v[190:193], v190 offset:3072
	s_add_u32 s74, s6, 0x1ae000
	s_addc_u32 s75, s7, 0
	s_mov_b32 m0, s36
	ds_read_b128 v[194:197], v221 offset:40960
	ds_read_b128 v[198:201], v221 offset:41984
	ds_read_b128 v[202:205], v221 offset:43008
	ds_read_b128 v[206:209], v221 offset:44032
	ds_read_b128 v[210:213], v221 offset:45056
	ds_read_b128 v[214:217], v221 offset:46080
	ds_read_b128 v[228:231], v221 offset:47104
	ds_read_b128 v[238:241], v221 offset:48128
	ds_read_b128 v[242:245], v221 offset:49152
	ds_read_b128 v[246:249], v221 offset:50176
	global_load_lds_dwordx4 v0, s[74:75]
	s_add_u32 s74, s6, 0x25a000
	s_addc_u32 s75, s7, 0
	s_mov_b32 m0, s37
	s_nop 0
	global_load_lds_dwordx4 v0, s[74:75]
	s_waitcnt vmcnt(8) lgkmcnt(0)
	s_barrier
	v_mfma_f32_16x16x32_bf16 v[158:161], v[162:165], v[194:197], v[158:161]
	v_mfma_f32_16x16x32_bf16 v[154:157], v[170:173], v[194:197], v[154:157]
	v_mfma_f32_16x16x32_bf16 v[142:145], v[162:165], v[202:205], v[142:145]
	v_mfma_f32_16x16x32_bf16 v[138:141], v[170:173], v[202:205], v[138:141]
	v_mfma_f32_16x16x32_bf16 v[126:129], v[162:165], v[210:213], v[126:129]
	v_mfma_f32_16x16x32_bf16 v[122:125], v[170:173], v[210:213], v[122:125]
	v_mfma_f32_16x16x32_bf16 v[110:113], v[162:165], v[228:231], v[110:113]
	v_mfma_f32_16x16x32_bf16 v[106:109], v[170:173], v[228:231], v[106:109]
	v_mfma_f32_16x16x32_bf16 v[94:97], v[162:165], v[242:245], v[94:97]
	v_mfma_f32_16x16x32_bf16 v[90:93], v[170:173], v[242:245], v[90:93]
	v_mfma_f32_16x16x32_bf16 v[158:161], v[166:169], v[198:201], v[158:161]
	v_mfma_f32_16x16x32_bf16 v[154:157], v[174:177], v[198:201], v[154:157]
	v_mfma_f32_16x16x32_bf16 v[142:145], v[166:169], v[206:209], v[142:145]
	v_mfma_f32_16x16x32_bf16 v[138:141], v[174:177], v[206:209], v[138:141]
	v_mfma_f32_16x16x32_bf16 v[126:129], v[166:169], v[214:217], v[126:129]
	v_mfma_f32_16x16x32_bf16 v[122:125], v[174:177], v[214:217], v[122:125]
	v_mfma_f32_16x16x32_bf16 v[110:113], v[166:169], v[238:241], v[110:113]
	v_mfma_f32_16x16x32_bf16 v[106:109], v[174:177], v[238:241], v[106:109]
	v_mfma_f32_16x16x32_bf16 v[94:97], v[166:169], v[246:249], v[94:97]
	v_mfma_f32_16x16x32_bf16 v[90:93], v[174:177], v[246:249], v[90:93]
	v_mfma_f32_16x16x32_bf16 v[150:153], v[178:181], v[194:197], v[150:153]
	v_mfma_f32_16x16x32_bf16 v[146:149], v[186:189], v[194:197], v[146:149]
	v_mfma_f32_16x16x32_bf16 v[134:137], v[178:181], v[202:205], v[134:137]
	v_mfma_f32_16x16x32_bf16 v[130:133], v[186:189], v[202:205], v[130:133]
	v_mfma_f32_16x16x32_bf16 v[118:121], v[178:181], v[210:213], v[118:121]
	v_mfma_f32_16x16x32_bf16 v[114:117], v[186:189], v[210:213], v[114:117]
	v_mfma_f32_16x16x32_bf16 v[102:105], v[178:181], v[228:231], v[102:105]
	v_mfma_f32_16x16x32_bf16 v[98:101], v[186:189], v[228:231], v[98:101]
	v_mfma_f32_16x16x32_bf16 v[86:89], v[178:181], v[242:245], v[86:89]
	v_mfma_f32_16x16x32_bf16 v[82:85], v[186:189], v[242:245], v[82:85]
	v_mfma_f32_16x16x32_bf16 v[150:153], v[182:185], v[198:201], v[150:153]
	v_mfma_f32_16x16x32_bf16 v[146:149], v[190:193], v[198:201], v[146:149]
	v_mfma_f32_16x16x32_bf16 v[134:137], v[182:185], v[206:209], v[134:137]
	v_mfma_f32_16x16x32_bf16 v[130:133], v[190:193], v[206:209], v[130:133]
	v_mfma_f32_16x16x32_bf16 v[118:121], v[182:185], v[214:217], v[118:121]
	v_mfma_f32_16x16x32_bf16 v[114:117], v[190:193], v[214:217], v[114:117]
	v_mfma_f32_16x16x32_bf16 v[102:105], v[182:185], v[238:241], v[102:105]
	v_mfma_f32_16x16x32_bf16 v[98:101], v[190:193], v[238:241], v[98:101]
	v_mfma_f32_16x16x32_bf16 v[86:89], v[182:185], v[246:249], v[86:89]
	v_mfma_f32_16x16x32_bf16 v[82:85], v[190:193], v[246:249], v[82:85]
	s_barrier
	s_add_u32 s74, s12, 0x80
	s_addc_u32 s75, s13, 0
	s_mov_b32 m0, s40
	ds_read_b128 v[194:197], v221 offset:61440
	ds_read_b128 v[198:201], v221 offset:62464
	ds_read_b128 v[202:205], v221 offset:63488
	ds_read_b128 v[206:209], v221 offset:64512
	ds_read_b128 v[210:213], v222 offset:4096
	ds_read_b128 v[214:217], v222 offset:5120
	ds_read_b128 v[228:231], v222 offset:6144
	ds_read_b128 v[238:241], v222 offset:7168
	ds_read_b128 v[242:245], v222 offset:8192
	ds_read_b128 v[246:249], v222 offset:9216
	global_load_lds_dwordx4 v220, s[74:75]
	s_add_u32 s74, s12, 0xac080
	s_addc_u32 s75, s13, 0
	s_mov_b32 m0, s41
	s_nop 0
	global_load_lds_dwordx4 v220, s[74:75]
	s_add_u32 s74, s12, 0x158080
	s_addc_u32 s75, s13, 0
	s_mov_b32 m0, s51
	s_add_u32 s12, s12, 0x204080
	global_load_lds_dwordx4 v220, s[74:75]
	s_addc_u32 s13, s13, 0
	s_mov_b32 m0, s56
	s_add_u32 s6, s6, 0xac080
	global_load_lds_dwordx4 v220, s[12:13]
	s_mov_b32 m0, s48
	s_addc_u32 s7, s7, 0
	global_load_lds_dwordx4 v0, s[10:11]
	s_mov_b32 m0, s50
	s_nop 0
	global_load_lds_dwordx4 v0, s[6:7]
	s_waitcnt vmcnt(8) lgkmcnt(0)
	s_barrier
	v_mfma_f32_16x16x32_bf16 v[78:81], v[162:165], v[194:197], v[78:81]
	v_mfma_f32_16x16x32_bf16 v[74:77], v[170:173], v[194:197], v[74:77]
	v_mfma_f32_16x16x32_bf16 v[62:65], v[162:165], v[202:205], v[62:65]
	v_mfma_f32_16x16x32_bf16 v[58:61], v[170:173], v[202:205], v[58:61]
	v_mfma_f32_16x16x32_bf16 v[46:49], v[162:165], v[210:213], v[46:49]
	v_mfma_f32_16x16x32_bf16 v[42:45], v[170:173], v[210:213], v[42:45]
	v_mfma_f32_16x16x32_bf16 v[30:33], v[162:165], v[228:231], v[30:33]
	v_mfma_f32_16x16x32_bf16 v[26:29], v[170:173], v[228:231], v[26:29]
	v_mfma_f32_16x16x32_bf16 v[14:17], v[162:165], v[242:245], v[14:17]
	v_mfma_f32_16x16x32_bf16 v[10:13], v[170:173], v[242:245], v[10:13]
	v_mfma_f32_16x16x32_bf16 v[78:81], v[166:169], v[198:201], v[78:81]
	v_mfma_f32_16x16x32_bf16 v[74:77], v[174:177], v[198:201], v[74:77]
	v_mfma_f32_16x16x32_bf16 v[62:65], v[166:169], v[206:209], v[62:65]
	v_mfma_f32_16x16x32_bf16 v[58:61], v[174:177], v[206:209], v[58:61]
	v_mfma_f32_16x16x32_bf16 v[46:49], v[166:169], v[214:217], v[46:49]
	v_mfma_f32_16x16x32_bf16 v[42:45], v[174:177], v[214:217], v[42:45]
	v_mfma_f32_16x16x32_bf16 v[30:33], v[166:169], v[238:241], v[30:33]
	v_mfma_f32_16x16x32_bf16 v[26:29], v[174:177], v[238:241], v[26:29]
	v_mfma_f32_16x16x32_bf16 v[14:17], v[166:169], v[246:249], v[14:17]
	v_mfma_f32_16x16x32_bf16 v[10:13], v[174:177], v[246:249], v[10:13]
	v_mfma_f32_16x16x32_bf16 v[70:73], v[178:181], v[194:197], v[70:73]
	v_mfma_f32_16x16x32_bf16 v[66:69], v[186:189], v[194:197], v[66:69]
	v_mfma_f32_16x16x32_bf16 v[54:57], v[178:181], v[202:205], v[54:57]
	v_mfma_f32_16x16x32_bf16 v[50:53], v[186:189], v[202:205], v[50:53]
	v_mfma_f32_16x16x32_bf16 v[38:41], v[178:181], v[210:213], v[38:41]
	v_mfma_f32_16x16x32_bf16 v[34:37], v[186:189], v[210:213], v[34:37]
	v_mfma_f32_16x16x32_bf16 v[22:25], v[178:181], v[228:231], v[22:25]
	v_mfma_f32_16x16x32_bf16 v[18:21], v[186:189], v[228:231], v[18:21]
	v_mfma_f32_16x16x32_bf16 v[6:9], v[178:181], v[242:245], v[6:9]
	v_mfma_f32_16x16x32_bf16 v[2:5], v[186:189], v[242:245], v[2:5]
	v_mfma_f32_16x16x32_bf16 v[70:73], v[182:185], v[198:201], v[70:73]
	v_mfma_f32_16x16x32_bf16 v[66:69], v[190:193], v[198:201], v[66:69]
	v_mfma_f32_16x16x32_bf16 v[54:57], v[182:185], v[206:209], v[54:57]
	v_mfma_f32_16x16x32_bf16 v[50:53], v[190:193], v[206:209], v[50:53]
	v_mfma_f32_16x16x32_bf16 v[38:41], v[182:185], v[214:217], v[38:41]
	v_mfma_f32_16x16x32_bf16 v[34:37], v[190:193], v[214:217], v[34:37]
	v_mfma_f32_16x16x32_bf16 v[22:25], v[182:185], v[238:241], v[22:25]
	v_mfma_f32_16x16x32_bf16 v[18:21], v[190:193], v[238:241], v[18:21]
	v_mfma_f32_16x16x32_bf16 v[6:9], v[182:185], v[246:249], v[6:9]
	v_mfma_f32_16x16x32_bf16 v[2:5], v[190:193], v[246:249], v[2:5]
	s_barrier
	s_add_i32 s84, s84, 2
	s_add_u32 s4, s4, 0x100
	s_addc_u32 s5, s5, 0
	s_add_u32 s70, s70, 0x100
	s_addc_u32 s72, s72, 0
	s_cmpk_gt_u32 s84, 0x53
	s_cbranch_scc0 .LBB0_650
	s_and_b64 vcc, exec, s[20:21]
	s_cbranch_vccz .LBB0_653
	s_barrier

.LBB0_716:
	v_add_u32_e32 v174, 0x14000, v223
	v_add_u32_e32 v190, 0x18000, v223
	ds_read_b128 v[162:165], v174
	ds_read_b128 v[166:169], v174 offset:1024
	ds_read_b128 v[170:173], v174 offset:2048
	ds_read_b128 v[174:177], v174 offset:3072
	ds_read_b128 v[178:181], v190
	ds_read_b128 v[182:185], v190 offset:1024
	ds_read_b128 v[186:189], v190 offset:2048
	ds_read_b128 v[190:193], v190 offset:3072
	s_add_u32 s6, s4, 0xffe52080
	s_addc_u32 s7, s5, -1
	s_cmpk_eq_i32 vcc_hi, 0x52
	s_cselect_b32 s6, s22, s6
	s_cselect_b32 s7, s23, s7
	s_cselect_b32 s12, s24, s97
	s_cselect_b32 s13, s25, vcc_lo
	s_add_u32 s10, s6, 0x80
	s_addc_u32 s11, s7, 0
	s_mov_b64 s[74:75], s[4:5]
	ds_read_b128 v[194:197], v221
	ds_read_b128 v[198:201], v221 offset:1024
	ds_read_b128 v[210:213], v221 offset:2048
	ds_read_b128 v[214:217], v221 offset:3072
	ds_read_b128 v[242:245], v221 offset:4096
	ds_read_b128 v[246:249], v221 offset:5120
	ds_read_b128 v[238:241], v221 offset:6144
	ds_read_b128 v[202:205], v221 offset:7168
	ds_read_b128 v[206:209], v221 offset:8192
	ds_read_b128 v[228:231], v221 offset:9216
	s_add_i32 m0, s28, 0xf000
	s_nop 0
	global_load_lds_dwordx4 v0, s[74:75]
	s_add_u32 s74, s4, 0xac000
	s_addc_u32 s75, s5, 0
	s_mov_b32 m0, s64
	s_nop 0
	global_load_lds_dwordx4 v0, s[74:75]
	s_add_u32 s74, s4, 0x158000
	s_addc_u32 s75, s5, 0
	s_mov_b32 m0, s66
	s_nop 0
	global_load_lds_dwordx4 v0, s[74:75]
	s_waitcnt vmcnt(10) lgkmcnt(0)
	s_barrier
	v_mfma_f32_16x16x32_bf16 v[158:161], v[162:165], v[194:197], v[158:161]
	v_mfma_f32_16x16x32_bf16 v[154:157], v[170:173], v[194:197], v[154:157]
	v_mfma_f32_16x16x32_bf16 v[142:145], v[162:165], v[210:213], v[142:145]
	v_mfma_f32_16x16x32_bf16 v[138:141], v[170:173], v[210:213], v[138:141]
	v_mfma_f32_16x16x32_bf16 v[126:129], v[162:165], v[242:245], v[126:129]
	v_mfma_f32_16x16x32_bf16 v[122:125], v[170:173], v[242:245], v[122:125]
	v_mfma_f32_16x16x32_bf16 v[110:113], v[162:165], v[238:241], v[110:113]
	v_mfma_f32_16x16x32_bf16 v[106:109], v[170:173], v[238:241], v[106:109]
	v_mfma_f32_16x16x32_bf16 v[94:97], v[162:165], v[206:209], v[94:97]
	v_mfma_f32_16x16x32_bf16 v[90:93], v[170:173], v[206:209], v[90:93]
	v_mfma_f32_16x16x32_bf16 v[158:161], v[166:169], v[198:201], v[158:161]
	v_mfma_f32_16x16x32_bf16 v[154:157], v[174:177], v[198:201], v[154:157]
	v_mfma_f32_16x16x32_bf16 v[142:145], v[166:169], v[214:217], v[142:145]
	v_mfma_f32_16x16x32_bf16 v[138:141], v[174:177], v[214:217], v[138:141]
	v_mfma_f32_16x16x32_bf16 v[126:129], v[166:169], v[246:249], v[126:129]
	v_mfma_f32_16x16x32_bf16 v[122:125], v[174:177], v[246:249], v[122:125]
	v_mfma_f32_16x16x32_bf16 v[110:113], v[166:169], v[202:205], v[110:113]
	v_mfma_f32_16x16x32_bf16 v[106:109], v[174:177], v[202:205], v[106:109]
	v_mfma_f32_16x16x32_bf16 v[94:97], v[166:169], v[228:231], v[94:97]
	v_mfma_f32_16x16x32_bf16 v[90:93], v[174:177], v[228:231], v[90:93]
	v_mfma_f32_16x16x32_bf16 v[150:153], v[178:181], v[194:197], v[150:153]
	v_mfma_f32_16x16x32_bf16 v[146:149], v[186:189], v[194:197], v[146:149]
	v_mfma_f32_16x16x32_bf16 v[134:137], v[178:181], v[210:213], v[134:137]
	v_mfma_f32_16x16x32_bf16 v[130:133], v[186:189], v[210:213], v[130:133]
	v_mfma_f32_16x16x32_bf16 v[118:121], v[178:181], v[242:245], v[118:121]
	v_mfma_f32_16x16x32_bf16 v[114:117], v[186:189], v[242:245], v[114:117]
	v_mfma_f32_16x16x32_bf16 v[102:105], v[178:181], v[238:241], v[102:105]
	v_mfma_f32_16x16x32_bf16 v[98:101], v[186:189], v[238:241], v[98:101]
	v_mfma_f32_16x16x32_bf16 v[86:89], v[178:181], v[206:209], v[86:89]
	v_mfma_f32_16x16x32_bf16 v[82:85], v[186:189], v[206:209], v[82:85]
	v_mfma_f32_16x16x32_bf16 v[150:153], v[182:185], v[198:201], v[150:153]
	v_mfma_f32_16x16x32_bf16 v[146:149], v[190:193], v[198:201], v[146:149]
	v_mfma_f32_16x16x32_bf16 v[134:137], v[182:185], v[214:217], v[134:137]
	v_mfma_f32_16x16x32_bf16 v[130:133], v[190:193], v[214:217], v[130:133]
	v_mfma_f32_16x16x32_bf16 v[118:121], v[182:185], v[246:249], v[118:121]
	v_mfma_f32_16x16x32_bf16 v[114:117], v[190:193], v[246:249], v[114:117]
	v_mfma_f32_16x16x32_bf16 v[102:105], v[182:185], v[202:205], v[102:105]
	v_mfma_f32_16x16x32_bf16 v[98:101], v[190:193], v[202:205], v[98:101]
	v_mfma_f32_16x16x32_bf16 v[86:89], v[182:185], v[228:231], v[86:89]
	v_mfma_f32_16x16x32_bf16 v[82:85], v[190:193], v[228:231], v[82:85]
	s_barrier
	s_mov_b64 s[74:75], s[12:13]
	s_mov_b32 m0, s29
	ds_read_b128 v[194:197], v221 offset:20480
	ds_read_b128 v[198:201], v221 offset:21504
	ds_read_b128 v[202:205], v221 offset:22528
	ds_read_b128 v[206:209], v221 offset:23552
	ds_read_b128 v[210:213], v221 offset:24576
	ds_read_b128 v[214:217], v221 offset:25600
	ds_read_b128 v[228:231], v221 offset:26624
	ds_read_b128 v[238:241], v221 offset:27648
	ds_read_b128 v[242:245], v221 offset:28672
	ds_read_b128 v[246:249], v221 offset:29696
	global_load_lds_dwordx4 v220, s[74:75]
	s_add_u32 s74, s12, 0xac000
	s_addc_u32 s75, s13, 0
	s_mov_b32 m0, s30
	s_nop 0
	global_load_lds_dwordx4 v220, s[74:75]
	s_add_u32 s74, s12, 0x158000
	s_addc_u32 s75, s13, 0
	s_mov_b32 m0, s31
	s_nop 0
	global_load_lds_dwordx4 v220, s[74:75]
	s_add_u32 s74, s12, 0x204000
	s_addc_u32 s75, s13, 0
	s_mov_b32 m0, s34
	s_nop 0
	global_load_lds_dwordx4 v220, s[74:75]
	s_mov_b64 s[74:75], s[6:7]
	s_mov_b32 m0, s28
	s_nop 0
	global_load_lds_dwordx4 v0, s[74:75]
	s_add_u32 s74, s6, 0xac000
	s_addc_u32 s75, s7, 0
	s_mov_b32 m0, s35
	s_nop 0
	global_load_lds_dwordx4 v0, s[74:75]
	s_add_u32 s74, s6, 0x158000
	s_addc_u32 s75, s7, 0
	s_mov_b32 m0, s36
	s_nop 0
	global_load_lds_dwordx4 v0, s[74:75]
	s_waitcnt vmcnt(10) lgkmcnt(0)
	s_barrier
	v_mfma_f32_16x16x32_bf16 v[78:81], v[162:165], v[194:197], v[78:81]
	v_mfma_f32_16x16x32_bf16 v[74:77], v[170:173], v[194:197], v[74:77]
	v_mfma_f32_16x16x32_bf16 v[62:65], v[162:165], v[202:205], v[62:65]
	v_mfma_f32_16x16x32_bf16 v[58:61], v[170:173], v[202:205], v[58:61]
	v_mfma_f32_16x16x32_bf16 v[46:49], v[162:165], v[210:213], v[46:49]
	v_mfma_f32_16x16x32_bf16 v[42:45], v[170:173], v[210:213], v[42:45]
	v_mfma_f32_16x16x32_bf16 v[30:33], v[162:165], v[228:231], v[30:33]
	v_mfma_f32_16x16x32_bf16 v[26:29], v[170:173], v[228:231], v[26:29]
	v_mfma_f32_16x16x32_bf16 v[14:17], v[162:165], v[242:245], v[14:17]
	v_mfma_f32_16x16x32_bf16 v[10:13], v[170:173], v[242:245], v[10:13]
	v_mfma_f32_16x16x32_bf16 v[78:81], v[166:169], v[198:201], v[78:81]
	v_mfma_f32_16x16x32_bf16 v[74:77], v[174:177], v[198:201], v[74:77]
	v_mfma_f32_16x16x32_bf16 v[62:65], v[166:169], v[206:209], v[62:65]
	v_mfma_f32_16x16x32_bf16 v[58:61], v[174:177], v[206:209], v[58:61]
	v_mfma_f32_16x16x32_bf16 v[46:49], v[166:169], v[214:217], v[46:49]
	v_mfma_f32_16x16x32_bf16 v[42:45], v[174:177], v[214:217], v[42:45]
	v_mfma_f32_16x16x32_bf16 v[30:33], v[166:169], v[238:241], v[30:33]
	v_mfma_f32_16x16x32_bf16 v[26:29], v[174:177], v[238:241], v[26:29]
	v_mfma_f32_16x16x32_bf16 v[14:17], v[166:169], v[246:249], v[14:17]
	v_mfma_f32_16x16x32_bf16 v[10:13], v[174:177], v[246:249], v[10:13]
	v_mfma_f32_16x16x32_bf16 v[70:73], v[178:181], v[194:197], v[70:73]
	v_mfma_f32_16x16x32_bf16 v[66:69], v[186:189], v[194:197], v[66:69]
	v_mfma_f32_16x16x32_bf16 v[54:57], v[178:181], v[202:205], v[54:57]
	v_mfma_f32_16x16x32_bf16 v[50:53], v[186:189], v[202:205], v[50:53]
	v_mfma_f32_16x16x32_bf16 v[38:41], v[178:181], v[210:213], v[38:41]
	v_mfma_f32_16x16x32_bf16 v[34:37], v[186:189], v[210:213], v[34:37]
	v_mfma_f32_16x16x32_bf16 v[22:25], v[178:181], v[228:231], v[22:25]
	v_mfma_f32_16x16x32_bf16 v[18:21], v[186:189], v[228:231], v[18:21]
	v_mfma_f32_16x16x32_bf16 v[6:9], v[178:181], v[242:245], v[6:9]
	v_mfma_f32_16x16x32_bf16 v[2:5], v[186:189], v[242:245], v[2:5]
	v_mfma_f32_16x16x32_bf16 v[70:73], v[182:185], v[198:201], v[70:73]
	v_mfma_f32_16x16x32_bf16 v[66:69], v[190:193], v[198:201], v[66:69]
	v_mfma_f32_16x16x32_bf16 v[54:57], v[182:185], v[206:209], v[54:57]
	v_mfma_f32_16x16x32_bf16 v[50:53], v[190:193], v[206:209], v[50:53]
	v_mfma_f32_16x16x32_bf16 v[38:41], v[182:185], v[214:217], v[38:41]
	v_mfma_f32_16x16x32_bf16 v[34:37], v[190:193], v[214:217], v[34:37]
	v_mfma_f32_16x16x32_bf16 v[22:25], v[182:185], v[238:241], v[22:25]
	v_mfma_f32_16x16x32_bf16 v[18:21], v[190:193], v[238:241], v[18:21]
	v_mfma_f32_16x16x32_bf16 v[6:9], v[182:185], v[246:249], v[6:9]
	v_mfma_f32_16x16x32_bf16 v[2:5], v[190:193], v[246:249], v[2:5]
	s_barrier
	v_add_u32_e32 v174, 0x1c000, v223
	v_add_u32_e32 v190, 0x20000, v223
	ds_read_b128 v[162:165], v174
	ds_read_b128 v[166:169], v174 offset:1024
	ds_read_b128 v[170:173], v174 offset:2048
	ds_read_b128 v[174:177], v174 offset:3072
	ds_read_b128 v[178:181], v190
	ds_read_b128 v[182:185], v190 offset:1024
	ds_read_b128 v[186:189], v190 offset:2048
	ds_read_b128 v[190:193], v190 offset:3072
	s_add_u32 s74, s6, 0x1ae000
	s_addc_u32 s75, s7, 0
	s_mov_b32 m0, s37
	ds_read_b128 v[194:197], v221 offset:40960
	ds_read_b128 v[198:201], v221 offset:41984
	ds_read_b128 v[202:205], v221 offset:43008
	ds_read_b128 v[206:209], v221 offset:44032
	ds_read_b128 v[210:213], v221 offset:45056
	ds_read_b128 v[214:217], v221 offset:46080
	ds_read_b128 v[228:231], v221 offset:47104
	ds_read_b128 v[238:241], v221 offset:48128
	ds_read_b128 v[242:245], v221 offset:49152
	ds_read_b128 v[246:249], v221 offset:50176
	global_load_lds_dwordx4 v0, s[74:75]
	s_add_u32 s74, s6, 0x25a000
	s_addc_u32 s75, s7, 0
	s_mov_b32 m0, s38
	s_nop 0
	global_load_lds_dwordx4 v0, s[74:75]
	s_add_u32 s74, s6, 0x306000
	s_addc_u32 s75, s7, 0
	s_mov_b32 m0, s39
	s_nop 0
	global_load_lds_dwordx4 v0, s[74:75]
	s_waitcnt vmcnt(10) lgkmcnt(0)
	s_barrier
	v_mfma_f32_16x16x32_bf16 v[158:161], v[162:165], v[194:197], v[158:161]
	v_mfma_f32_16x16x32_bf16 v[154:157], v[170:173], v[194:197], v[154:157]
	v_mfma_f32_16x16x32_bf16 v[142:145], v[162:165], v[202:205], v[142:145]
	v_mfma_f32_16x16x32_bf16 v[138:141], v[170:173], v[202:205], v[138:141]
	v_mfma_f32_16x16x32_bf16 v[126:129], v[162:165], v[210:213], v[126:129]
	v_mfma_f32_16x16x32_bf16 v[122:125], v[170:173], v[210:213], v[122:125]
	v_mfma_f32_16x16x32_bf16 v[110:113], v[162:165], v[228:231], v[110:113]
	v_mfma_f32_16x16x32_bf16 v[106:109], v[170:173], v[228:231], v[106:109]
	v_mfma_f32_16x16x32_bf16 v[94:97], v[162:165], v[242:245], v[94:97]
	v_mfma_f32_16x16x32_bf16 v[90:93], v[170:173], v[242:245], v[90:93]
	v_mfma_f32_16x16x32_bf16 v[158:161], v[166:169], v[198:201], v[158:161]
	v_mfma_f32_16x16x32_bf16 v[154:157], v[174:177], v[198:201], v[154:157]
	v_mfma_f32_16x16x32_bf16 v[142:145], v[166:169], v[206:209], v[142:145]
	v_mfma_f32_16x16x32_bf16 v[138:141], v[174:177], v[206:209], v[138:141]
	v_mfma_f32_16x16x32_bf16 v[126:129], v[166:169], v[214:217], v[126:129]
	v_mfma_f32_16x16x32_bf16 v[122:125], v[174:177], v[214:217], v[122:125]
	v_mfma_f32_16x16x32_bf16 v[110:113], v[166:169], v[238:241], v[110:113]
	v_mfma_f32_16x16x32_bf16 v[106:109], v[174:177], v[238:241], v[106:109]
	v_mfma_f32_16x16x32_bf16 v[94:97], v[166:169], v[246:249], v[94:97]
	v_mfma_f32_16x16x32_bf16 v[90:93], v[174:177], v[246:249], v[90:93]
	v_mfma_f32_16x16x32_bf16 v[150:153], v[178:181], v[194:197], v[150:153]
	v_mfma_f32_16x16x32_bf16 v[146:149], v[186:189], v[194:197], v[146:149]
	v_mfma_f32_16x16x32_bf16 v[134:137], v[178:181], v[202:205], v[134:137]
	v_mfma_f32_16x16x32_bf16 v[130:133], v[186:189], v[202:205], v[130:133]
	v_mfma_f32_16x16x32_bf16 v[118:121], v[178:181], v[210:213], v[118:121]
	v_mfma_f32_16x16x32_bf16 v[114:117], v[186:189], v[210:213], v[114:117]
	v_mfma_f32_16x16x32_bf16 v[102:105], v[178:181], v[228:231], v[102:105]
	v_mfma_f32_16x16x32_bf16 v[98:101], v[186:189], v[228:231], v[98:101]
	v_mfma_f32_16x16x32_bf16 v[86:89], v[178:181], v[242:245], v[86:89]
	v_mfma_f32_16x16x32_bf16 v[82:85], v[186:189], v[242:245], v[82:85]
	v_mfma_f32_16x16x32_bf16 v[150:153], v[182:185], v[198:201], v[150:153]
	v_mfma_f32_16x16x32_bf16 v[146:149], v[190:193], v[198:201], v[146:149]
	v_mfma_f32_16x16x32_bf16 v[134:137], v[182:185], v[206:209], v[134:137]
	v_mfma_f32_16x16x32_bf16 v[130:133], v[190:193], v[206:209], v[130:133]
	v_mfma_f32_16x16x32_bf16 v[118:121], v[182:185], v[214:217], v[118:121]
	v_mfma_f32_16x16x32_bf16 v[114:117], v[190:193], v[214:217], v[114:117]
	v_mfma_f32_16x16x32_bf16 v[102:105], v[182:185], v[238:241], v[102:105]
	v_mfma_f32_16x16x32_bf16 v[98:101], v[190:193], v[238:241], v[98:101]
	v_mfma_f32_16x16x32_bf16 v[86:89], v[182:185], v[246:249], v[86:89]
	v_mfma_f32_16x16x32_bf16 v[82:85], v[190:193], v[246:249], v[82:85]
	s_barrier
	s_add_u32 s74, s12, 0x80
	s_addc_u32 s75, s13, 0
	s_mov_b32 m0, s48
	ds_read_b128 v[194:197], v221 offset:61440
	ds_read_b128 v[198:201], v221 offset:62464
	ds_read_b128 v[202:205], v221 offset:63488
	ds_read_b128 v[206:209], v221 offset:64512
	ds_read_b128 v[210:213], v222 offset:4096
	ds_read_b128 v[214:217], v222 offset:5120
	ds_read_b128 v[228:231], v222 offset:6144
	ds_read_b128 v[238:241], v222 offset:7168
	ds_read_b128 v[242:245], v222 offset:8192
	ds_read_b128 v[246:249], v222 offset:9216
	global_load_lds_dwordx4 v220, s[74:75]
	s_add_u32 s74, s12, 0xac080
	s_addc_u32 s75, s13, 0
	s_mov_b32 m0, s50
	s_nop 0
	global_load_lds_dwordx4 v220, s[74:75]
	s_add_u32 s74, s12, 0x158080
	s_addc_u32 s75, s13, 0
	s_mov_b32 m0, s60
	s_add_u32 s12, s12, 0x204080
	global_load_lds_dwordx4 v220, s[74:75]
	s_addc_u32 s13, s13, 0
	s_mov_b32 m0, s62
	s_nop 0
	global_load_lds_dwordx4 v220, s[12:13]
	s_mov_b32 m0, s51
	s_nop 0
	global_load_lds_dwordx4 v0, s[10:11]
	s_add_u32 s10, s6, 0xac080
	s_addc_u32 s11, s7, 0
	s_mov_b32 m0, s56
	s_add_u32 s6, s6, 0x158080
	global_load_lds_dwordx4 v0, s[10:11]
	s_addc_u32 s7, s7, 0
	s_mov_b32 m0, s58
	s_nop 0
	global_load_lds_dwordx4 v0, s[6:7]
	s_waitcnt vmcnt(10) lgkmcnt(0)
	s_barrier
	v_mfma_f32_16x16x32_bf16 v[78:81], v[162:165], v[194:197], v[78:81]
	v_mfma_f32_16x16x32_bf16 v[74:77], v[170:173], v[194:197], v[74:77]
	v_mfma_f32_16x16x32_bf16 v[62:65], v[162:165], v[202:205], v[62:65]
	v_mfma_f32_16x16x32_bf16 v[58:61], v[170:173], v[202:205], v[58:61]
	v_mfma_f32_16x16x32_bf16 v[46:49], v[162:165], v[210:213], v[46:49]
	v_mfma_f32_16x16x32_bf16 v[42:45], v[170:173], v[210:213], v[42:45]
	v_mfma_f32_16x16x32_bf16 v[30:33], v[162:165], v[228:231], v[30:33]
	v_mfma_f32_16x16x32_bf16 v[26:29], v[170:173], v[228:231], v[26:29]
	v_mfma_f32_16x16x32_bf16 v[14:17], v[162:165], v[242:245], v[14:17]
	v_mfma_f32_16x16x32_bf16 v[10:13], v[170:173], v[242:245], v[10:13]
	v_mfma_f32_16x16x32_bf16 v[78:81], v[166:169], v[198:201], v[78:81]
	v_mfma_f32_16x16x32_bf16 v[74:77], v[174:177], v[198:201], v[74:77]
	v_mfma_f32_16x16x32_bf16 v[62:65], v[166:169], v[206:209], v[62:65]
	v_mfma_f32_16x16x32_bf16 v[58:61], v[174:177], v[206:209], v[58:61]
	v_mfma_f32_16x16x32_bf16 v[46:49], v[166:169], v[214:217], v[46:49]
	v_mfma_f32_16x16x32_bf16 v[42:45], v[174:177], v[214:217], v[42:45]
	v_mfma_f32_16x16x32_bf16 v[30:33], v[166:169], v[238:241], v[30:33]
	v_mfma_f32_16x16x32_bf16 v[26:29], v[174:177], v[238:241], v[26:29]
	v_mfma_f32_16x16x32_bf16 v[14:17], v[166:169], v[246:249], v[14:17]
	v_mfma_f32_16x16x32_bf16 v[10:13], v[174:177], v[246:249], v[10:13]
	v_mfma_f32_16x16x32_bf16 v[70:73], v[178:181], v[194:197], v[70:73]
	v_mfma_f32_16x16x32_bf16 v[66:69], v[186:189], v[194:197], v[66:69]
	v_mfma_f32_16x16x32_bf16 v[54:57], v[178:181], v[202:205], v[54:57]
	v_mfma_f32_16x16x32_bf16 v[50:53], v[186:189], v[202:205], v[50:53]
	v_mfma_f32_16x16x32_bf16 v[38:41], v[178:181], v[210:213], v[38:41]
	v_mfma_f32_16x16x32_bf16 v[34:37], v[186:189], v[210:213], v[34:37]
	v_mfma_f32_16x16x32_bf16 v[22:25], v[178:181], v[228:231], v[22:25]
	v_mfma_f32_16x16x32_bf16 v[18:21], v[186:189], v[228:231], v[18:21]
	v_mfma_f32_16x16x32_bf16 v[6:9], v[178:181], v[242:245], v[6:9]
	v_mfma_f32_16x16x32_bf16 v[2:5], v[186:189], v[242:245], v[2:5]
	v_mfma_f32_16x16x32_bf16 v[70:73], v[182:185], v[198:201], v[70:73]
	v_mfma_f32_16x16x32_bf16 v[66:69], v[190:193], v[198:201], v[66:69]
	v_mfma_f32_16x16x32_bf16 v[54:57], v[182:185], v[206:209], v[54:57]
	v_mfma_f32_16x16x32_bf16 v[50:53], v[190:193], v[206:209], v[50:53]
	v_mfma_f32_16x16x32_bf16 v[38:41], v[182:185], v[214:217], v[38:41]
	v_mfma_f32_16x16x32_bf16 v[34:37], v[190:193], v[214:217], v[34:37]
	v_mfma_f32_16x16x32_bf16 v[22:25], v[182:185], v[238:241], v[22:25]
	v_mfma_f32_16x16x32_bf16 v[18:21], v[190:193], v[238:241], v[18:21]
	v_mfma_f32_16x16x32_bf16 v[6:9], v[182:185], v[246:249], v[6:9]
	v_mfma_f32_16x16x32_bf16 v[2:5], v[190:193], v[246:249], v[2:5]
	s_barrier
	s_add_i32 vcc_hi, vcc_hi, 2
	s_add_u32 s4, s4, 0x100
	s_addc_u32 s5, s5, 0
	s_add_u32 s97, s97, 0x100
	s_addc_u32 vcc_lo, vcc_lo, 0
	s_cmpk_gt_u32 vcc_hi, 0x53
	s_cbranch_scc0 .LBB0_716
	s_and_b64 vcc, exec, s[20:21]
	s_cbranch_vccz .LBB0_719
	s_barrier

.LBB0_897:
	v_add_u32_e32 v174, 0x14000, v223
	v_add_u32_e32 v190, 0x18000, v223
	ds_read_b128 v[162:165], v174
	ds_read_b128 v[166:169], v174 offset:1024
	ds_read_b128 v[170:173], v174 offset:2048
	ds_read_b128 v[174:177], v174 offset:3072
	ds_read_b128 v[178:181], v190
	ds_read_b128 v[182:185], v190 offset:1024
	ds_read_b128 v[186:189], v190 offset:2048
	ds_read_b128 v[190:193], v190 offset:3072
	s_add_u32 s6, s4, 0xfff60080
	s_addc_u32 s7, s5, -1
	s_cmp_eq_u32 s92, 4
	s_cselect_b32 s6, s24, s6
	s_cselect_b32 s7, s25, s7
	s_cselect_b32 s16, s23, s72
	s_cselect_b32 s17, s21, s84
	s_add_u32 s10, s6, 0x80
	s_addc_u32 s11, s7, 0
	s_mov_b64 s[74:75], s[4:5]
	ds_read_b128 v[194:197], v221
	ds_read_b128 v[198:201], v221 offset:1024
	ds_read_b128 v[202:205], v221 offset:2048
	ds_read_b128 v[206:209], v221 offset:3072
	ds_read_b128 v[210:213], v221 offset:4096
	ds_read_b128 v[214:217], v221 offset:5120
	ds_read_b128 v[228:231], v221 offset:6144
	ds_read_b128 v[238:241], v221 offset:7168
	ds_read_b128 v[242:245], v221 offset:8192
	ds_read_b128 v[246:249], v221 offset:9216
	s_add_i32 m0, s34, 0xf000
	s_nop 0
	global_load_lds_dwordx4 v0, s[74:75]
	s_add_u32 s74, s4, 0x40000
	s_addc_u32 s75, s5, 0
	s_mov_b32 m0, s62
	s_nop 0
	global_load_lds_dwordx4 v0, s[74:75]
	s_waitcnt vmcnt(8) lgkmcnt(0)
	s_barrier
	v_mfma_f32_16x16x32_bf16 v[158:161], v[162:165], v[194:197], v[158:161]
	v_mfma_f32_16x16x32_bf16 v[154:157], v[170:173], v[194:197], v[154:157]
	v_mfma_f32_16x16x32_bf16 v[142:145], v[162:165], v[202:205], v[142:145]
	v_mfma_f32_16x16x32_bf16 v[138:141], v[170:173], v[202:205], v[138:141]
	v_mfma_f32_16x16x32_bf16 v[126:129], v[162:165], v[210:213], v[126:129]
	v_mfma_f32_16x16x32_bf16 v[122:125], v[170:173], v[210:213], v[122:125]
	v_mfma_f32_16x16x32_bf16 v[110:113], v[162:165], v[228:231], v[110:113]
	v_mfma_f32_16x16x32_bf16 v[106:109], v[170:173], v[228:231], v[106:109]
	v_mfma_f32_16x16x32_bf16 v[94:97], v[162:165], v[242:245], v[94:97]
	v_mfma_f32_16x16x32_bf16 v[90:93], v[170:173], v[242:245], v[90:93]
	v_mfma_f32_16x16x32_bf16 v[158:161], v[166:169], v[198:201], v[158:161]
	v_mfma_f32_16x16x32_bf16 v[154:157], v[174:177], v[198:201], v[154:157]
	v_mfma_f32_16x16x32_bf16 v[142:145], v[166:169], v[206:209], v[142:145]
	v_mfma_f32_16x16x32_bf16 v[138:141], v[174:177], v[206:209], v[138:141]
	v_mfma_f32_16x16x32_bf16 v[126:129], v[166:169], v[214:217], v[126:129]
	v_mfma_f32_16x16x32_bf16 v[122:125], v[174:177], v[214:217], v[122:125]
	v_mfma_f32_16x16x32_bf16 v[110:113], v[166:169], v[238:241], v[110:113]
	v_mfma_f32_16x16x32_bf16 v[106:109], v[174:177], v[238:241], v[106:109]
	v_mfma_f32_16x16x32_bf16 v[94:97], v[166:169], v[246:249], v[94:97]
	v_mfma_f32_16x16x32_bf16 v[90:93], v[174:177], v[246:249], v[90:93]
	v_mfma_f32_16x16x32_bf16 v[150:153], v[178:181], v[194:197], v[150:153]
	v_mfma_f32_16x16x32_bf16 v[146:149], v[186:189], v[194:197], v[146:149]
	v_mfma_f32_16x16x32_bf16 v[134:137], v[178:181], v[202:205], v[134:137]
	v_mfma_f32_16x16x32_bf16 v[130:133], v[186:189], v[202:205], v[130:133]
	v_mfma_f32_16x16x32_bf16 v[118:121], v[178:181], v[210:213], v[118:121]
	v_mfma_f32_16x16x32_bf16 v[114:117], v[186:189], v[210:213], v[114:117]
	v_mfma_f32_16x16x32_bf16 v[102:105], v[178:181], v[228:231], v[102:105]
	v_mfma_f32_16x16x32_bf16 v[98:101], v[186:189], v[228:231], v[98:101]
	v_mfma_f32_16x16x32_bf16 v[86:89], v[178:181], v[242:245], v[86:89]
	v_mfma_f32_16x16x32_bf16 v[82:85], v[186:189], v[242:245], v[82:85]
	v_mfma_f32_16x16x32_bf16 v[150:153], v[182:185], v[198:201], v[150:153]
	v_mfma_f32_16x16x32_bf16 v[146:149], v[190:193], v[198:201], v[146:149]
	v_mfma_f32_16x16x32_bf16 v[134:137], v[182:185], v[206:209], v[134:137]
	v_mfma_f32_16x16x32_bf16 v[130:133], v[190:193], v[206:209], v[130:133]
	v_mfma_f32_16x16x32_bf16 v[118:121], v[182:185], v[214:217], v[118:121]
	v_mfma_f32_16x16x32_bf16 v[114:117], v[190:193], v[214:217], v[114:117]
	v_mfma_f32_16x16x32_bf16 v[102:105], v[182:185], v[238:241], v[102:105]
	v_mfma_f32_16x16x32_bf16 v[98:101], v[190:193], v[238:241], v[98:101]
	v_mfma_f32_16x16x32_bf16 v[86:89], v[182:185], v[246:249], v[86:89]
	v_mfma_f32_16x16x32_bf16 v[82:85], v[190:193], v[246:249], v[82:85]
	s_barrier
	s_mov_b64 s[74:75], s[16:17]
	s_mov_b32 m0, s35
	ds_read_b128 v[194:197], v221 offset:20480
	ds_read_b128 v[198:201], v221 offset:21504
	ds_read_b128 v[202:205], v221 offset:22528
	ds_read_b128 v[206:209], v221 offset:23552
	ds_read_b128 v[210:213], v221 offset:24576
	ds_read_b128 v[214:217], v221 offset:25600
	ds_read_b128 v[228:231], v221 offset:26624
	ds_read_b128 v[238:241], v221 offset:27648
	ds_read_b128 v[242:245], v221 offset:28672
	ds_read_b128 v[246:249], v221 offset:29696
	global_load_lds_dwordx4 v220, s[74:75]
	s_add_u32 s74, s16, 0x10000
	s_addc_u32 s75, s17, 0
	s_mov_b32 m0, s36
	s_nop 0
	global_load_lds_dwordx4 v220, s[74:75]
	s_add_u32 s74, s16, 0x20000
	s_addc_u32 s75, s17, 0
	s_mov_b32 m0, s37
	s_nop 0
	global_load_lds_dwordx4 v220, s[74:75]
	s_add_u32 s74, s16, 0x30000
	s_addc_u32 s75, s17, 0
	s_mov_b32 m0, s38
	s_nop 0
	global_load_lds_dwordx4 v220, s[74:75]
	s_mov_b64 s[74:75], s[6:7]
	s_mov_b32 m0, s34
	s_nop 0
	global_load_lds_dwordx4 v0, s[74:75]
	s_add_u32 s74, s6, 0x40000
	s_addc_u32 s75, s7, 0
	s_mov_b32 m0, s39
	s_nop 0
	global_load_lds_dwordx4 v0, s[74:75]
	s_waitcnt vmcnt(8) lgkmcnt(0)
	s_barrier
	v_mfma_f32_16x16x32_bf16 v[78:81], v[162:165], v[194:197], v[78:81]
	v_mfma_f32_16x16x32_bf16 v[74:77], v[170:173], v[194:197], v[74:77]
	v_mfma_f32_16x16x32_bf16 v[62:65], v[162:165], v[202:205], v[62:65]
	v_mfma_f32_16x16x32_bf16 v[58:61], v[170:173], v[202:205], v[58:61]
	v_mfma_f32_16x16x32_bf16 v[46:49], v[162:165], v[210:213], v[46:49]
	v_mfma_f32_16x16x32_bf16 v[42:45], v[170:173], v[210:213], v[42:45]
	v_mfma_f32_16x16x32_bf16 v[30:33], v[162:165], v[228:231], v[30:33]
	v_mfma_f32_16x16x32_bf16 v[26:29], v[170:173], v[228:231], v[26:29]
	v_mfma_f32_16x16x32_bf16 v[14:17], v[162:165], v[242:245], v[14:17]
	v_mfma_f32_16x16x32_bf16 v[10:13], v[170:173], v[242:245], v[10:13]
	v_mfma_f32_16x16x32_bf16 v[78:81], v[166:169], v[198:201], v[78:81]
	v_mfma_f32_16x16x32_bf16 v[74:77], v[174:177], v[198:201], v[74:77]
	v_mfma_f32_16x16x32_bf16 v[62:65], v[166:169], v[206:209], v[62:65]
	v_mfma_f32_16x16x32_bf16 v[58:61], v[174:177], v[206:209], v[58:61]
	v_mfma_f32_16x16x32_bf16 v[46:49], v[166:169], v[214:217], v[46:49]
	v_mfma_f32_16x16x32_bf16 v[42:45], v[174:177], v[214:217], v[42:45]
	v_mfma_f32_16x16x32_bf16 v[30:33], v[166:169], v[238:241], v[30:33]
	v_mfma_f32_16x16x32_bf16 v[26:29], v[174:177], v[238:241], v[26:29]
	v_mfma_f32_16x16x32_bf16 v[14:17], v[166:169], v[246:249], v[14:17]
	v_mfma_f32_16x16x32_bf16 v[10:13], v[174:177], v[246:249], v[10:13]
	v_mfma_f32_16x16x32_bf16 v[70:73], v[178:181], v[194:197], v[70:73]
	v_mfma_f32_16x16x32_bf16 v[66:69], v[186:189], v[194:197], v[66:69]
	v_mfma_f32_16x16x32_bf16 v[54:57], v[178:181], v[202:205], v[54:57]
	v_mfma_f32_16x16x32_bf16 v[50:53], v[186:189], v[202:205], v[50:53]
	v_mfma_f32_16x16x32_bf16 v[38:41], v[178:181], v[210:213], v[38:41]
	v_mfma_f32_16x16x32_bf16 v[34:37], v[186:189], v[210:213], v[34:37]
	v_mfma_f32_16x16x32_bf16 v[22:25], v[178:181], v[228:231], v[22:25]
	v_mfma_f32_16x16x32_bf16 v[18:21], v[186:189], v[228:231], v[18:21]
	v_mfma_f32_16x16x32_bf16 v[6:9], v[178:181], v[242:245], v[6:9]
	v_mfma_f32_16x16x32_bf16 v[2:5], v[186:189], v[242:245], v[2:5]
	v_mfma_f32_16x16x32_bf16 v[70:73], v[182:185], v[198:201], v[70:73]
	v_mfma_f32_16x16x32_bf16 v[66:69], v[190:193], v[198:201], v[66:69]
	v_mfma_f32_16x16x32_bf16 v[54:57], v[182:185], v[206:209], v[54:57]
	v_mfma_f32_16x16x32_bf16 v[50:53], v[190:193], v[206:209], v[50:53]
	v_mfma_f32_16x16x32_bf16 v[38:41], v[182:185], v[214:217], v[38:41]
	v_mfma_f32_16x16x32_bf16 v[34:37], v[190:193], v[214:217], v[34:37]
	v_mfma_f32_16x16x32_bf16 v[22:25], v[182:185], v[238:241], v[22:25]
	v_mfma_f32_16x16x32_bf16 v[18:21], v[190:193], v[238:241], v[18:21]
	v_mfma_f32_16x16x32_bf16 v[6:9], v[182:185], v[246:249], v[6:9]
	v_mfma_f32_16x16x32_bf16 v[2:5], v[190:193], v[246:249], v[2:5]
	s_barrier
	v_add_u32_e32 v174, 0x1c000, v223
	v_add_u32_e32 v190, 0x20000, v223
	ds_read_b128 v[162:165], v174
	ds_read_b128 v[166:169], v174 offset:1024
	ds_read_b128 v[170:173], v174 offset:2048
	ds_read_b128 v[174:177], v174 offset:3072
	ds_read_b128 v[178:181], v190
	ds_read_b128 v[182:185], v190 offset:1024
	ds_read_b128 v[186:189], v190 offset:2048
	ds_read_b128 v[190:193], v190 offset:3072
	s_add_u32 s74, s6, 0xa0000
	s_addc_u32 s75, s7, 0
	s_mov_b32 m0, s40
	ds_read_b128 v[194:197], v221 offset:40960
	ds_read_b128 v[198:201], v221 offset:41984
	ds_read_b128 v[202:205], v221 offset:43008
	ds_read_b128 v[206:209], v221 offset:44032
	ds_read_b128 v[210:213], v221 offset:45056
	ds_read_b128 v[214:217], v221 offset:46080
	ds_read_b128 v[228:231], v221 offset:47104
	ds_read_b128 v[238:241], v221 offset:48128
	ds_read_b128 v[242:245], v221 offset:49152
	ds_read_b128 v[246:249], v221 offset:50176
	global_load_lds_dwordx4 v0, s[74:75]
	s_add_u32 s74, s6, 0xe0000
	s_addc_u32 s75, s7, 0
	s_mov_b32 m0, s41
	s_nop 0
	global_load_lds_dwordx4 v0, s[74:75]
	s_waitcnt vmcnt(8) lgkmcnt(0)
	s_barrier
	v_mfma_f32_16x16x32_bf16 v[158:161], v[162:165], v[194:197], v[158:161]
	v_mfma_f32_16x16x32_bf16 v[154:157], v[170:173], v[194:197], v[154:157]
	v_mfma_f32_16x16x32_bf16 v[142:145], v[162:165], v[202:205], v[142:145]
	v_mfma_f32_16x16x32_bf16 v[138:141], v[170:173], v[202:205], v[138:141]
	v_mfma_f32_16x16x32_bf16 v[126:129], v[162:165], v[210:213], v[126:129]
	v_mfma_f32_16x16x32_bf16 v[122:125], v[170:173], v[210:213], v[122:125]
	v_mfma_f32_16x16x32_bf16 v[110:113], v[162:165], v[228:231], v[110:113]
	v_mfma_f32_16x16x32_bf16 v[106:109], v[170:173], v[228:231], v[106:109]
	v_mfma_f32_16x16x32_bf16 v[94:97], v[162:165], v[242:245], v[94:97]
	v_mfma_f32_16x16x32_bf16 v[90:93], v[170:173], v[242:245], v[90:93]
	v_mfma_f32_16x16x32_bf16 v[158:161], v[166:169], v[198:201], v[158:161]
	v_mfma_f32_16x16x32_bf16 v[154:157], v[174:177], v[198:201], v[154:157]
	v_mfma_f32_16x16x32_bf16 v[142:145], v[166:169], v[206:209], v[142:145]
	v_mfma_f32_16x16x32_bf16 v[138:141], v[174:177], v[206:209], v[138:141]
	v_mfma_f32_16x16x32_bf16 v[126:129], v[166:169], v[214:217], v[126:129]
	v_mfma_f32_16x16x32_bf16 v[122:125], v[174:177], v[214:217], v[122:125]
	v_mfma_f32_16x16x32_bf16 v[110:113], v[166:169], v[238:241], v[110:113]
	v_mfma_f32_16x16x32_bf16 v[106:109], v[174:177], v[238:241], v[106:109]
	v_mfma_f32_16x16x32_bf16 v[94:97], v[166:169], v[246:249], v[94:97]
	v_mfma_f32_16x16x32_bf16 v[90:93], v[174:177], v[246:249], v[90:93]
	v_mfma_f32_16x16x32_bf16 v[150:153], v[178:181], v[194:197], v[150:153]
	v_mfma_f32_16x16x32_bf16 v[146:149], v[186:189], v[194:197], v[146:149]
	v_mfma_f32_16x16x32_bf16 v[134:137], v[178:181], v[202:205], v[134:137]
	v_mfma_f32_16x16x32_bf16 v[130:133], v[186:189], v[202:205], v[130:133]
	v_mfma_f32_16x16x32_bf16 v[118:121], v[178:181], v[210:213], v[118:121]
	v_mfma_f32_16x16x32_bf16 v[114:117], v[186:189], v[210:213], v[114:117]
	v_mfma_f32_16x16x32_bf16 v[102:105], v[178:181], v[228:231], v[102:105]
	v_mfma_f32_16x16x32_bf16 v[98:101], v[186:189], v[228:231], v[98:101]
	v_mfma_f32_16x16x32_bf16 v[86:89], v[178:181], v[242:245], v[86:89]
	v_mfma_f32_16x16x32_bf16 v[82:85], v[186:189], v[242:245], v[82:85]
	v_mfma_f32_16x16x32_bf16 v[150:153], v[182:185], v[198:201], v[150:153]
	v_mfma_f32_16x16x32_bf16 v[146:149], v[190:193], v[198:201], v[146:149]
	v_mfma_f32_16x16x32_bf16 v[134:137], v[182:185], v[206:209], v[134:137]
	v_mfma_f32_16x16x32_bf16 v[130:133], v[190:193], v[206:209], v[130:133]
	v_mfma_f32_16x16x32_bf16 v[118:121], v[182:185], v[214:217], v[118:121]
	v_mfma_f32_16x16x32_bf16 v[114:117], v[190:193], v[214:217], v[114:117]
	v_mfma_f32_16x16x32_bf16 v[102:105], v[182:185], v[238:241], v[102:105]
	v_mfma_f32_16x16x32_bf16 v[98:101], v[190:193], v[238:241], v[98:101]
	v_mfma_f32_16x16x32_bf16 v[86:89], v[182:185], v[246:249], v[86:89]
	v_mfma_f32_16x16x32_bf16 v[82:85], v[190:193], v[246:249], v[82:85]
	s_barrier
	s_add_u32 s74, s16, 0x80
	s_addc_u32 s75, s17, 0
	s_mov_b32 m0, s48
	ds_read_b128 v[194:197], v221 offset:61440
	ds_read_b128 v[198:201], v221 offset:62464
	ds_read_b128 v[202:205], v221 offset:63488
	ds_read_b128 v[206:209], v221 offset:64512
	ds_read_b128 v[210:213], v222 offset:4096
	ds_read_b128 v[214:217], v222 offset:5120
	ds_read_b128 v[228:231], v222 offset:6144
	ds_read_b128 v[238:241], v222 offset:7168
	ds_read_b128 v[242:245], v222 offset:8192
	ds_read_b128 v[246:249], v222 offset:9216
	global_load_lds_dwordx4 v220, s[74:75]
	s_add_u32 s74, s16, 0x10080
	s_addc_u32 s75, s17, 0
	s_mov_b32 m0, s50
	s_nop 0
	global_load_lds_dwordx4 v220, s[74:75]
	s_add_u32 s74, s16, 0x20080
	s_addc_u32 s75, s17, 0
	s_mov_b32 m0, s58
	s_add_u32 s16, s16, 0x30080
	global_load_lds_dwordx4 v220, s[74:75]
	s_addc_u32 s17, s17, 0
	s_mov_b32 m0, s60
	s_add_u32 s6, s6, 0x40080
	global_load_lds_dwordx4 v220, s[16:17]
	s_mov_b32 m0, s51
	s_addc_u32 s7, s7, 0
	global_load_lds_dwordx4 v0, s[10:11]
	s_mov_b32 m0, s56
	s_nop 0
	global_load_lds_dwordx4 v0, s[6:7]
	s_waitcnt vmcnt(8) lgkmcnt(0)
	s_barrier
	v_mfma_f32_16x16x32_bf16 v[78:81], v[162:165], v[194:197], v[78:81]
	v_mfma_f32_16x16x32_bf16 v[74:77], v[170:173], v[194:197], v[74:77]
	v_mfma_f32_16x16x32_bf16 v[62:65], v[162:165], v[202:205], v[62:65]
	v_mfma_f32_16x16x32_bf16 v[58:61], v[170:173], v[202:205], v[58:61]
	v_mfma_f32_16x16x32_bf16 v[46:49], v[162:165], v[210:213], v[46:49]
	v_mfma_f32_16x16x32_bf16 v[42:45], v[170:173], v[210:213], v[42:45]
	v_mfma_f32_16x16x32_bf16 v[30:33], v[162:165], v[228:231], v[30:33]
	v_mfma_f32_16x16x32_bf16 v[26:29], v[170:173], v[228:231], v[26:29]
	v_mfma_f32_16x16x32_bf16 v[14:17], v[162:165], v[242:245], v[14:17]
	v_mfma_f32_16x16x32_bf16 v[10:13], v[170:173], v[242:245], v[10:13]
	v_mfma_f32_16x16x32_bf16 v[78:81], v[166:169], v[198:201], v[78:81]
	v_mfma_f32_16x16x32_bf16 v[74:77], v[174:177], v[198:201], v[74:77]
	v_mfma_f32_16x16x32_bf16 v[62:65], v[166:169], v[206:209], v[62:65]
	v_mfma_f32_16x16x32_bf16 v[58:61], v[174:177], v[206:209], v[58:61]
	v_mfma_f32_16x16x32_bf16 v[46:49], v[166:169], v[214:217], v[46:49]
	v_mfma_f32_16x16x32_bf16 v[42:45], v[174:177], v[214:217], v[42:45]
	v_mfma_f32_16x16x32_bf16 v[30:33], v[166:169], v[238:241], v[30:33]
	v_mfma_f32_16x16x32_bf16 v[26:29], v[174:177], v[238:241], v[26:29]
	v_mfma_f32_16x16x32_bf16 v[14:17], v[166:169], v[246:249], v[14:17]
	v_mfma_f32_16x16x32_bf16 v[10:13], v[174:177], v[246:249], v[10:13]
	v_mfma_f32_16x16x32_bf16 v[70:73], v[178:181], v[194:197], v[70:73]
	v_mfma_f32_16x16x32_bf16 v[66:69], v[186:189], v[194:197], v[66:69]
	v_mfma_f32_16x16x32_bf16 v[54:57], v[178:181], v[202:205], v[54:57]
	v_mfma_f32_16x16x32_bf16 v[50:53], v[186:189], v[202:205], v[50:53]
	v_mfma_f32_16x16x32_bf16 v[38:41], v[178:181], v[210:213], v[38:41]
	v_mfma_f32_16x16x32_bf16 v[34:37], v[186:189], v[210:213], v[34:37]
	v_mfma_f32_16x16x32_bf16 v[22:25], v[178:181], v[228:231], v[22:25]
	v_mfma_f32_16x16x32_bf16 v[18:21], v[186:189], v[228:231], v[18:21]
	v_mfma_f32_16x16x32_bf16 v[6:9], v[178:181], v[242:245], v[6:9]
	v_mfma_f32_16x16x32_bf16 v[2:5], v[186:189], v[242:245], v[2:5]
	v_mfma_f32_16x16x32_bf16 v[70:73], v[182:185], v[198:201], v[70:73]
	v_mfma_f32_16x16x32_bf16 v[66:69], v[190:193], v[198:201], v[66:69]
	v_mfma_f32_16x16x32_bf16 v[54:57], v[182:185], v[206:209], v[54:57]
	v_mfma_f32_16x16x32_bf16 v[50:53], v[190:193], v[206:209], v[50:53]
	v_mfma_f32_16x16x32_bf16 v[38:41], v[182:185], v[214:217], v[38:41]
	v_mfma_f32_16x16x32_bf16 v[34:37], v[190:193], v[214:217], v[34:37]
	v_mfma_f32_16x16x32_bf16 v[22:25], v[182:185], v[238:241], v[22:25]
	v_mfma_f32_16x16x32_bf16 v[18:21], v[190:193], v[238:241], v[18:21]
	v_mfma_f32_16x16x32_bf16 v[6:9], v[182:185], v[246:249], v[6:9]
	v_mfma_f32_16x16x32_bf16 v[2:5], v[190:193], v[246:249], v[2:5]
	s_barrier
	s_add_i32 s92, s92, 2
	s_add_u32 s4, s4, 0x100
	s_addc_u32 s5, s5, 0
	s_add_u32 s72, s72, 0x100
	s_addc_u32 s84, s84, 0
	s_cmp_gt_u32 s92, 5
	s_cbranch_scc0 .LBB0_897
	s_and_b64 vcc, exec, s[18:19]
	s_cbranch_vccz .LBB0_900
	s_barrier

.LBB0_929:
	v_add_u32_e32 v174, 0x14000, v223
	v_add_u32_e32 v190, 0x18000, v223
	ds_read_b128 v[162:165], v174
	ds_read_b128 v[166:169], v174 offset:1024
	ds_read_b128 v[170:173], v174 offset:2048
	ds_read_b128 v[174:177], v174 offset:3072
	ds_read_b128 v[178:181], v190
	ds_read_b128 v[182:185], v190 offset:1024
	ds_read_b128 v[186:189], v190 offset:2048
	ds_read_b128 v[190:193], v190 offset:3072
	s_add_u32 s6, s4, 0xfff60080
	s_addc_u32 s7, s5, -1
	s_cmp_eq_u32 s14, 4
	s_cselect_b32 s6, s24, s6
	s_cselect_b32 s7, s25, s7
	s_cselect_b32 s16, s23, vcc_lo
	s_cselect_b32 s17, s21, vcc_hi
	s_add_u32 s10, s6, 0x80
	s_addc_u32 s11, s7, 0
	s_mov_b64 s[74:75], s[4:5]
	ds_read_b128 v[194:197], v221
	ds_read_b128 v[198:201], v221 offset:1024
	ds_read_b128 v[202:205], v221 offset:2048
	ds_read_b128 v[206:209], v221 offset:3072
	ds_read_b128 v[210:213], v221 offset:4096
	ds_read_b128 v[214:217], v221 offset:5120
	ds_read_b128 v[228:231], v221 offset:6144
	ds_read_b128 v[238:241], v221 offset:7168
	ds_read_b128 v[242:245], v221 offset:8192
	ds_read_b128 v[246:249], v221 offset:9216
	s_add_i32 m0, s34, 0xf000
	s_nop 0
	global_load_lds_dwordx4 v0, s[74:75]
	s_add_u32 s74, s4, 0x40000
	s_addc_u32 s75, s5, 0
	s_mov_b32 m0, s68
	s_nop 0
	global_load_lds_dwordx4 v0, s[74:75]
	s_add_u32 s74, s4, 0x80000
	s_addc_u32 s75, s5, 0
	s_mov_b32 m0, s70
	s_nop 0
	global_load_lds_dwordx4 v0, s[74:75]
	s_waitcnt vmcnt(10) lgkmcnt(0)
	s_barrier
	v_mfma_f32_16x16x32_bf16 v[158:161], v[162:165], v[194:197], v[158:161]
	v_mfma_f32_16x16x32_bf16 v[154:157], v[170:173], v[194:197], v[154:157]
	v_mfma_f32_16x16x32_bf16 v[142:145], v[162:165], v[202:205], v[142:145]
	v_mfma_f32_16x16x32_bf16 v[138:141], v[170:173], v[202:205], v[138:141]
	v_mfma_f32_16x16x32_bf16 v[126:129], v[162:165], v[210:213], v[126:129]
	v_mfma_f32_16x16x32_bf16 v[122:125], v[170:173], v[210:213], v[122:125]
	v_mfma_f32_16x16x32_bf16 v[110:113], v[162:165], v[228:231], v[110:113]
	v_mfma_f32_16x16x32_bf16 v[106:109], v[170:173], v[228:231], v[106:109]
	v_mfma_f32_16x16x32_bf16 v[94:97], v[162:165], v[242:245], v[94:97]
	v_mfma_f32_16x16x32_bf16 v[90:93], v[170:173], v[242:245], v[90:93]
	v_mfma_f32_16x16x32_bf16 v[158:161], v[166:169], v[198:201], v[158:161]
	v_mfma_f32_16x16x32_bf16 v[154:157], v[174:177], v[198:201], v[154:157]
	v_mfma_f32_16x16x32_bf16 v[142:145], v[166:169], v[206:209], v[142:145]
	v_mfma_f32_16x16x32_bf16 v[138:141], v[174:177], v[206:209], v[138:141]
	v_mfma_f32_16x16x32_bf16 v[126:129], v[166:169], v[214:217], v[126:129]
	v_mfma_f32_16x16x32_bf16 v[122:125], v[174:177], v[214:217], v[122:125]
	v_mfma_f32_16x16x32_bf16 v[110:113], v[166:169], v[238:241], v[110:113]
	v_mfma_f32_16x16x32_bf16 v[106:109], v[174:177], v[238:241], v[106:109]
	v_mfma_f32_16x16x32_bf16 v[94:97], v[166:169], v[246:249], v[94:97]
	v_mfma_f32_16x16x32_bf16 v[90:93], v[174:177], v[246:249], v[90:93]
	v_mfma_f32_16x16x32_bf16 v[150:153], v[178:181], v[194:197], v[150:153]
	v_mfma_f32_16x16x32_bf16 v[146:149], v[186:189], v[194:197], v[146:149]
	v_mfma_f32_16x16x32_bf16 v[134:137], v[178:181], v[202:205], v[134:137]
	v_mfma_f32_16x16x32_bf16 v[130:133], v[186:189], v[202:205], v[130:133]
	v_mfma_f32_16x16x32_bf16 v[118:121], v[178:181], v[210:213], v[118:121]
	v_mfma_f32_16x16x32_bf16 v[114:117], v[186:189], v[210:213], v[114:117]
	v_mfma_f32_16x16x32_bf16 v[102:105], v[178:181], v[228:231], v[102:105]
	v_mfma_f32_16x16x32_bf16 v[98:101], v[186:189], v[228:231], v[98:101]
	v_mfma_f32_16x16x32_bf16 v[86:89], v[178:181], v[242:245], v[86:89]
	v_mfma_f32_16x16x32_bf16 v[82:85], v[186:189], v[242:245], v[82:85]
	v_mfma_f32_16x16x32_bf16 v[150:153], v[182:185], v[198:201], v[150:153]
	v_mfma_f32_16x16x32_bf16 v[146:149], v[190:193], v[198:201], v[146:149]
	v_mfma_f32_16x16x32_bf16 v[134:137], v[182:185], v[206:209], v[134:137]
	v_mfma_f32_16x16x32_bf16 v[130:133], v[190:193], v[206:209], v[130:133]
	v_mfma_f32_16x16x32_bf16 v[118:121], v[182:185], v[214:217], v[118:121]
	v_mfma_f32_16x16x32_bf16 v[114:117], v[190:193], v[214:217], v[114:117]
	v_mfma_f32_16x16x32_bf16 v[102:105], v[182:185], v[238:241], v[102:105]
	v_mfma_f32_16x16x32_bf16 v[98:101], v[190:193], v[238:241], v[98:101]
	v_mfma_f32_16x16x32_bf16 v[86:89], v[182:185], v[246:249], v[86:89]
	v_mfma_f32_16x16x32_bf16 v[82:85], v[190:193], v[246:249], v[82:85]
	s_barrier
	s_mov_b64 s[74:75], s[16:17]
	s_mov_b32 m0, s35
	ds_read_b128 v[194:197], v221 offset:20480
	ds_read_b128 v[198:201], v221 offset:21504
	ds_read_b128 v[202:205], v221 offset:22528
	ds_read_b128 v[206:209], v221 offset:23552
	ds_read_b128 v[210:213], v221 offset:24576
	ds_read_b128 v[214:217], v221 offset:25600
	ds_read_b128 v[228:231], v221 offset:26624
	ds_read_b128 v[238:241], v221 offset:27648
	ds_read_b128 v[242:245], v221 offset:28672
	ds_read_b128 v[246:249], v221 offset:29696
	global_load_lds_dwordx4 v220, s[74:75]
	s_add_u32 s74, s16, 0x10000
	s_addc_u32 s75, s17, 0
	s_mov_b32 m0, s36
	s_nop 0
	global_load_lds_dwordx4 v220, s[74:75]
	s_add_u32 s74, s16, 0x20000
	s_addc_u32 s75, s17, 0
	s_mov_b32 m0, s37
	s_nop 0
	global_load_lds_dwordx4 v220, s[74:75]
	s_add_u32 s74, s16, 0x30000
	s_addc_u32 s75, s17, 0
	s_mov_b32 m0, s38
	s_nop 0
	global_load_lds_dwordx4 v220, s[74:75]
	s_mov_b64 s[74:75], s[6:7]
	s_mov_b32 m0, s34
	s_nop 0
	global_load_lds_dwordx4 v0, s[74:75]
	s_add_u32 s74, s6, 0x40000
	s_addc_u32 s75, s7, 0
	s_mov_b32 m0, s39
	s_nop 0
	global_load_lds_dwordx4 v0, s[74:75]
	s_add_u32 s74, s6, 0x80000
	s_addc_u32 s75, s7, 0
	s_mov_b32 m0, s40
	s_nop 0
	global_load_lds_dwordx4 v0, s[74:75]
	s_waitcnt vmcnt(10) lgkmcnt(0)
	s_barrier
	v_mfma_f32_16x16x32_bf16 v[78:81], v[162:165], v[194:197], v[78:81]
	v_mfma_f32_16x16x32_bf16 v[74:77], v[170:173], v[194:197], v[74:77]
	v_mfma_f32_16x16x32_bf16 v[62:65], v[162:165], v[202:205], v[62:65]
	v_mfma_f32_16x16x32_bf16 v[58:61], v[170:173], v[202:205], v[58:61]
	v_mfma_f32_16x16x32_bf16 v[46:49], v[162:165], v[210:213], v[46:49]
	v_mfma_f32_16x16x32_bf16 v[42:45], v[170:173], v[210:213], v[42:45]
	v_mfma_f32_16x16x32_bf16 v[30:33], v[162:165], v[228:231], v[30:33]
	v_mfma_f32_16x16x32_bf16 v[26:29], v[170:173], v[228:231], v[26:29]
	v_mfma_f32_16x16x32_bf16 v[14:17], v[162:165], v[242:245], v[14:17]
	v_mfma_f32_16x16x32_bf16 v[10:13], v[170:173], v[242:245], v[10:13]
	v_mfma_f32_16x16x32_bf16 v[78:81], v[166:169], v[198:201], v[78:81]
	v_mfma_f32_16x16x32_bf16 v[74:77], v[174:177], v[198:201], v[74:77]
	v_mfma_f32_16x16x32_bf16 v[62:65], v[166:169], v[206:209], v[62:65]
	v_mfma_f32_16x16x32_bf16 v[58:61], v[174:177], v[206:209], v[58:61]
	v_mfma_f32_16x16x32_bf16 v[46:49], v[166:169], v[214:217], v[46:49]
	v_mfma_f32_16x16x32_bf16 v[42:45], v[174:177], v[214:217], v[42:45]
	v_mfma_f32_16x16x32_bf16 v[30:33], v[166:169], v[238:241], v[30:33]
	v_mfma_f32_16x16x32_bf16 v[26:29], v[174:177], v[238:241], v[26:29]
	v_mfma_f32_16x16x32_bf16 v[14:17], v[166:169], v[246:249], v[14:17]
	v_mfma_f32_16x16x32_bf16 v[10:13], v[174:177], v[246:249], v[10:13]
	v_mfma_f32_16x16x32_bf16 v[70:73], v[178:181], v[194:197], v[70:73]
	v_mfma_f32_16x16x32_bf16 v[66:69], v[186:189], v[194:197], v[66:69]
	v_mfma_f32_16x16x32_bf16 v[54:57], v[178:181], v[202:205], v[54:57]
	v_mfma_f32_16x16x32_bf16 v[50:53], v[186:189], v[202:205], v[50:53]
	v_mfma_f32_16x16x32_bf16 v[38:41], v[178:181], v[210:213], v[38:41]
	v_mfma_f32_16x16x32_bf16 v[34:37], v[186:189], v[210:213], v[34:37]
	v_mfma_f32_16x16x32_bf16 v[22:25], v[178:181], v[228:231], v[22:25]
	v_mfma_f32_16x16x32_bf16 v[18:21], v[186:189], v[228:231], v[18:21]
	v_mfma_f32_16x16x32_bf16 v[6:9], v[178:181], v[242:245], v[6:9]
	v_mfma_f32_16x16x32_bf16 v[2:5], v[186:189], v[242:245], v[2:5]
	v_mfma_f32_16x16x32_bf16 v[70:73], v[182:185], v[198:201], v[70:73]
	v_mfma_f32_16x16x32_bf16 v[66:69], v[190:193], v[198:201], v[66:69]
	v_mfma_f32_16x16x32_bf16 v[54:57], v[182:185], v[206:209], v[54:57]
	v_mfma_f32_16x16x32_bf16 v[50:53], v[190:193], v[206:209], v[50:53]
	v_mfma_f32_16x16x32_bf16 v[38:41], v[182:185], v[214:217], v[38:41]
	v_mfma_f32_16x16x32_bf16 v[34:37], v[190:193], v[214:217], v[34:37]
	v_mfma_f32_16x16x32_bf16 v[22:25], v[182:185], v[238:241], v[22:25]
	v_mfma_f32_16x16x32_bf16 v[18:21], v[190:193], v[238:241], v[18:21]
	v_mfma_f32_16x16x32_bf16 v[6:9], v[182:185], v[246:249], v[6:9]
	v_mfma_f32_16x16x32_bf16 v[2:5], v[190:193], v[246:249], v[2:5]
	s_barrier
	v_add_u32_e32 v174, 0x1c000, v223
	v_add_u32_e32 v190, 0x20000, v223
	ds_read_b128 v[162:165], v174
	ds_read_b128 v[166:169], v174 offset:1024
	ds_read_b128 v[170:173], v174 offset:2048
	ds_read_b128 v[174:177], v174 offset:3072
	ds_read_b128 v[178:181], v190
	ds_read_b128 v[182:185], v190 offset:1024
	ds_read_b128 v[186:189], v190 offset:2048
	ds_read_b128 v[190:193], v190 offset:3072
	s_add_u32 s74, s6, 0xa0000
	s_addc_u32 s75, s7, 0
	s_mov_b32 m0, s41
	ds_read_b128 v[194:197], v221 offset:40960
	ds_read_b128 v[198:201], v221 offset:41984
	ds_read_b128 v[202:205], v221 offset:43008
	ds_read_b128 v[206:209], v221 offset:44032
	ds_read_b128 v[210:213], v221 offset:45056
	ds_read_b128 v[214:217], v221 offset:46080
	ds_read_b128 v[228:231], v221 offset:47104
	ds_read_b128 v[238:241], v221 offset:48128
	ds_read_b128 v[242:245], v221 offset:49152
	ds_read_b128 v[246:249], v221 offset:50176
	global_load_lds_dwordx4 v0, s[74:75]
	s_add_u32 s74, s6, 0xe0000
	s_addc_u32 s75, s7, 0
	s_mov_b32 m0, s42
	s_nop 0
	global_load_lds_dwordx4 v0, s[74:75]
	s_add_u32 s74, s6, 0x120000
	s_addc_u32 s75, s7, 0
	s_mov_b32 m0, s43
	s_nop 0
	global_load_lds_dwordx4 v0, s[74:75]
	s_waitcnt vmcnt(10) lgkmcnt(0)
	s_barrier
	v_mfma_f32_16x16x32_bf16 v[158:161], v[162:165], v[194:197], v[158:161]
	v_mfma_f32_16x16x32_bf16 v[154:157], v[170:173], v[194:197], v[154:157]
	v_mfma_f32_16x16x32_bf16 v[142:145], v[162:165], v[202:205], v[142:145]
	v_mfma_f32_16x16x32_bf16 v[138:141], v[170:173], v[202:205], v[138:141]
	v_mfma_f32_16x16x32_bf16 v[126:129], v[162:165], v[210:213], v[126:129]
	v_mfma_f32_16x16x32_bf16 v[122:125], v[170:173], v[210:213], v[122:125]
	v_mfma_f32_16x16x32_bf16 v[110:113], v[162:165], v[228:231], v[110:113]
	v_mfma_f32_16x16x32_bf16 v[106:109], v[170:173], v[228:231], v[106:109]
	v_mfma_f32_16x16x32_bf16 v[94:97], v[162:165], v[242:245], v[94:97]
	v_mfma_f32_16x16x32_bf16 v[90:93], v[170:173], v[242:245], v[90:93]
	v_mfma_f32_16x16x32_bf16 v[158:161], v[166:169], v[198:201], v[158:161]
	v_mfma_f32_16x16x32_bf16 v[154:157], v[174:177], v[198:201], v[154:157]
	v_mfma_f32_16x16x32_bf16 v[142:145], v[166:169], v[206:209], v[142:145]
	v_mfma_f32_16x16x32_bf16 v[138:141], v[174:177], v[206:209], v[138:141]
	v_mfma_f32_16x16x32_bf16 v[126:129], v[166:169], v[214:217], v[126:129]
	v_mfma_f32_16x16x32_bf16 v[122:125], v[174:177], v[214:217], v[122:125]
	v_mfma_f32_16x16x32_bf16 v[110:113], v[166:169], v[238:241], v[110:113]
	v_mfma_f32_16x16x32_bf16 v[106:109], v[174:177], v[238:241], v[106:109]
	v_mfma_f32_16x16x32_bf16 v[94:97], v[166:169], v[246:249], v[94:97]
	v_mfma_f32_16x16x32_bf16 v[90:93], v[174:177], v[246:249], v[90:93]
	v_mfma_f32_16x16x32_bf16 v[150:153], v[178:181], v[194:197], v[150:153]
	v_mfma_f32_16x16x32_bf16 v[146:149], v[186:189], v[194:197], v[146:149]
	v_mfma_f32_16x16x32_bf16 v[134:137], v[178:181], v[202:205], v[134:137]
	v_mfma_f32_16x16x32_bf16 v[130:133], v[186:189], v[202:205], v[130:133]
	v_mfma_f32_16x16x32_bf16 v[118:121], v[178:181], v[210:213], v[118:121]
	v_mfma_f32_16x16x32_bf16 v[114:117], v[186:189], v[210:213], v[114:117]
	v_mfma_f32_16x16x32_bf16 v[102:105], v[178:181], v[228:231], v[102:105]
	v_mfma_f32_16x16x32_bf16 v[98:101], v[186:189], v[228:231], v[98:101]
	v_mfma_f32_16x16x32_bf16 v[86:89], v[178:181], v[242:245], v[86:89]
	v_mfma_f32_16x16x32_bf16 v[82:85], v[186:189], v[242:245], v[82:85]
	v_mfma_f32_16x16x32_bf16 v[150:153], v[182:185], v[198:201], v[150:153]
	v_mfma_f32_16x16x32_bf16 v[146:149], v[190:193], v[198:201], v[146:149]
	v_mfma_f32_16x16x32_bf16 v[134:137], v[182:185], v[206:209], v[134:137]
	v_mfma_f32_16x16x32_bf16 v[130:133], v[190:193], v[206:209], v[130:133]
	v_mfma_f32_16x16x32_bf16 v[118:121], v[182:185], v[214:217], v[118:121]
	v_mfma_f32_16x16x32_bf16 v[114:117], v[190:193], v[214:217], v[114:117]
	v_mfma_f32_16x16x32_bf16 v[102:105], v[182:185], v[238:241], v[102:105]
	v_mfma_f32_16x16x32_bf16 v[98:101], v[190:193], v[238:241], v[98:101]
	v_mfma_f32_16x16x32_bf16 v[86:89], v[182:185], v[246:249], v[86:89]
	v_mfma_f32_16x16x32_bf16 v[82:85], v[190:193], v[246:249], v[82:85]
	s_barrier
	s_add_u32 s74, s16, 0x80
	s_addc_u32 s75, s17, 0
	s_mov_b32 m0, s51
	ds_read_b128 v[194:197], v221 offset:61440
	ds_read_b128 v[198:201], v221 offset:62464
	ds_read_b128 v[202:205], v221 offset:63488
	ds_read_b128 v[206:209], v221 offset:64512
	ds_read_b128 v[210:213], v222 offset:4096
	ds_read_b128 v[214:217], v222 offset:5120
	ds_read_b128 v[228:231], v222 offset:6144
	ds_read_b128 v[238:241], v222 offset:7168
	ds_read_b128 v[242:245], v222 offset:8192
	ds_read_b128 v[246:249], v222 offset:9216
	global_load_lds_dwordx4 v220, s[74:75]
	s_add_u32 s74, s16, 0x10080
	s_addc_u32 s75, s17, 0
	s_mov_b32 m0, s56
	s_nop 0
	global_load_lds_dwordx4 v220, s[74:75]
	s_add_u32 s74, s16, 0x20080
	s_addc_u32 s75, s17, 0
	s_mov_b32 m0, s64
	s_add_u32 s16, s16, 0x30080
	global_load_lds_dwordx4 v220, s[74:75]
	s_addc_u32 s17, s17, 0
	s_mov_b32 m0, s66
	s_nop 0
	global_load_lds_dwordx4 v220, s[16:17]
	s_mov_b32 m0, s58
	s_nop 0
	global_load_lds_dwordx4 v0, s[10:11]
	s_add_u32 s10, s6, 0x40080
	s_addc_u32 s11, s7, 0
	s_mov_b32 m0, s60
	s_add_u32 s6, s6, 0x80080
	global_load_lds_dwordx4 v0, s[10:11]
	s_addc_u32 s7, s7, 0
	s_mov_b32 m0, s62
	s_nop 0
	global_load_lds_dwordx4 v0, s[6:7]
	s_waitcnt vmcnt(10) lgkmcnt(0)
	s_barrier
	v_mfma_f32_16x16x32_bf16 v[78:81], v[162:165], v[194:197], v[78:81]
	v_mfma_f32_16x16x32_bf16 v[74:77], v[170:173], v[194:197], v[74:77]
	v_mfma_f32_16x16x32_bf16 v[62:65], v[162:165], v[202:205], v[62:65]
	v_mfma_f32_16x16x32_bf16 v[58:61], v[170:173], v[202:205], v[58:61]
	v_mfma_f32_16x16x32_bf16 v[46:49], v[162:165], v[210:213], v[46:49]
	v_mfma_f32_16x16x32_bf16 v[42:45], v[170:173], v[210:213], v[42:45]
	v_mfma_f32_16x16x32_bf16 v[30:33], v[162:165], v[228:231], v[30:33]
	v_mfma_f32_16x16x32_bf16 v[26:29], v[170:173], v[228:231], v[26:29]
	v_mfma_f32_16x16x32_bf16 v[14:17], v[162:165], v[242:245], v[14:17]
	v_mfma_f32_16x16x32_bf16 v[10:13], v[170:173], v[242:245], v[10:13]
	v_mfma_f32_16x16x32_bf16 v[78:81], v[166:169], v[198:201], v[78:81]
	v_mfma_f32_16x16x32_bf16 v[74:77], v[174:177], v[198:201], v[74:77]
	v_mfma_f32_16x16x32_bf16 v[62:65], v[166:169], v[206:209], v[62:65]
	v_mfma_f32_16x16x32_bf16 v[58:61], v[174:177], v[206:209], v[58:61]
	v_mfma_f32_16x16x32_bf16 v[46:49], v[166:169], v[214:217], v[46:49]
	v_mfma_f32_16x16x32_bf16 v[42:45], v[174:177], v[214:217], v[42:45]
	v_mfma_f32_16x16x32_bf16 v[30:33], v[166:169], v[238:241], v[30:33]
	v_mfma_f32_16x16x32_bf16 v[26:29], v[174:177], v[238:241], v[26:29]
	v_mfma_f32_16x16x32_bf16 v[14:17], v[166:169], v[246:249], v[14:17]
	v_mfma_f32_16x16x32_bf16 v[10:13], v[174:177], v[246:249], v[10:13]
	v_mfma_f32_16x16x32_bf16 v[70:73], v[178:181], v[194:197], v[70:73]
	v_mfma_f32_16x16x32_bf16 v[66:69], v[186:189], v[194:197], v[66:69]
	v_mfma_f32_16x16x32_bf16 v[54:57], v[178:181], v[202:205], v[54:57]
	v_mfma_f32_16x16x32_bf16 v[50:53], v[186:189], v[202:205], v[50:53]
	v_mfma_f32_16x16x32_bf16 v[38:41], v[178:181], v[210:213], v[38:41]
	v_mfma_f32_16x16x32_bf16 v[34:37], v[186:189], v[210:213], v[34:37]
	v_mfma_f32_16x16x32_bf16 v[22:25], v[178:181], v[228:231], v[22:25]
	v_mfma_f32_16x16x32_bf16 v[18:21], v[186:189], v[228:231], v[18:21]
	v_mfma_f32_16x16x32_bf16 v[6:9], v[178:181], v[242:245], v[6:9]
	v_mfma_f32_16x16x32_bf16 v[2:5], v[186:189], v[242:245], v[2:5]
	v_mfma_f32_16x16x32_bf16 v[70:73], v[182:185], v[198:201], v[70:73]
	v_mfma_f32_16x16x32_bf16 v[66:69], v[190:193], v[198:201], v[66:69]
	v_mfma_f32_16x16x32_bf16 v[54:57], v[182:185], v[206:209], v[54:57]
	v_mfma_f32_16x16x32_bf16 v[50:53], v[190:193], v[206:209], v[50:53]
	v_mfma_f32_16x16x32_bf16 v[38:41], v[182:185], v[214:217], v[38:41]
	v_mfma_f32_16x16x32_bf16 v[34:37], v[190:193], v[214:217], v[34:37]
	v_mfma_f32_16x16x32_bf16 v[22:25], v[182:185], v[238:241], v[22:25]
	v_mfma_f32_16x16x32_bf16 v[18:21], v[190:193], v[238:241], v[18:21]
	v_mfma_f32_16x16x32_bf16 v[6:9], v[182:185], v[246:249], v[6:9]
	v_mfma_f32_16x16x32_bf16 v[2:5], v[190:193], v[246:249], v[2:5]
	s_barrier
	s_add_i32 s14, s14, 2
	s_add_u32 s4, s4, 0x100
	s_addc_u32 s5, s5, 0
	s_add_u32 vcc_lo, vcc_lo, 0x100
	s_addc_u32 vcc_hi, vcc_hi, 0
	s_cmp_gt_u32 s14, 5
	s_cbranch_scc0 .LBB0_929
	s_and_b64 vcc, exec, s[18:19]
	s_cbranch_vccz .LBB0_932
	s_barrier

.LBB0_1046:
	v_add_u32_e32 v0, 0x10000, v134
	ds_read_b128 v[136:139], v0
	ds_read_b128 v[140:143], v0 offset:1024
	ds_read_b128 v[144:147], v0 offset:2048
	ds_read_b128 v[148:151], v0 offset:3072
	v_add_u32_e32 v0, 0x14000, v134
	ds_read_b128 v[152:155], v0
	ds_read_b128 v[156:159], v0 offset:1024
	ds_read_b128 v[160:163], v0 offset:2048
	ds_read_b128 v[164:167], v0 offset:3072
	s_cmp_eq_u32 s72, 28
	s_cselect_b32 s4, s60, s64
	s_cselect_b32 s5, s21, s66
	s_cselect_b32 s16, s62, s68
	s_cselect_b32 s17, s19, s70
	s_add_u32 s6, s4, 0x80
	s_addc_u32 s7, s5, 0
	s_add_u32 s74, s64, 0x7ff80
	s_addc_u32 s75, s66, 0
	ds_read_b128 v[168:171], v135
	ds_read_b128 v[172:175], v135 offset:1024
	ds_read_b128 v[176:179], v135 offset:2048
	ds_read_b128 v[180:183], v135 offset:3072
	ds_read_b128 v[184:187], v135 offset:4096
	ds_read_b128 v[188:191], v135 offset:5120
	ds_read_b128 v[192:195], v135 offset:6144
	ds_read_b128 v[196:199], v135 offset:7168
	s_add_i32 m0, s28, 0xc000
	s_nop 0
	global_load_lds_dwordx4 v132, s[74:75]
	s_add_u32 s74, s64, 0xbff80
	s_addc_u32 s75, s66, 0
	s_add_i32 m0, s28, 0xe000
	s_nop 0
	global_load_lds_dwordx4 v132, s[74:75]
	s_waitcnt vmcnt(8) lgkmcnt(0)
	s_barrier
	v_mfma_f32_16x16x32_bf16 v[126:129], v[136:139], v[168:171], v[126:129]
	v_mfma_f32_16x16x32_bf16 v[122:125], v[144:147], v[168:171], v[122:125]
	v_mfma_f32_16x16x32_bf16 v[118:121], v[136:139], v[176:179], v[118:121]
	v_mfma_f32_16x16x32_bf16 v[114:117], v[144:147], v[176:179], v[114:117]
	v_mfma_f32_16x16x32_bf16 v[102:105], v[136:139], v[184:187], v[102:105]
	v_mfma_f32_16x16x32_bf16 v[98:101], v[144:147], v[184:187], v[98:101]
	v_mfma_f32_16x16x32_bf16 v[86:89], v[136:139], v[192:195], v[86:89]
	v_mfma_f32_16x16x32_bf16 v[82:85], v[144:147], v[192:195], v[82:85]
	v_mfma_f32_16x16x32_bf16 v[126:129], v[140:143], v[172:175], v[126:129]
	v_mfma_f32_16x16x32_bf16 v[122:125], v[148:151], v[172:175], v[122:125]
	v_mfma_f32_16x16x32_bf16 v[118:121], v[140:143], v[180:183], v[118:121]
	v_mfma_f32_16x16x32_bf16 v[114:117], v[148:151], v[180:183], v[114:117]
	v_mfma_f32_16x16x32_bf16 v[102:105], v[140:143], v[188:191], v[102:105]
	v_mfma_f32_16x16x32_bf16 v[98:101], v[148:151], v[188:191], v[98:101]
	v_mfma_f32_16x16x32_bf16 v[86:89], v[140:143], v[196:199], v[86:89]
	v_mfma_f32_16x16x32_bf16 v[82:85], v[148:151], v[196:199], v[82:85]
	v_mfma_f32_16x16x32_bf16 v[110:113], v[152:155], v[168:171], v[110:113]
	v_mfma_f32_16x16x32_bf16 v[106:109], v[160:163], v[168:171], v[106:109]
	v_mfma_f32_16x16x32_bf16 v[94:97], v[152:155], v[176:179], v[94:97]
	v_mfma_f32_16x16x32_bf16 v[90:93], v[160:163], v[176:179], v[90:93]
	v_mfma_f32_16x16x32_bf16 v[78:81], v[152:155], v[184:187], v[78:81]
	v_mfma_f32_16x16x32_bf16 v[74:77], v[160:163], v[184:187], v[74:77]
	v_mfma_f32_16x16x32_bf16 v[70:73], v[152:155], v[192:195], v[70:73]
	v_mfma_f32_16x16x32_bf16 v[66:69], v[160:163], v[192:195], v[66:69]
	v_mfma_f32_16x16x32_bf16 v[110:113], v[156:159], v[172:175], v[110:113]
	v_mfma_f32_16x16x32_bf16 v[106:109], v[164:167], v[172:175], v[106:109]
	v_mfma_f32_16x16x32_bf16 v[94:97], v[156:159], v[180:183], v[94:97]
	v_mfma_f32_16x16x32_bf16 v[90:93], v[164:167], v[180:183], v[90:93]
	v_mfma_f32_16x16x32_bf16 v[78:81], v[156:159], v[188:191], v[78:81]
	v_mfma_f32_16x16x32_bf16 v[74:77], v[164:167], v[188:191], v[74:77]
	v_mfma_f32_16x16x32_bf16 v[70:73], v[156:159], v[196:199], v[70:73]
	v_mfma_f32_16x16x32_bf16 v[66:69], v[164:167], v[196:199], v[66:69]
	s_barrier
	s_mov_b64 s[74:75], s[16:17]
	s_mov_b32 m0, s29
	ds_read_b128 v[168:171], v135 offset:16384
	ds_read_b128 v[172:175], v135 offset:17408
	ds_read_b128 v[176:179], v135 offset:18432
	ds_read_b128 v[180:183], v135 offset:19456
	ds_read_b128 v[184:187], v135 offset:20480
	ds_read_b128 v[188:191], v135 offset:21504
	ds_read_b128 v[192:195], v135 offset:22528
	ds_read_b128 v[196:199], v135 offset:23552
	global_load_lds_dwordx4 v133, s[74:75]
	s_add_u32 s74, s16, 0x40000
	s_addc_u32 s75, s17, 0
	s_mov_b32 m0, s30
	s_nop 0
	global_load_lds_dwordx4 v133, s[74:75]
	s_add_u32 s74, s16, 0x80000
	s_addc_u32 s75, s17, 0
	s_mov_b32 m0, s31
	s_nop 0
	global_load_lds_dwordx4 v133, s[74:75]
	s_add_u32 s74, s16, 0xc0000
	s_addc_u32 s75, s17, 0
	s_mov_b32 m0, s34
	s_nop 0
	global_load_lds_dwordx4 v133, s[74:75]
	s_mov_b64 s[74:75], s[4:5]
	s_mov_b32 m0, s28
	s_nop 0
	global_load_lds_dwordx4 v132, s[74:75]
	s_add_u32 s74, s4, 0x40000
	s_addc_u32 s75, s5, 0
	s_mov_b32 m0, s35
	s_nop 0
	global_load_lds_dwordx4 v132, s[74:75]
	s_waitcnt vmcnt(8) lgkmcnt(0)
	s_barrier
	v_mfma_f32_16x16x32_bf16 v[62:65], v[136:139], v[168:171], v[62:65]
	v_mfma_f32_16x16x32_bf16 v[58:61], v[144:147], v[168:171], v[58:61]
	v_mfma_f32_16x16x32_bf16 v[54:57], v[136:139], v[176:179], v[54:57]
	v_mfma_f32_16x16x32_bf16 v[50:53], v[144:147], v[176:179], v[50:53]
	v_mfma_f32_16x16x32_bf16 v[38:41], v[136:139], v[184:187], v[38:41]
	v_mfma_f32_16x16x32_bf16 v[34:37], v[144:147], v[184:187], v[34:37]
	v_mfma_f32_16x16x32_bf16 v[22:25], v[136:139], v[192:195], v[22:25]
	v_mfma_f32_16x16x32_bf16 v[18:21], v[144:147], v[192:195], v[18:21]
	v_mfma_f32_16x16x32_bf16 v[62:65], v[140:143], v[172:175], v[62:65]
	v_mfma_f32_16x16x32_bf16 v[58:61], v[148:151], v[172:175], v[58:61]
	v_mfma_f32_16x16x32_bf16 v[54:57], v[140:143], v[180:183], v[54:57]
	v_mfma_f32_16x16x32_bf16 v[50:53], v[148:151], v[180:183], v[50:53]
	v_mfma_f32_16x16x32_bf16 v[38:41], v[140:143], v[188:191], v[38:41]
	v_mfma_f32_16x16x32_bf16 v[34:37], v[148:151], v[188:191], v[34:37]
	v_mfma_f32_16x16x32_bf16 v[22:25], v[140:143], v[196:199], v[22:25]
	v_mfma_f32_16x16x32_bf16 v[18:21], v[148:151], v[196:199], v[18:21]
	v_mfma_f32_16x16x32_bf16 v[46:49], v[152:155], v[168:171], v[46:49]
	v_mfma_f32_16x16x32_bf16 v[42:45], v[160:163], v[168:171], v[42:45]
	v_mfma_f32_16x16x32_bf16 v[30:33], v[152:155], v[176:179], v[30:33]
	v_mfma_f32_16x16x32_bf16 v[26:29], v[160:163], v[176:179], v[26:29]
	v_mfma_f32_16x16x32_bf16 v[14:17], v[152:155], v[184:187], v[14:17]
	v_mfma_f32_16x16x32_bf16 v[10:13], v[160:163], v[184:187], v[10:13]
	v_mfma_f32_16x16x32_bf16 v[6:9], v[152:155], v[192:195], v[6:9]
	v_mfma_f32_16x16x32_bf16 v[2:5], v[160:163], v[192:195], v[2:5]
	v_mfma_f32_16x16x32_bf16 v[46:49], v[156:159], v[172:175], v[46:49]
	v_mfma_f32_16x16x32_bf16 v[42:45], v[164:167], v[172:175], v[42:45]
	v_mfma_f32_16x16x32_bf16 v[30:33], v[156:159], v[180:183], v[30:33]
	v_mfma_f32_16x16x32_bf16 v[26:29], v[164:167], v[180:183], v[26:29]
	v_mfma_f32_16x16x32_bf16 v[14:17], v[156:159], v[188:191], v[14:17]
	v_mfma_f32_16x16x32_bf16 v[10:13], v[164:167], v[188:191], v[10:13]
	v_mfma_f32_16x16x32_bf16 v[6:9], v[156:159], v[196:199], v[6:9]
	v_mfma_f32_16x16x32_bf16 v[2:5], v[164:167], v[196:199], v[2:5]
	s_barrier
	v_add_u32_e32 v0, 0x18000, v134
	ds_read_b128 v[136:139], v0
	ds_read_b128 v[140:143], v0 offset:1024
	ds_read_b128 v[144:147], v0 offset:2048
	ds_read_b128 v[148:151], v0 offset:3072
	v_add_u32_e32 v0, 0x1c000, v134
	ds_read_b128 v[152:155], v0
	ds_read_b128 v[156:159], v0 offset:1024
	ds_read_b128 v[160:163], v0 offset:2048
	ds_read_b128 v[164:167], v0 offset:3072
	s_add_u32 s74, s4, 0x80000
	s_addc_u32 s75, s5, 0
	s_mov_b32 m0, s36
	ds_read_b128 v[168:171], v135 offset:32768
	ds_read_b128 v[172:175], v135 offset:33792
	ds_read_b128 v[176:179], v135 offset:34816
	ds_read_b128 v[180:183], v135 offset:35840
	ds_read_b128 v[184:187], v135 offset:36864
	ds_read_b128 v[188:191], v135 offset:37888
	ds_read_b128 v[192:195], v135 offset:38912
	ds_read_b128 v[196:199], v135 offset:39936
	global_load_lds_dwordx4 v132, s[74:75]
	s_add_u32 s74, s4, 0xc0000
	s_addc_u32 s75, s5, 0
	s_mov_b32 m0, s37
	s_nop 0
	global_load_lds_dwordx4 v132, s[74:75]
	s_waitcnt vmcnt(8) lgkmcnt(0)
	s_barrier
	v_mfma_f32_16x16x32_bf16 v[126:129], v[136:139], v[168:171], v[126:129]
	v_mfma_f32_16x16x32_bf16 v[122:125], v[144:147], v[168:171], v[122:125]
	v_mfma_f32_16x16x32_bf16 v[118:121], v[136:139], v[176:179], v[118:121]
	v_mfma_f32_16x16x32_bf16 v[114:117], v[144:147], v[176:179], v[114:117]
	v_mfma_f32_16x16x32_bf16 v[102:105], v[136:139], v[184:187], v[102:105]
	v_mfma_f32_16x16x32_bf16 v[98:101], v[144:147], v[184:187], v[98:101]
	v_mfma_f32_16x16x32_bf16 v[86:89], v[136:139], v[192:195], v[86:89]
	v_mfma_f32_16x16x32_bf16 v[82:85], v[144:147], v[192:195], v[82:85]
	v_mfma_f32_16x16x32_bf16 v[126:129], v[140:143], v[172:175], v[126:129]
	v_mfma_f32_16x16x32_bf16 v[122:125], v[148:151], v[172:175], v[122:125]
	v_mfma_f32_16x16x32_bf16 v[118:121], v[140:143], v[180:183], v[118:121]
	v_mfma_f32_16x16x32_bf16 v[114:117], v[148:151], v[180:183], v[114:117]
	v_mfma_f32_16x16x32_bf16 v[102:105], v[140:143], v[188:191], v[102:105]
	v_mfma_f32_16x16x32_bf16 v[98:101], v[148:151], v[188:191], v[98:101]
	v_mfma_f32_16x16x32_bf16 v[86:89], v[140:143], v[196:199], v[86:89]
	v_mfma_f32_16x16x32_bf16 v[82:85], v[148:151], v[196:199], v[82:85]
	v_mfma_f32_16x16x32_bf16 v[110:113], v[152:155], v[168:171], v[110:113]
	v_mfma_f32_16x16x32_bf16 v[106:109], v[160:163], v[168:171], v[106:109]
	v_mfma_f32_16x16x32_bf16 v[94:97], v[152:155], v[176:179], v[94:97]
	v_mfma_f32_16x16x32_bf16 v[90:93], v[160:163], v[176:179], v[90:93]
	v_mfma_f32_16x16x32_bf16 v[78:81], v[152:155], v[184:187], v[78:81]
	v_mfma_f32_16x16x32_bf16 v[74:77], v[160:163], v[184:187], v[74:77]
	v_mfma_f32_16x16x32_bf16 v[70:73], v[152:155], v[192:195], v[70:73]
	v_mfma_f32_16x16x32_bf16 v[66:69], v[160:163], v[192:195], v[66:69]
	v_mfma_f32_16x16x32_bf16 v[110:113], v[156:159], v[172:175], v[110:113]
	v_mfma_f32_16x16x32_bf16 v[106:109], v[164:167], v[172:175], v[106:109]
	v_mfma_f32_16x16x32_bf16 v[94:97], v[156:159], v[180:183], v[94:97]
	v_mfma_f32_16x16x32_bf16 v[90:93], v[164:167], v[180:183], v[90:93]
	v_mfma_f32_16x16x32_bf16 v[78:81], v[156:159], v[188:191], v[78:81]
	v_mfma_f32_16x16x32_bf16 v[74:77], v[164:167], v[188:191], v[74:77]
	v_mfma_f32_16x16x32_bf16 v[70:73], v[156:159], v[196:199], v[70:73]
	v_mfma_f32_16x16x32_bf16 v[66:69], v[164:167], v[196:199], v[66:69]
	s_barrier
	s_add_u32 s74, s16, 0x80
	s_addc_u32 s75, s17, 0
	s_mov_b32 m0, s40
	ds_read_b128 v[168:171], v135 offset:49152
	ds_read_b128 v[172:175], v135 offset:50176
	ds_read_b128 v[176:179], v135 offset:51200
	ds_read_b128 v[180:183], v135 offset:52224
	ds_read_b128 v[184:187], v135 offset:53248
	ds_read_b128 v[188:191], v135 offset:54272
	ds_read_b128 v[192:195], v135 offset:55296
	ds_read_b128 v[196:199], v135 offset:56320
	global_load_lds_dwordx4 v133, s[74:75]
	s_add_u32 s74, s16, 0x40080
	s_addc_u32 s75, s17, 0
	s_mov_b32 m0, s41
	s_nop 0
	global_load_lds_dwordx4 v133, s[74:75]
	s_add_u32 s74, s16, 0x80080
	s_addc_u32 s75, s17, 0
	s_mov_b32 m0, s48
	s_add_u32 s16, s16, 0xc0080
	global_load_lds_dwordx4 v133, s[74:75]
	s_addc_u32 s17, s17, 0
	s_mov_b32 m0, s50
	s_add_u32 s4, s4, 0x40080
	global_load_lds_dwordx4 v133, s[16:17]
	s_mov_b32 m0, s42
	s_addc_u32 s5, s5, 0
	global_load_lds_dwordx4 v132, s[6:7]
	s_mov_b32 m0, s43
	s_nop 0
	global_load_lds_dwordx4 v132, s[4:5]
	s_waitcnt vmcnt(8) lgkmcnt(0)
	s_barrier
	v_mfma_f32_16x16x32_bf16 v[62:65], v[136:139], v[168:171], v[62:65]
	v_mfma_f32_16x16x32_bf16 v[58:61], v[144:147], v[168:171], v[58:61]
	v_mfma_f32_16x16x32_bf16 v[54:57], v[136:139], v[176:179], v[54:57]
	v_mfma_f32_16x16x32_bf16 v[50:53], v[144:147], v[176:179], v[50:53]
	v_mfma_f32_16x16x32_bf16 v[38:41], v[136:139], v[184:187], v[38:41]
	v_mfma_f32_16x16x32_bf16 v[34:37], v[144:147], v[184:187], v[34:37]
	v_mfma_f32_16x16x32_bf16 v[22:25], v[136:139], v[192:195], v[22:25]
	v_mfma_f32_16x16x32_bf16 v[18:21], v[144:147], v[192:195], v[18:21]
	v_mfma_f32_16x16x32_bf16 v[62:65], v[140:143], v[172:175], v[62:65]
	v_mfma_f32_16x16x32_bf16 v[58:61], v[148:151], v[172:175], v[58:61]
	v_mfma_f32_16x16x32_bf16 v[54:57], v[140:143], v[180:183], v[54:57]
	v_mfma_f32_16x16x32_bf16 v[50:53], v[148:151], v[180:183], v[50:53]
	v_mfma_f32_16x16x32_bf16 v[38:41], v[140:143], v[188:191], v[38:41]
	v_mfma_f32_16x16x32_bf16 v[34:37], v[148:151], v[188:191], v[34:37]
	v_mfma_f32_16x16x32_bf16 v[22:25], v[140:143], v[196:199], v[22:25]
	v_mfma_f32_16x16x32_bf16 v[18:21], v[148:151], v[196:199], v[18:21]
	v_mfma_f32_16x16x32_bf16 v[46:49], v[152:155], v[168:171], v[46:49]
	v_mfma_f32_16x16x32_bf16 v[42:45], v[160:163], v[168:171], v[42:45]
	v_mfma_f32_16x16x32_bf16 v[30:33], v[152:155], v[176:179], v[30:33]
	v_mfma_f32_16x16x32_bf16 v[26:29], v[160:163], v[176:179], v[26:29]
	v_mfma_f32_16x16x32_bf16 v[14:17], v[152:155], v[184:187], v[14:17]
	v_mfma_f32_16x16x32_bf16 v[10:13], v[160:163], v[184:187], v[10:13]
	v_mfma_f32_16x16x32_bf16 v[6:9], v[152:155], v[192:195], v[6:9]
	v_mfma_f32_16x16x32_bf16 v[2:5], v[160:163], v[192:195], v[2:5]
	v_mfma_f32_16x16x32_bf16 v[46:49], v[156:159], v[172:175], v[46:49]
	v_mfma_f32_16x16x32_bf16 v[42:45], v[164:167], v[172:175], v[42:45]
	v_mfma_f32_16x16x32_bf16 v[30:33], v[156:159], v[180:183], v[30:33]
	v_mfma_f32_16x16x32_bf16 v[26:29], v[164:167], v[180:183], v[26:29]
	v_mfma_f32_16x16x32_bf16 v[14:17], v[156:159], v[188:191], v[14:17]
	v_mfma_f32_16x16x32_bf16 v[10:13], v[164:167], v[188:191], v[10:13]
	v_mfma_f32_16x16x32_bf16 v[6:9], v[156:159], v[196:199], v[6:9]
	v_mfma_f32_16x16x32_bf16 v[2:5], v[164:167], v[196:199], v[2:5]
	s_barrier
	s_add_i32 s72, s72, 2
	s_add_u32 s64, s64, 0x100
	s_addc_u32 s66, s66, 0
	s_add_u32 s68, s68, 0x100
	s_addc_u32 s70, s70, 0
	s_cmp_gt_u32 s72, 29
	s_cbranch_scc0 .LBB0_1046
	s_and_b64 vcc, exec, s[12:13]
	s_cbranch_vccz .LBB0_1049
	s_barrier

.LBB0_1522:
	v_add_u32_e32 v154, 0x14000, v223
	v_add_u32_e32 v178, 0x18000, v223
	ds_read_b128 v[138:141], v154
	ds_read_b128 v[142:145], v154 offset:1024
	ds_read_b128 v[146:149], v154 offset:2048
	ds_read_b128 v[154:157], v154 offset:3072
	ds_read_b128 v[162:165], v178
	ds_read_b128 v[170:173], v178 offset:1024
	ds_read_b128 v[174:177], v178 offset:2048
	ds_read_b128 v[178:181], v178 offset:3072
	s_add_u32 s10, s6, 0xfff60080
	s_addc_u32 s11, s7, -1
	s_cmp_eq_u32 s70, 28
	s_cselect_b32 s10, s18, s10
	s_cselect_b32 s11, s19, s11
	s_cselect_b32 s22, s64, s66
	s_cselect_b32 s23, s15, s68
	s_add_u32 s16, s10, 0x80
	s_addc_u32 s17, s11, 0
	s_mov_b64 s[74:75], s[6:7]
	ds_read_b128 v[194:197], v221
	ds_read_b128 v[198:201], v221 offset:1024
	ds_read_b128 v[202:205], v221 offset:2048
	ds_read_b128 v[206:209], v221 offset:3072
	ds_read_b128 v[210:213], v221 offset:4096
	ds_read_b128 v[214:217], v221 offset:5120
	ds_read_b128 v[228:231], v221 offset:6144
	ds_read_b128 v[238:241], v221 offset:7168
	ds_read_b128 v[242:245], v221 offset:8192
	ds_read_b128 v[246:249], v221 offset:9216
	s_add_i32 m0, s28, 0xf000
	s_nop 0
	global_load_lds_dwordx4 v0, s[74:75]
	s_add_u32 s74, s6, 0x40000
	s_addc_u32 s75, s7, 0
	s_mov_b32 m0, s51
	s_nop 0
	global_load_lds_dwordx4 v0, s[74:75]
	s_waitcnt vmcnt(8) lgkmcnt(0)
	s_barrier
	v_mfma_f32_16x16x32_bf16 v[190:193], v[138:141], v[194:197], v[190:193]
	v_mfma_f32_16x16x32_bf16 v[186:189], v[146:149], v[194:197], v[186:189]
	v_mfma_f32_16x16x32_bf16 v[158:161], v[138:141], v[202:205], v[158:161]
	v_mfma_f32_16x16x32_bf16 v[150:153], v[146:149], v[202:205], v[150:153]
	v_mfma_f32_16x16x32_bf16 v[126:129], v[138:141], v[210:213], v[126:129]
	v_mfma_f32_16x16x32_bf16 v[122:125], v[146:149], v[210:213], v[122:125]
	v_mfma_f32_16x16x32_bf16 v[110:113], v[138:141], v[228:231], v[110:113]
	v_mfma_f32_16x16x32_bf16 v[106:109], v[146:149], v[228:231], v[106:109]
	v_mfma_f32_16x16x32_bf16 v[94:97], v[138:141], v[242:245], v[94:97]
	v_mfma_f32_16x16x32_bf16 v[90:93], v[146:149], v[242:245], v[90:93]
	v_mfma_f32_16x16x32_bf16 v[190:193], v[142:145], v[198:201], v[190:193]
	v_mfma_f32_16x16x32_bf16 v[186:189], v[154:157], v[198:201], v[186:189]
	v_mfma_f32_16x16x32_bf16 v[158:161], v[142:145], v[206:209], v[158:161]
	v_mfma_f32_16x16x32_bf16 v[150:153], v[154:157], v[206:209], v[150:153]
	v_mfma_f32_16x16x32_bf16 v[126:129], v[142:145], v[214:217], v[126:129]
	v_mfma_f32_16x16x32_bf16 v[122:125], v[154:157], v[214:217], v[122:125]
	v_mfma_f32_16x16x32_bf16 v[110:113], v[142:145], v[238:241], v[110:113]
	v_mfma_f32_16x16x32_bf16 v[106:109], v[154:157], v[238:241], v[106:109]
	v_mfma_f32_16x16x32_bf16 v[94:97], v[142:145], v[246:249], v[94:97]
	v_mfma_f32_16x16x32_bf16 v[90:93], v[154:157], v[246:249], v[90:93]
	v_mfma_f32_16x16x32_bf16 v[182:185], v[162:165], v[194:197], v[182:185]
	v_mfma_f32_16x16x32_bf16 v[166:169], v[174:177], v[194:197], v[166:169]
	v_mfma_f32_16x16x32_bf16 v[134:137], v[162:165], v[202:205], v[134:137]
	v_mfma_f32_16x16x32_bf16 v[130:133], v[174:177], v[202:205], v[130:133]
	v_mfma_f32_16x16x32_bf16 v[118:121], v[162:165], v[210:213], v[118:121]
	v_mfma_f32_16x16x32_bf16 v[114:117], v[174:177], v[210:213], v[114:117]
	v_mfma_f32_16x16x32_bf16 v[102:105], v[162:165], v[228:231], v[102:105]
	v_mfma_f32_16x16x32_bf16 v[98:101], v[174:177], v[228:231], v[98:101]
	v_mfma_f32_16x16x32_bf16 v[86:89], v[162:165], v[242:245], v[86:89]
	v_mfma_f32_16x16x32_bf16 v[82:85], v[174:177], v[242:245], v[82:85]
	v_mfma_f32_16x16x32_bf16 v[182:185], v[170:173], v[198:201], v[182:185]
	v_mfma_f32_16x16x32_bf16 v[166:169], v[178:181], v[198:201], v[166:169]
	v_mfma_f32_16x16x32_bf16 v[134:137], v[170:173], v[206:209], v[134:137]
	v_mfma_f32_16x16x32_bf16 v[130:133], v[178:181], v[206:209], v[130:133]
	v_mfma_f32_16x16x32_bf16 v[118:121], v[170:173], v[214:217], v[118:121]
	v_mfma_f32_16x16x32_bf16 v[114:117], v[178:181], v[214:217], v[114:117]
	v_mfma_f32_16x16x32_bf16 v[102:105], v[170:173], v[238:241], v[102:105]
	v_mfma_f32_16x16x32_bf16 v[98:101], v[178:181], v[238:241], v[98:101]
	v_mfma_f32_16x16x32_bf16 v[86:89], v[170:173], v[246:249], v[86:89]
	v_mfma_f32_16x16x32_bf16 v[82:85], v[178:181], v[246:249], v[82:85]
	s_barrier
	s_mov_b64 s[74:75], s[22:23]
	s_mov_b32 m0, s29
	ds_read_b128 v[194:197], v221 offset:20480
	ds_read_b128 v[198:201], v221 offset:21504
	ds_read_b128 v[202:205], v221 offset:22528
	ds_read_b128 v[206:209], v221 offset:23552
	ds_read_b128 v[210:213], v221 offset:24576
	ds_read_b128 v[214:217], v221 offset:25600
	ds_read_b128 v[228:231], v221 offset:26624
	ds_read_b128 v[238:241], v221 offset:27648
	ds_read_b128 v[242:245], v221 offset:28672
	ds_read_b128 v[246:249], v221 offset:29696
	global_load_lds_dwordx4 v220, s[74:75]
	s_add_u32 s74, s22, 0x40000
	s_addc_u32 s75, s23, 0
	s_mov_b32 m0, s30
	s_nop 0
	global_load_lds_dwordx4 v220, s[74:75]
	s_add_u32 s74, s22, 0x80000
	s_addc_u32 s75, s23, 0
	s_mov_b32 m0, s31
	s_nop 0
	global_load_lds_dwordx4 v220, s[74:75]
	s_add_u32 s74, s22, 0xc0000
	s_addc_u32 s75, s23, 0
	s_mov_b32 m0, s34
	s_nop 0
	global_load_lds_dwordx4 v220, s[74:75]
	s_mov_b64 s[74:75], s[10:11]
	s_mov_b32 m0, s28
	s_nop 0
	global_load_lds_dwordx4 v0, s[74:75]
	s_add_u32 s74, s10, 0x40000
	s_addc_u32 s75, s11, 0
	s_mov_b32 m0, s35
	s_nop 0
	global_load_lds_dwordx4 v0, s[74:75]
	s_waitcnt vmcnt(8) lgkmcnt(0)
	s_barrier
	v_mfma_f32_16x16x32_bf16 v[78:81], v[138:141], v[194:197], v[78:81]
	v_mfma_f32_16x16x32_bf16 v[74:77], v[146:149], v[194:197], v[74:77]
	v_mfma_f32_16x16x32_bf16 v[62:65], v[138:141], v[202:205], v[62:65]
	v_mfma_f32_16x16x32_bf16 v[58:61], v[146:149], v[202:205], v[58:61]
	v_mfma_f32_16x16x32_bf16 v[46:49], v[138:141], v[210:213], v[46:49]
	v_mfma_f32_16x16x32_bf16 v[42:45], v[146:149], v[210:213], v[42:45]
	v_mfma_f32_16x16x32_bf16 v[30:33], v[138:141], v[228:231], v[30:33]
	v_mfma_f32_16x16x32_bf16 v[26:29], v[146:149], v[228:231], v[26:29]
	v_mfma_f32_16x16x32_bf16 v[14:17], v[138:141], v[242:245], v[14:17]
	v_mfma_f32_16x16x32_bf16 v[10:13], v[146:149], v[242:245], v[10:13]
	v_mfma_f32_16x16x32_bf16 v[78:81], v[142:145], v[198:201], v[78:81]
	v_mfma_f32_16x16x32_bf16 v[74:77], v[154:157], v[198:201], v[74:77]
	v_mfma_f32_16x16x32_bf16 v[62:65], v[142:145], v[206:209], v[62:65]
	v_mfma_f32_16x16x32_bf16 v[58:61], v[154:157], v[206:209], v[58:61]
	v_mfma_f32_16x16x32_bf16 v[46:49], v[142:145], v[214:217], v[46:49]
	v_mfma_f32_16x16x32_bf16 v[42:45], v[154:157], v[214:217], v[42:45]
	v_mfma_f32_16x16x32_bf16 v[30:33], v[142:145], v[238:241], v[30:33]
	v_mfma_f32_16x16x32_bf16 v[26:29], v[154:157], v[238:241], v[26:29]
	v_mfma_f32_16x16x32_bf16 v[14:17], v[142:145], v[246:249], v[14:17]
	v_mfma_f32_16x16x32_bf16 v[10:13], v[154:157], v[246:249], v[10:13]
	v_mfma_f32_16x16x32_bf16 v[70:73], v[162:165], v[194:197], v[70:73]
	v_mfma_f32_16x16x32_bf16 v[66:69], v[174:177], v[194:197], v[66:69]
	v_mfma_f32_16x16x32_bf16 v[54:57], v[162:165], v[202:205], v[54:57]
	v_mfma_f32_16x16x32_bf16 v[50:53], v[174:177], v[202:205], v[50:53]
	v_mfma_f32_16x16x32_bf16 v[38:41], v[162:165], v[210:213], v[38:41]
	v_mfma_f32_16x16x32_bf16 v[34:37], v[174:177], v[210:213], v[34:37]
	v_mfma_f32_16x16x32_bf16 v[22:25], v[162:165], v[228:231], v[22:25]
	v_mfma_f32_16x16x32_bf16 v[18:21], v[174:177], v[228:231], v[18:21]
	v_mfma_f32_16x16x32_bf16 v[6:9], v[162:165], v[242:245], v[6:9]
	v_mfma_f32_16x16x32_bf16 v[2:5], v[174:177], v[242:245], v[2:5]
	v_mfma_f32_16x16x32_bf16 v[70:73], v[170:173], v[198:201], v[70:73]
	v_mfma_f32_16x16x32_bf16 v[66:69], v[178:181], v[198:201], v[66:69]
	v_mfma_f32_16x16x32_bf16 v[54:57], v[170:173], v[206:209], v[54:57]
	v_mfma_f32_16x16x32_bf16 v[50:53], v[178:181], v[206:209], v[50:53]
	v_mfma_f32_16x16x32_bf16 v[38:41], v[170:173], v[214:217], v[38:41]
	v_mfma_f32_16x16x32_bf16 v[34:37], v[178:181], v[214:217], v[34:37]
	v_mfma_f32_16x16x32_bf16 v[22:25], v[170:173], v[238:241], v[22:25]
	v_mfma_f32_16x16x32_bf16 v[18:21], v[178:181], v[238:241], v[18:21]
	v_mfma_f32_16x16x32_bf16 v[6:9], v[170:173], v[246:249], v[6:9]
	v_mfma_f32_16x16x32_bf16 v[2:5], v[178:181], v[246:249], v[2:5]
	s_barrier
	v_add_u32_e32 v154, 0x1c000, v223
	v_add_u32_e32 v178, 0x20000, v223
	ds_read_b128 v[138:141], v154
	ds_read_b128 v[142:145], v154 offset:1024
	ds_read_b128 v[146:149], v154 offset:2048
	ds_read_b128 v[154:157], v154 offset:3072
	ds_read_b128 v[162:165], v178
	ds_read_b128 v[170:173], v178 offset:1024
	ds_read_b128 v[174:177], v178 offset:2048
	ds_read_b128 v[178:181], v178 offset:3072
	s_add_u32 s74, s10, 0xa0000
	s_addc_u32 s75, s11, 0
	s_mov_b32 m0, s36
	ds_read_b128 v[194:197], v221 offset:40960
	ds_read_b128 v[198:201], v221 offset:41984
	ds_read_b128 v[202:205], v221 offset:43008
	ds_read_b128 v[206:209], v221 offset:44032
	ds_read_b128 v[210:213], v221 offset:45056
	ds_read_b128 v[214:217], v221 offset:46080
	ds_read_b128 v[228:231], v221 offset:47104
	ds_read_b128 v[238:241], v221 offset:48128
	ds_read_b128 v[242:245], v221 offset:49152
	ds_read_b128 v[246:249], v221 offset:50176
	global_load_lds_dwordx4 v0, s[74:75]
	s_add_u32 s74, s10, 0xe0000
	s_addc_u32 s75, s11, 0
	s_mov_b32 m0, s37
	s_nop 0
	global_load_lds_dwordx4 v0, s[74:75]
	s_waitcnt vmcnt(8) lgkmcnt(0)
	s_barrier
	v_mfma_f32_16x16x32_bf16 v[190:193], v[138:141], v[194:197], v[190:193]
	v_mfma_f32_16x16x32_bf16 v[186:189], v[146:149], v[194:197], v[186:189]
	v_mfma_f32_16x16x32_bf16 v[158:161], v[138:141], v[202:205], v[158:161]
	v_mfma_f32_16x16x32_bf16 v[150:153], v[146:149], v[202:205], v[150:153]
	v_mfma_f32_16x16x32_bf16 v[126:129], v[138:141], v[210:213], v[126:129]
	v_mfma_f32_16x16x32_bf16 v[122:125], v[146:149], v[210:213], v[122:125]
	v_mfma_f32_16x16x32_bf16 v[110:113], v[138:141], v[228:231], v[110:113]
	v_mfma_f32_16x16x32_bf16 v[106:109], v[146:149], v[228:231], v[106:109]
	v_mfma_f32_16x16x32_bf16 v[94:97], v[138:141], v[242:245], v[94:97]
	v_mfma_f32_16x16x32_bf16 v[90:93], v[146:149], v[242:245], v[90:93]
	v_mfma_f32_16x16x32_bf16 v[190:193], v[142:145], v[198:201], v[190:193]
	v_mfma_f32_16x16x32_bf16 v[186:189], v[154:157], v[198:201], v[186:189]
	v_mfma_f32_16x16x32_bf16 v[158:161], v[142:145], v[206:209], v[158:161]
	v_mfma_f32_16x16x32_bf16 v[150:153], v[154:157], v[206:209], v[150:153]
	v_mfma_f32_16x16x32_bf16 v[126:129], v[142:145], v[214:217], v[126:129]
	v_mfma_f32_16x16x32_bf16 v[122:125], v[154:157], v[214:217], v[122:125]
	v_mfma_f32_16x16x32_bf16 v[110:113], v[142:145], v[238:241], v[110:113]
	v_mfma_f32_16x16x32_bf16 v[106:109], v[154:157], v[238:241], v[106:109]
	v_mfma_f32_16x16x32_bf16 v[94:97], v[142:145], v[246:249], v[94:97]
	v_mfma_f32_16x16x32_bf16 v[90:93], v[154:157], v[246:249], v[90:93]
	v_mfma_f32_16x16x32_bf16 v[182:185], v[162:165], v[194:197], v[182:185]
	v_mfma_f32_16x16x32_bf16 v[166:169], v[174:177], v[194:197], v[166:169]
	v_mfma_f32_16x16x32_bf16 v[134:137], v[162:165], v[202:205], v[134:137]
	v_mfma_f32_16x16x32_bf16 v[130:133], v[174:177], v[202:205], v[130:133]
	v_mfma_f32_16x16x32_bf16 v[118:121], v[162:165], v[210:213], v[118:121]
	v_mfma_f32_16x16x32_bf16 v[114:117], v[174:177], v[210:213], v[114:117]
	v_mfma_f32_16x16x32_bf16 v[102:105], v[162:165], v[228:231], v[102:105]
	v_mfma_f32_16x16x32_bf16 v[98:101], v[174:177], v[228:231], v[98:101]
	v_mfma_f32_16x16x32_bf16 v[86:89], v[162:165], v[242:245], v[86:89]
	v_mfma_f32_16x16x32_bf16 v[82:85], v[174:177], v[242:245], v[82:85]
	v_mfma_f32_16x16x32_bf16 v[182:185], v[170:173], v[198:201], v[182:185]
	v_mfma_f32_16x16x32_bf16 v[166:169], v[178:181], v[198:201], v[166:169]
	v_mfma_f32_16x16x32_bf16 v[134:137], v[170:173], v[206:209], v[134:137]
	v_mfma_f32_16x16x32_bf16 v[130:133], v[178:181], v[206:209], v[130:133]
	v_mfma_f32_16x16x32_bf16 v[118:121], v[170:173], v[214:217], v[118:121]
	v_mfma_f32_16x16x32_bf16 v[114:117], v[178:181], v[214:217], v[114:117]
	v_mfma_f32_16x16x32_bf16 v[102:105], v[170:173], v[238:241], v[102:105]
	v_mfma_f32_16x16x32_bf16 v[98:101], v[178:181], v[238:241], v[98:101]
	v_mfma_f32_16x16x32_bf16 v[86:89], v[170:173], v[246:249], v[86:89]
	v_mfma_f32_16x16x32_bf16 v[82:85], v[178:181], v[246:249], v[82:85]
	s_barrier
	s_add_u32 s74, s22, 0x80
	s_addc_u32 s75, s23, 0
	s_mov_b32 m0, s40
	ds_read_b128 v[194:197], v221 offset:61440
	ds_read_b128 v[198:201], v221 offset:62464
	ds_read_b128 v[202:205], v221 offset:63488
	ds_read_b128 v[206:209], v221 offset:64512
	ds_read_b128 v[210:213], v222 offset:4096
	ds_read_b128 v[214:217], v222 offset:5120
	ds_read_b128 v[228:231], v222 offset:6144
	ds_read_b128 v[238:241], v222 offset:7168
	ds_read_b128 v[242:245], v222 offset:8192
	ds_read_b128 v[246:249], v222 offset:9216
	global_load_lds_dwordx4 v220, s[74:75]
	s_add_u32 s74, s22, 0x40080
	s_addc_u32 s75, s23, 0
	s_mov_b32 m0, s41
	s_nop 0
	global_load_lds_dwordx4 v220, s[74:75]
	s_add_u32 s74, s22, 0x80080
	s_addc_u32 s75, s23, 0
	s_mov_b32 m0, s48
	s_add_u32 s22, s22, 0xc0080
	global_load_lds_dwordx4 v220, s[74:75]
	s_addc_u32 s23, s23, 0
	s_mov_b32 m0, s50
	s_add_u32 s10, s10, 0x40080
	global_load_lds_dwordx4 v220, s[22:23]
	s_mov_b32 m0, s42
	s_addc_u32 s11, s11, 0
	global_load_lds_dwordx4 v0, s[16:17]
	s_mov_b32 m0, s43
	s_nop 0
	global_load_lds_dwordx4 v0, s[10:11]
	s_waitcnt vmcnt(8) lgkmcnt(0)
	s_barrier
	v_mfma_f32_16x16x32_bf16 v[78:81], v[138:141], v[194:197], v[78:81]
	v_mfma_f32_16x16x32_bf16 v[74:77], v[146:149], v[194:197], v[74:77]
	v_mfma_f32_16x16x32_bf16 v[62:65], v[138:141], v[202:205], v[62:65]
	v_mfma_f32_16x16x32_bf16 v[58:61], v[146:149], v[202:205], v[58:61]
	v_mfma_f32_16x16x32_bf16 v[46:49], v[138:141], v[210:213], v[46:49]
	v_mfma_f32_16x16x32_bf16 v[42:45], v[146:149], v[210:213], v[42:45]
	v_mfma_f32_16x16x32_bf16 v[30:33], v[138:141], v[228:231], v[30:33]
	v_mfma_f32_16x16x32_bf16 v[26:29], v[146:149], v[228:231], v[26:29]
	v_mfma_f32_16x16x32_bf16 v[14:17], v[138:141], v[242:245], v[14:17]
	v_mfma_f32_16x16x32_bf16 v[10:13], v[146:149], v[242:245], v[10:13]
	v_mfma_f32_16x16x32_bf16 v[78:81], v[142:145], v[198:201], v[78:81]
	v_mfma_f32_16x16x32_bf16 v[74:77], v[154:157], v[198:201], v[74:77]
	v_mfma_f32_16x16x32_bf16 v[62:65], v[142:145], v[206:209], v[62:65]
	v_mfma_f32_16x16x32_bf16 v[58:61], v[154:157], v[206:209], v[58:61]
	v_mfma_f32_16x16x32_bf16 v[46:49], v[142:145], v[214:217], v[46:49]
	v_mfma_f32_16x16x32_bf16 v[42:45], v[154:157], v[214:217], v[42:45]
	v_mfma_f32_16x16x32_bf16 v[30:33], v[142:145], v[238:241], v[30:33]
	v_mfma_f32_16x16x32_bf16 v[26:29], v[154:157], v[238:241], v[26:29]
	v_mfma_f32_16x16x32_bf16 v[14:17], v[142:145], v[246:249], v[14:17]
	v_mfma_f32_16x16x32_bf16 v[10:13], v[154:157], v[246:249], v[10:13]
	v_mfma_f32_16x16x32_bf16 v[70:73], v[162:165], v[194:197], v[70:73]
	v_mfma_f32_16x16x32_bf16 v[66:69], v[174:177], v[194:197], v[66:69]
	v_mfma_f32_16x16x32_bf16 v[54:57], v[162:165], v[202:205], v[54:57]
	v_mfma_f32_16x16x32_bf16 v[50:53], v[174:177], v[202:205], v[50:53]
	v_mfma_f32_16x16x32_bf16 v[38:41], v[162:165], v[210:213], v[38:41]
	v_mfma_f32_16x16x32_bf16 v[34:37], v[174:177], v[210:213], v[34:37]
	v_mfma_f32_16x16x32_bf16 v[22:25], v[162:165], v[228:231], v[22:25]
	v_mfma_f32_16x16x32_bf16 v[18:21], v[174:177], v[228:231], v[18:21]
	v_mfma_f32_16x16x32_bf16 v[6:9], v[162:165], v[242:245], v[6:9]
	v_mfma_f32_16x16x32_bf16 v[2:5], v[174:177], v[242:245], v[2:5]
	v_mfma_f32_16x16x32_bf16 v[70:73], v[170:173], v[198:201], v[70:73]
	v_mfma_f32_16x16x32_bf16 v[66:69], v[178:181], v[198:201], v[66:69]
	v_mfma_f32_16x16x32_bf16 v[54:57], v[170:173], v[206:209], v[54:57]
	v_mfma_f32_16x16x32_bf16 v[50:53], v[178:181], v[206:209], v[50:53]
	v_mfma_f32_16x16x32_bf16 v[38:41], v[170:173], v[214:217], v[38:41]
	v_mfma_f32_16x16x32_bf16 v[34:37], v[178:181], v[214:217], v[34:37]
	v_mfma_f32_16x16x32_bf16 v[22:25], v[170:173], v[238:241], v[22:25]
	v_mfma_f32_16x16x32_bf16 v[18:21], v[178:181], v[238:241], v[18:21]
	v_mfma_f32_16x16x32_bf16 v[6:9], v[170:173], v[246:249], v[6:9]
	v_mfma_f32_16x16x32_bf16 v[2:5], v[178:181], v[246:249], v[2:5]
	s_barrier
	s_add_i32 s70, s70, 2
	s_add_u32 s6, s6, 0x100
	s_addc_u32 s7, s7, 0
	s_add_u32 s66, s66, 0x100
	s_addc_u32 s68, s68, 0
	s_cmp_gt_u32 s70, 29
	s_cbranch_scc0 .LBB0_1522
	s_and_b64 vcc, exec, s[12:13]
	s_cbranch_vccz .LBB0_1525
	s_barrier

.LBB0_1546:
	v_add_u32_e32 v158, 0x14000, v223
	v_add_u32_e32 v178, 0x18000, v223
	ds_read_b128 v[142:145], v158
	ds_read_b128 v[146:149], v158 offset:1024
	ds_read_b128 v[154:157], v158 offset:2048
	ds_read_b128 v[158:161], v158 offset:3072
	ds_read_b128 v[166:169], v178
	ds_read_b128 v[170:173], v178 offset:1024
	ds_read_b128 v[174:177], v178 offset:2048
	ds_read_b128 v[178:181], v178 offset:3072
	s_add_u32 s10, s6, 0xfff60080
	s_addc_u32 s11, s7, -1
	s_cmp_eq_u32 s97, 28
	s_cselect_b32 s10, s18, s10
	s_cselect_b32 s11, s19, s11
	s_cselect_b32 s22, s72, s84
	s_cselect_b32 s23, s15, s92
	s_add_u32 s16, s10, 0x80
	s_addc_u32 s17, s11, 0
	s_mov_b64 s[74:75], s[6:7]
	ds_read_b128 v[194:197], v221
	ds_read_b128 v[198:201], v221 offset:1024
	ds_read_b128 v[202:205], v221 offset:2048
	ds_read_b128 v[206:209], v221 offset:3072
	ds_read_b128 v[210:213], v221 offset:4096
	ds_read_b128 v[214:217], v221 offset:5120
	ds_read_b128 v[228:231], v221 offset:6144
	ds_read_b128 v[238:241], v221 offset:7168
	ds_read_b128 v[242:245], v221 offset:8192
	ds_read_b128 v[246:249], v221 offset:9216
	s_add_i32 m0, s28, 0xf000
	s_nop 0
	global_load_lds_dwordx4 v0, s[74:75]
	s_add_u32 s74, s6, 0x40000
	s_addc_u32 s75, s7, 0
	s_mov_b32 m0, s60
	s_nop 0
	global_load_lds_dwordx4 v0, s[74:75]
	s_add_u32 s74, s6, 0x80000
	s_addc_u32 s75, s7, 0
	s_mov_b32 m0, s62
	s_nop 0
	global_load_lds_dwordx4 v0, s[74:75]
	s_waitcnt vmcnt(10) lgkmcnt(0)
	s_barrier
	v_mfma_f32_16x16x32_bf16 v[190:193], v[142:145], v[194:197], v[190:193]
	v_mfma_f32_16x16x32_bf16 v[186:189], v[154:157], v[194:197], v[186:189]
	v_mfma_f32_16x16x32_bf16 v[150:153], v[142:145], v[202:205], v[150:153]
	v_mfma_f32_16x16x32_bf16 v[138:141], v[154:157], v[202:205], v[138:141]
	v_mfma_f32_16x16x32_bf16 v[126:129], v[142:145], v[210:213], v[126:129]
	v_mfma_f32_16x16x32_bf16 v[122:125], v[154:157], v[210:213], v[122:125]
	v_mfma_f32_16x16x32_bf16 v[110:113], v[142:145], v[228:231], v[110:113]
	v_mfma_f32_16x16x32_bf16 v[106:109], v[154:157], v[228:231], v[106:109]
	v_mfma_f32_16x16x32_bf16 v[94:97], v[142:145], v[242:245], v[94:97]
	v_mfma_f32_16x16x32_bf16 v[90:93], v[154:157], v[242:245], v[90:93]
	v_mfma_f32_16x16x32_bf16 v[190:193], v[146:149], v[198:201], v[190:193]
	v_mfma_f32_16x16x32_bf16 v[186:189], v[158:161], v[198:201], v[186:189]
	v_mfma_f32_16x16x32_bf16 v[150:153], v[146:149], v[206:209], v[150:153]
	v_mfma_f32_16x16x32_bf16 v[138:141], v[158:161], v[206:209], v[138:141]
	v_mfma_f32_16x16x32_bf16 v[126:129], v[146:149], v[214:217], v[126:129]
	v_mfma_f32_16x16x32_bf16 v[122:125], v[158:161], v[214:217], v[122:125]
	v_mfma_f32_16x16x32_bf16 v[110:113], v[146:149], v[238:241], v[110:113]
	v_mfma_f32_16x16x32_bf16 v[106:109], v[158:161], v[238:241], v[106:109]
	v_mfma_f32_16x16x32_bf16 v[94:97], v[146:149], v[246:249], v[94:97]
	v_mfma_f32_16x16x32_bf16 v[90:93], v[158:161], v[246:249], v[90:93]
	v_mfma_f32_16x16x32_bf16 v[182:185], v[166:169], v[194:197], v[182:185]
	v_mfma_f32_16x16x32_bf16 v[162:165], v[174:177], v[194:197], v[162:165]
	v_mfma_f32_16x16x32_bf16 v[134:137], v[166:169], v[202:205], v[134:137]
	v_mfma_f32_16x16x32_bf16 v[130:133], v[174:177], v[202:205], v[130:133]
	v_mfma_f32_16x16x32_bf16 v[118:121], v[166:169], v[210:213], v[118:121]
	v_mfma_f32_16x16x32_bf16 v[114:117], v[174:177], v[210:213], v[114:117]
	v_mfma_f32_16x16x32_bf16 v[102:105], v[166:169], v[228:231], v[102:105]
	v_mfma_f32_16x16x32_bf16 v[98:101], v[174:177], v[228:231], v[98:101]
	v_mfma_f32_16x16x32_bf16 v[86:89], v[166:169], v[242:245], v[86:89]
	v_mfma_f32_16x16x32_bf16 v[82:85], v[174:177], v[242:245], v[82:85]
	v_mfma_f32_16x16x32_bf16 v[182:185], v[170:173], v[198:201], v[182:185]
	v_mfma_f32_16x16x32_bf16 v[162:165], v[178:181], v[198:201], v[162:165]
	v_mfma_f32_16x16x32_bf16 v[134:137], v[170:173], v[206:209], v[134:137]
	v_mfma_f32_16x16x32_bf16 v[130:133], v[178:181], v[206:209], v[130:133]
	v_mfma_f32_16x16x32_bf16 v[118:121], v[170:173], v[214:217], v[118:121]
	v_mfma_f32_16x16x32_bf16 v[114:117], v[178:181], v[214:217], v[114:117]
	v_mfma_f32_16x16x32_bf16 v[102:105], v[170:173], v[238:241], v[102:105]
	v_mfma_f32_16x16x32_bf16 v[98:101], v[178:181], v[238:241], v[98:101]
	v_mfma_f32_16x16x32_bf16 v[86:89], v[170:173], v[246:249], v[86:89]
	v_mfma_f32_16x16x32_bf16 v[82:85], v[178:181], v[246:249], v[82:85]
	s_barrier
	s_mov_b64 s[74:75], s[22:23]
	s_mov_b32 m0, s29
	ds_read_b128 v[194:197], v221 offset:20480
	ds_read_b128 v[198:201], v221 offset:21504
	ds_read_b128 v[202:205], v221 offset:22528
	ds_read_b128 v[206:209], v221 offset:23552
	ds_read_b128 v[210:213], v221 offset:24576
	ds_read_b128 v[214:217], v221 offset:25600
	ds_read_b128 v[228:231], v221 offset:26624
	ds_read_b128 v[238:241], v221 offset:27648
	ds_read_b128 v[242:245], v221 offset:28672
	ds_read_b128 v[246:249], v221 offset:29696
	global_load_lds_dwordx4 v220, s[74:75]
	s_add_u32 s74, s22, 0x40000
	s_addc_u32 s75, s23, 0
	s_mov_b32 m0, s30
	s_nop 0
	global_load_lds_dwordx4 v220, s[74:75]
	s_add_u32 s74, s22, 0x80000
	s_addc_u32 s75, s23, 0
	s_mov_b32 m0, s31
	s_nop 0
	global_load_lds_dwordx4 v220, s[74:75]
	s_add_u32 s74, s22, 0xc0000
	s_addc_u32 s75, s23, 0
	s_mov_b32 m0, s34
	s_nop 0
	global_load_lds_dwordx4 v220, s[74:75]
	s_mov_b64 s[74:75], s[10:11]
	s_mov_b32 m0, s28
	s_nop 0
	global_load_lds_dwordx4 v0, s[74:75]
	s_add_u32 s74, s10, 0x40000
	s_addc_u32 s75, s11, 0
	s_mov_b32 m0, s35
	s_nop 0
	global_load_lds_dwordx4 v0, s[74:75]
	s_add_u32 s74, s10, 0x80000
	s_addc_u32 s75, s11, 0
	s_mov_b32 m0, s36
	s_nop 0
	global_load_lds_dwordx4 v0, s[74:75]
	s_waitcnt vmcnt(10) lgkmcnt(0)
	s_barrier
	v_mfma_f32_16x16x32_bf16 v[78:81], v[142:145], v[194:197], v[78:81]
	v_mfma_f32_16x16x32_bf16 v[74:77], v[154:157], v[194:197], v[74:77]
	v_mfma_f32_16x16x32_bf16 v[62:65], v[142:145], v[202:205], v[62:65]
	v_mfma_f32_16x16x32_bf16 v[58:61], v[154:157], v[202:205], v[58:61]
	v_mfma_f32_16x16x32_bf16 v[46:49], v[142:145], v[210:213], v[46:49]
	v_mfma_f32_16x16x32_bf16 v[42:45], v[154:157], v[210:213], v[42:45]
	v_mfma_f32_16x16x32_bf16 v[30:33], v[142:145], v[228:231], v[30:33]
	v_mfma_f32_16x16x32_bf16 v[26:29], v[154:157], v[228:231], v[26:29]
	v_mfma_f32_16x16x32_bf16 v[14:17], v[142:145], v[242:245], v[14:17]
	v_mfma_f32_16x16x32_bf16 v[10:13], v[154:157], v[242:245], v[10:13]
	v_mfma_f32_16x16x32_bf16 v[78:81], v[146:149], v[198:201], v[78:81]
	v_mfma_f32_16x16x32_bf16 v[74:77], v[158:161], v[198:201], v[74:77]
	v_mfma_f32_16x16x32_bf16 v[62:65], v[146:149], v[206:209], v[62:65]
	v_mfma_f32_16x16x32_bf16 v[58:61], v[158:161], v[206:209], v[58:61]
	v_mfma_f32_16x16x32_bf16 v[46:49], v[146:149], v[214:217], v[46:49]
	v_mfma_f32_16x16x32_bf16 v[42:45], v[158:161], v[214:217], v[42:45]
	v_mfma_f32_16x16x32_bf16 v[30:33], v[146:149], v[238:241], v[30:33]
	v_mfma_f32_16x16x32_bf16 v[26:29], v[158:161], v[238:241], v[26:29]
	v_mfma_f32_16x16x32_bf16 v[14:17], v[146:149], v[246:249], v[14:17]
	v_mfma_f32_16x16x32_bf16 v[10:13], v[158:161], v[246:249], v[10:13]
	v_mfma_f32_16x16x32_bf16 v[70:73], v[166:169], v[194:197], v[70:73]
	v_mfma_f32_16x16x32_bf16 v[66:69], v[174:177], v[194:197], v[66:69]
	v_mfma_f32_16x16x32_bf16 v[54:57], v[166:169], v[202:205], v[54:57]
	v_mfma_f32_16x16x32_bf16 v[50:53], v[174:177], v[202:205], v[50:53]
	v_mfma_f32_16x16x32_bf16 v[38:41], v[166:169], v[210:213], v[38:41]
	v_mfma_f32_16x16x32_bf16 v[34:37], v[174:177], v[210:213], v[34:37]
	v_mfma_f32_16x16x32_bf16 v[22:25], v[166:169], v[228:231], v[22:25]
	v_mfma_f32_16x16x32_bf16 v[18:21], v[174:177], v[228:231], v[18:21]
	v_mfma_f32_16x16x32_bf16 v[6:9], v[166:169], v[242:245], v[6:9]
	v_mfma_f32_16x16x32_bf16 v[2:5], v[174:177], v[242:245], v[2:5]
	v_mfma_f32_16x16x32_bf16 v[70:73], v[170:173], v[198:201], v[70:73]
	v_mfma_f32_16x16x32_bf16 v[66:69], v[178:181], v[198:201], v[66:69]
	v_mfma_f32_16x16x32_bf16 v[54:57], v[170:173], v[206:209], v[54:57]
	v_mfma_f32_16x16x32_bf16 v[50:53], v[178:181], v[206:209], v[50:53]
	v_mfma_f32_16x16x32_bf16 v[38:41], v[170:173], v[214:217], v[38:41]
	v_mfma_f32_16x16x32_bf16 v[34:37], v[178:181], v[214:217], v[34:37]
	v_mfma_f32_16x16x32_bf16 v[22:25], v[170:173], v[238:241], v[22:25]
	v_mfma_f32_16x16x32_bf16 v[18:21], v[178:181], v[238:241], v[18:21]
	v_mfma_f32_16x16x32_bf16 v[6:9], v[170:173], v[246:249], v[6:9]
	v_mfma_f32_16x16x32_bf16 v[2:5], v[178:181], v[246:249], v[2:5]
	s_barrier
	v_add_u32_e32 v158, 0x1c000, v223
	v_add_u32_e32 v178, 0x20000, v223
	ds_read_b128 v[142:145], v158
	ds_read_b128 v[146:149], v158 offset:1024
	ds_read_b128 v[154:157], v158 offset:2048
	ds_read_b128 v[158:161], v158 offset:3072
	ds_read_b128 v[166:169], v178
	ds_read_b128 v[170:173], v178 offset:1024
	ds_read_b128 v[174:177], v178 offset:2048
	ds_read_b128 v[178:181], v178 offset:3072
	s_add_u32 s74, s10, 0xa0000
	s_addc_u32 s75, s11, 0
	s_mov_b32 m0, s37
	ds_read_b128 v[194:197], v221 offset:40960
	ds_read_b128 v[198:201], v221 offset:41984
	ds_read_b128 v[202:205], v221 offset:43008
	ds_read_b128 v[206:209], v221 offset:44032
	ds_read_b128 v[210:213], v221 offset:45056
	ds_read_b128 v[214:217], v221 offset:46080
	ds_read_b128 v[228:231], v221 offset:47104
	ds_read_b128 v[238:241], v221 offset:48128
	ds_read_b128 v[242:245], v221 offset:49152
	ds_read_b128 v[246:249], v221 offset:50176
	global_load_lds_dwordx4 v0, s[74:75]
	s_add_u32 s74, s10, 0xe0000
	s_addc_u32 s75, s11, 0
	s_mov_b32 m0, s38
	s_nop 0
	global_load_lds_dwordx4 v0, s[74:75]
	s_add_u32 s74, s10, 0x120000
	s_addc_u32 s75, s11, 0
	s_mov_b32 m0, s39
	s_nop 0
	global_load_lds_dwordx4 v0, s[74:75]
	s_waitcnt vmcnt(10) lgkmcnt(0)
	s_barrier
	v_mfma_f32_16x16x32_bf16 v[190:193], v[142:145], v[194:197], v[190:193]
	v_mfma_f32_16x16x32_bf16 v[186:189], v[154:157], v[194:197], v[186:189]
	v_mfma_f32_16x16x32_bf16 v[150:153], v[142:145], v[202:205], v[150:153]
	v_mfma_f32_16x16x32_bf16 v[138:141], v[154:157], v[202:205], v[138:141]
	v_mfma_f32_16x16x32_bf16 v[126:129], v[142:145], v[210:213], v[126:129]
	v_mfma_f32_16x16x32_bf16 v[122:125], v[154:157], v[210:213], v[122:125]
	v_mfma_f32_16x16x32_bf16 v[110:113], v[142:145], v[228:231], v[110:113]
	v_mfma_f32_16x16x32_bf16 v[106:109], v[154:157], v[228:231], v[106:109]
	v_mfma_f32_16x16x32_bf16 v[94:97], v[142:145], v[242:245], v[94:97]
	v_mfma_f32_16x16x32_bf16 v[90:93], v[154:157], v[242:245], v[90:93]
	v_mfma_f32_16x16x32_bf16 v[190:193], v[146:149], v[198:201], v[190:193]
	v_mfma_f32_16x16x32_bf16 v[186:189], v[158:161], v[198:201], v[186:189]
	v_mfma_f32_16x16x32_bf16 v[150:153], v[146:149], v[206:209], v[150:153]
	v_mfma_f32_16x16x32_bf16 v[138:141], v[158:161], v[206:209], v[138:141]
	v_mfma_f32_16x16x32_bf16 v[126:129], v[146:149], v[214:217], v[126:129]
	v_mfma_f32_16x16x32_bf16 v[122:125], v[158:161], v[214:217], v[122:125]
	v_mfma_f32_16x16x32_bf16 v[110:113], v[146:149], v[238:241], v[110:113]
	v_mfma_f32_16x16x32_bf16 v[106:109], v[158:161], v[238:241], v[106:109]
	v_mfma_f32_16x16x32_bf16 v[94:97], v[146:149], v[246:249], v[94:97]
	v_mfma_f32_16x16x32_bf16 v[90:93], v[158:161], v[246:249], v[90:93]
	v_mfma_f32_16x16x32_bf16 v[182:185], v[166:169], v[194:197], v[182:185]
	v_mfma_f32_16x16x32_bf16 v[162:165], v[174:177], v[194:197], v[162:165]
	v_mfma_f32_16x16x32_bf16 v[134:137], v[166:169], v[202:205], v[134:137]
	v_mfma_f32_16x16x32_bf16 v[130:133], v[174:177], v[202:205], v[130:133]
	v_mfma_f32_16x16x32_bf16 v[118:121], v[166:169], v[210:213], v[118:121]
	v_mfma_f32_16x16x32_bf16 v[114:117], v[174:177], v[210:213], v[114:117]
	v_mfma_f32_16x16x32_bf16 v[102:105], v[166:169], v[228:231], v[102:105]
	v_mfma_f32_16x16x32_bf16 v[98:101], v[174:177], v[228:231], v[98:101]
	v_mfma_f32_16x16x32_bf16 v[86:89], v[166:169], v[242:245], v[86:89]
	v_mfma_f32_16x16x32_bf16 v[82:85], v[174:177], v[242:245], v[82:85]
	v_mfma_f32_16x16x32_bf16 v[182:185], v[170:173], v[198:201], v[182:185]
	v_mfma_f32_16x16x32_bf16 v[162:165], v[178:181], v[198:201], v[162:165]
	v_mfma_f32_16x16x32_bf16 v[134:137], v[170:173], v[206:209], v[134:137]
	v_mfma_f32_16x16x32_bf16 v[130:133], v[178:181], v[206:209], v[130:133]
	v_mfma_f32_16x16x32_bf16 v[118:121], v[170:173], v[214:217], v[118:121]
	v_mfma_f32_16x16x32_bf16 v[114:117], v[178:181], v[214:217], v[114:117]
	v_mfma_f32_16x16x32_bf16 v[102:105], v[170:173], v[238:241], v[102:105]
	v_mfma_f32_16x16x32_bf16 v[98:101], v[178:181], v[238:241], v[98:101]
	v_mfma_f32_16x16x32_bf16 v[86:89], v[170:173], v[246:249], v[86:89]
	v_mfma_f32_16x16x32_bf16 v[82:85], v[178:181], v[246:249], v[82:85]
	s_barrier
	s_add_u32 s74, s22, 0x80
	s_addc_u32 s75, s23, 0
	s_mov_b32 m0, s42
	ds_read_b128 v[194:197], v221 offset:61440
	ds_read_b128 v[198:201], v221 offset:62464
	ds_read_b128 v[202:205], v221 offset:63488
	ds_read_b128 v[206:209], v221 offset:64512
	ds_read_b128 v[210:213], v222 offset:4096
	ds_read_b128 v[214:217], v222 offset:5120
	ds_read_b128 v[228:231], v222 offset:6144
	ds_read_b128 v[238:241], v222 offset:7168
	ds_read_b128 v[242:245], v222 offset:8192
	ds_read_b128 v[246:249], v222 offset:9216
	global_load_lds_dwordx4 v220, s[74:75]
	s_add_u32 s74, s22, 0x40080
	s_addc_u32 s75, s23, 0
	s_mov_b32 m0, s43
	s_nop 0
	global_load_lds_dwordx4 v220, s[74:75]
	s_add_u32 s74, s22, 0x80080
	s_addc_u32 s75, s23, 0
	s_mov_b32 m0, s56
	s_add_u32 s22, s22, 0xc0080
	global_load_lds_dwordx4 v220, s[74:75]
	s_addc_u32 s23, s23, 0
	s_mov_b32 m0, s58
	s_nop 0
	global_load_lds_dwordx4 v220, s[22:23]
	s_mov_b32 m0, s48
	s_nop 0
	global_load_lds_dwordx4 v0, s[16:17]
	s_add_u32 s16, s10, 0x40080
	s_addc_u32 s17, s11, 0
	s_mov_b32 m0, s50
	s_add_u32 s10, s10, 0x80080
	global_load_lds_dwordx4 v0, s[16:17]
	s_addc_u32 s11, s11, 0
	s_mov_b32 m0, s51
	s_nop 0
	global_load_lds_dwordx4 v0, s[10:11]
	s_waitcnt vmcnt(10) lgkmcnt(0)
	s_barrier
	v_mfma_f32_16x16x32_bf16 v[78:81], v[142:145], v[194:197], v[78:81]
	v_mfma_f32_16x16x32_bf16 v[74:77], v[154:157], v[194:197], v[74:77]
	v_mfma_f32_16x16x32_bf16 v[62:65], v[142:145], v[202:205], v[62:65]
	v_mfma_f32_16x16x32_bf16 v[58:61], v[154:157], v[202:205], v[58:61]
	v_mfma_f32_16x16x32_bf16 v[46:49], v[142:145], v[210:213], v[46:49]
	v_mfma_f32_16x16x32_bf16 v[42:45], v[154:157], v[210:213], v[42:45]
	v_mfma_f32_16x16x32_bf16 v[30:33], v[142:145], v[228:231], v[30:33]
	v_mfma_f32_16x16x32_bf16 v[26:29], v[154:157], v[228:231], v[26:29]
	v_mfma_f32_16x16x32_bf16 v[14:17], v[142:145], v[242:245], v[14:17]
	v_mfma_f32_16x16x32_bf16 v[10:13], v[154:157], v[242:245], v[10:13]
	v_mfma_f32_16x16x32_bf16 v[78:81], v[146:149], v[198:201], v[78:81]
	v_mfma_f32_16x16x32_bf16 v[74:77], v[158:161], v[198:201], v[74:77]
	v_mfma_f32_16x16x32_bf16 v[62:65], v[146:149], v[206:209], v[62:65]
	v_mfma_f32_16x16x32_bf16 v[58:61], v[158:161], v[206:209], v[58:61]
	v_mfma_f32_16x16x32_bf16 v[46:49], v[146:149], v[214:217], v[46:49]
	v_mfma_f32_16x16x32_bf16 v[42:45], v[158:161], v[214:217], v[42:45]
	v_mfma_f32_16x16x32_bf16 v[30:33], v[146:149], v[238:241], v[30:33]
	v_mfma_f32_16x16x32_bf16 v[26:29], v[158:161], v[238:241], v[26:29]
	v_mfma_f32_16x16x32_bf16 v[14:17], v[146:149], v[246:249], v[14:17]
	v_mfma_f32_16x16x32_bf16 v[10:13], v[158:161], v[246:249], v[10:13]
	v_mfma_f32_16x16x32_bf16 v[70:73], v[166:169], v[194:197], v[70:73]
	v_mfma_f32_16x16x32_bf16 v[66:69], v[174:177], v[194:197], v[66:69]
	v_mfma_f32_16x16x32_bf16 v[54:57], v[166:169], v[202:205], v[54:57]
	v_mfma_f32_16x16x32_bf16 v[50:53], v[174:177], v[202:205], v[50:53]
	v_mfma_f32_16x16x32_bf16 v[38:41], v[166:169], v[210:213], v[38:41]
	v_mfma_f32_16x16x32_bf16 v[34:37], v[174:177], v[210:213], v[34:37]
	v_mfma_f32_16x16x32_bf16 v[22:25], v[166:169], v[228:231], v[22:25]
	v_mfma_f32_16x16x32_bf16 v[18:21], v[174:177], v[228:231], v[18:21]
	v_mfma_f32_16x16x32_bf16 v[6:9], v[166:169], v[242:245], v[6:9]
	v_mfma_f32_16x16x32_bf16 v[2:5], v[174:177], v[242:245], v[2:5]
	v_mfma_f32_16x16x32_bf16 v[70:73], v[170:173], v[198:201], v[70:73]
	v_mfma_f32_16x16x32_bf16 v[66:69], v[178:181], v[198:201], v[66:69]
	v_mfma_f32_16x16x32_bf16 v[54:57], v[170:173], v[206:209], v[54:57]
	v_mfma_f32_16x16x32_bf16 v[50:53], v[178:181], v[206:209], v[50:53]
	v_mfma_f32_16x16x32_bf16 v[38:41], v[170:173], v[214:217], v[38:41]
	v_mfma_f32_16x16x32_bf16 v[34:37], v[178:181], v[214:217], v[34:37]
	v_mfma_f32_16x16x32_bf16 v[22:25], v[170:173], v[238:241], v[22:25]
	v_mfma_f32_16x16x32_bf16 v[18:21], v[178:181], v[238:241], v[18:21]
	v_mfma_f32_16x16x32_bf16 v[6:9], v[170:173], v[246:249], v[6:9]
	v_mfma_f32_16x16x32_bf16 v[2:5], v[178:181], v[246:249], v[2:5]
	s_barrier
	s_add_i32 s97, s97, 2
	s_add_u32 s6, s6, 0x100
	s_addc_u32 s7, s7, 0
	s_add_u32 s84, s84, 0x100
	s_addc_u32 s92, s92, 0
	s_cmp_gt_u32 s97, 29
	s_cbranch_scc0 .LBB0_1546
	s_and_b64 vcc, exec, s[12:13]
	s_cbranch_vccz .LBB0_1549
	s_barrier

.LBB0_1654:
	v_add_u32_e32 v130, 0x10000, v133
	ds_read_b128 v[136:139], v130
	ds_read_b128 v[140:143], v130 offset:1024
	ds_read_b128 v[144:147], v130 offset:2048
	ds_read_b128 v[148:151], v130 offset:3072
	v_add_u32_e32 v130, 0x14000, v133
	ds_read_b128 v[152:155], v130
	ds_read_b128 v[156:159], v130 offset:1024
	ds_read_b128 v[160:163], v130 offset:2048
	ds_read_b128 v[164:167], v130 offset:3072
	s_cmp_eq_u32 s70, 28
	s_cselect_b32 s6, s58, s62
	s_cselect_b32 s7, s15, s64
	s_cselect_b32 s22, s60, s66
	s_cselect_b32 s23, s13, s68
	s_add_u32 s16, s6, 0x80
	s_addc_u32 s17, s7, 0
	s_add_u32 s74, s62, 0x7ff80
	s_addc_u32 s75, s64, 0
	ds_read_b128 v[168:171], v134
	ds_read_b128 v[172:175], v134 offset:1024
	ds_read_b128 v[176:179], v134 offset:2048
	ds_read_b128 v[180:183], v134 offset:3072
	ds_read_b128 v[184:187], v134 offset:4096
	ds_read_b128 v[188:191], v134 offset:5120
	ds_read_b128 v[192:195], v134 offset:6144
	ds_read_b128 v[196:199], v134 offset:7168
	s_add_i32 m0, s26, 0xc000
	s_nop 0
	global_load_lds_dwordx4 v0, s[74:75]
	s_add_u32 s74, s62, 0xbff80
	s_addc_u32 s75, s64, 0
	s_add_i32 m0, s26, 0xe000
	s_nop 0
	global_load_lds_dwordx4 v0, s[74:75]
	s_waitcnt vmcnt(8) lgkmcnt(0)
	s_barrier
	v_mfma_f32_16x16x32_bf16 v[122:125], v[136:139], v[168:171], v[122:125]
	v_mfma_f32_16x16x32_bf16 v[114:117], v[144:147], v[168:171], v[114:117]
	v_mfma_f32_16x16x32_bf16 v[106:109], v[136:139], v[176:179], v[106:109]
	v_mfma_f32_16x16x32_bf16 v[98:101], v[144:147], v[176:179], v[98:101]
	v_mfma_f32_16x16x32_bf16 v[90:93], v[136:139], v[184:187], v[90:93]
	v_mfma_f32_16x16x32_bf16 v[82:85], v[144:147], v[184:187], v[82:85]
	v_mfma_f32_16x16x32_bf16 v[74:77], v[136:139], v[192:195], v[74:77]
	v_mfma_f32_16x16x32_bf16 v[66:69], v[144:147], v[192:195], v[66:69]
	v_mfma_f32_16x16x32_bf16 v[122:125], v[140:143], v[172:175], v[122:125]
	v_mfma_f32_16x16x32_bf16 v[114:117], v[148:151], v[172:175], v[114:117]
	v_mfma_f32_16x16x32_bf16 v[106:109], v[140:143], v[180:183], v[106:109]
	v_mfma_f32_16x16x32_bf16 v[98:101], v[148:151], v[180:183], v[98:101]
	v_mfma_f32_16x16x32_bf16 v[90:93], v[140:143], v[188:191], v[90:93]
	v_mfma_f32_16x16x32_bf16 v[82:85], v[148:151], v[188:191], v[82:85]
	v_mfma_f32_16x16x32_bf16 v[74:77], v[140:143], v[196:199], v[74:77]
	v_mfma_f32_16x16x32_bf16 v[66:69], v[148:151], v[196:199], v[66:69]
	v_mfma_f32_16x16x32_bf16 v[126:129], v[152:155], v[168:171], v[126:129]
	v_mfma_f32_16x16x32_bf16 v[118:121], v[160:163], v[168:171], v[118:121]
	v_mfma_f32_16x16x32_bf16 v[110:113], v[152:155], v[176:179], v[110:113]
	v_mfma_f32_16x16x32_bf16 v[102:105], v[160:163], v[176:179], v[102:105]
	v_mfma_f32_16x16x32_bf16 v[94:97], v[152:155], v[184:187], v[94:97]
	v_mfma_f32_16x16x32_bf16 v[86:89], v[160:163], v[184:187], v[86:89]
	v_mfma_f32_16x16x32_bf16 v[78:81], v[152:155], v[192:195], v[78:81]
	v_mfma_f32_16x16x32_bf16 v[70:73], v[160:163], v[192:195], v[70:73]
	v_mfma_f32_16x16x32_bf16 v[126:129], v[156:159], v[172:175], v[126:129]
	v_mfma_f32_16x16x32_bf16 v[118:121], v[164:167], v[172:175], v[118:121]
	v_mfma_f32_16x16x32_bf16 v[110:113], v[156:159], v[180:183], v[110:113]
	v_mfma_f32_16x16x32_bf16 v[102:105], v[164:167], v[180:183], v[102:105]
	v_mfma_f32_16x16x32_bf16 v[94:97], v[156:159], v[188:191], v[94:97]
	v_mfma_f32_16x16x32_bf16 v[86:89], v[164:167], v[188:191], v[86:89]
	v_mfma_f32_16x16x32_bf16 v[78:81], v[156:159], v[196:199], v[78:81]
	v_mfma_f32_16x16x32_bf16 v[70:73], v[164:167], v[196:199], v[70:73]
	s_barrier
	s_mov_b64 s[74:75], s[22:23]
	s_mov_b32 m0, s27
	ds_read_b128 v[168:171], v134 offset:16384
	ds_read_b128 v[172:175], v134 offset:17408
	ds_read_b128 v[176:179], v134 offset:18432
	ds_read_b128 v[180:183], v134 offset:19456
	ds_read_b128 v[184:187], v134 offset:20480
	ds_read_b128 v[188:191], v134 offset:21504
	ds_read_b128 v[192:195], v134 offset:22528
	ds_read_b128 v[196:199], v134 offset:23552
	global_load_lds_dwordx4 v132, s[74:75]
	s_add_u32 s74, s22, 0x40000
	s_addc_u32 s75, s23, 0
	s_mov_b32 m0, s28
	s_nop 0
	global_load_lds_dwordx4 v132, s[74:75]
	s_add_u32 s74, s22, 0x80000
	s_addc_u32 s75, s23, 0
	s_mov_b32 m0, s29
	s_nop 0
	global_load_lds_dwordx4 v132, s[74:75]
	s_add_u32 s74, s22, 0xc0000
	s_addc_u32 s75, s23, 0
	s_mov_b32 m0, s30
	s_nop 0
	global_load_lds_dwordx4 v132, s[74:75]
	s_mov_b64 s[74:75], s[6:7]
	s_mov_b32 m0, s26
	s_nop 0
	global_load_lds_dwordx4 v0, s[74:75]
	s_add_u32 s74, s6, 0x40000
	s_addc_u32 s75, s7, 0
	s_mov_b32 m0, s31
	s_nop 0
	global_load_lds_dwordx4 v0, s[74:75]
	s_waitcnt vmcnt(8) lgkmcnt(0)
	s_barrier
	v_mfma_f32_16x16x32_bf16 v[58:61], v[136:139], v[168:171], v[58:61]
	v_mfma_f32_16x16x32_bf16 v[50:53], v[144:147], v[168:171], v[50:53]
	v_mfma_f32_16x16x32_bf16 v[42:45], v[136:139], v[176:179], v[42:45]
	v_mfma_f32_16x16x32_bf16 v[34:37], v[144:147], v[176:179], v[34:37]
	v_mfma_f32_16x16x32_bf16 v[26:29], v[136:139], v[184:187], v[26:29]
	v_mfma_f32_16x16x32_bf16 v[18:21], v[144:147], v[184:187], v[18:21]
	v_mfma_f32_16x16x32_bf16 v[10:13], v[136:139], v[192:195], v[10:13]
	v_mfma_f32_16x16x32_bf16 v[2:5], v[144:147], v[192:195], v[2:5]
	v_mfma_f32_16x16x32_bf16 v[58:61], v[140:143], v[172:175], v[58:61]
	v_mfma_f32_16x16x32_bf16 v[50:53], v[148:151], v[172:175], v[50:53]
	v_mfma_f32_16x16x32_bf16 v[42:45], v[140:143], v[180:183], v[42:45]
	v_mfma_f32_16x16x32_bf16 v[34:37], v[148:151], v[180:183], v[34:37]
	v_mfma_f32_16x16x32_bf16 v[26:29], v[140:143], v[188:191], v[26:29]
	v_mfma_f32_16x16x32_bf16 v[18:21], v[148:151], v[188:191], v[18:21]
	v_mfma_f32_16x16x32_bf16 v[10:13], v[140:143], v[196:199], v[10:13]
	v_mfma_f32_16x16x32_bf16 v[2:5], v[148:151], v[196:199], v[2:5]
	v_mfma_f32_16x16x32_bf16 v[62:65], v[152:155], v[168:171], v[62:65]
	v_mfma_f32_16x16x32_bf16 v[54:57], v[160:163], v[168:171], v[54:57]
	v_mfma_f32_16x16x32_bf16 v[46:49], v[152:155], v[176:179], v[46:49]
	v_mfma_f32_16x16x32_bf16 v[38:41], v[160:163], v[176:179], v[38:41]
	v_mfma_f32_16x16x32_bf16 v[30:33], v[152:155], v[184:187], v[30:33]
	v_mfma_f32_16x16x32_bf16 v[22:25], v[160:163], v[184:187], v[22:25]
	v_mfma_f32_16x16x32_bf16 v[14:17], v[152:155], v[192:195], v[14:17]
	v_mfma_f32_16x16x32_bf16 v[6:9], v[160:163], v[192:195], v[6:9]
	v_mfma_f32_16x16x32_bf16 v[62:65], v[156:159], v[172:175], v[62:65]
	v_mfma_f32_16x16x32_bf16 v[54:57], v[164:167], v[172:175], v[54:57]
	v_mfma_f32_16x16x32_bf16 v[46:49], v[156:159], v[180:183], v[46:49]
	v_mfma_f32_16x16x32_bf16 v[38:41], v[164:167], v[180:183], v[38:41]
	v_mfma_f32_16x16x32_bf16 v[30:33], v[156:159], v[188:191], v[30:33]
	v_mfma_f32_16x16x32_bf16 v[22:25], v[164:167], v[188:191], v[22:25]
	v_mfma_f32_16x16x32_bf16 v[14:17], v[156:159], v[196:199], v[14:17]
	v_mfma_f32_16x16x32_bf16 v[6:9], v[164:167], v[196:199], v[6:9]
	s_barrier
	v_add_u32_e32 v130, 0x18000, v133
	ds_read_b128 v[136:139], v130
	ds_read_b128 v[140:143], v130 offset:1024
	ds_read_b128 v[144:147], v130 offset:2048
	ds_read_b128 v[148:151], v130 offset:3072
	v_add_u32_e32 v130, 0x1c000, v133
	ds_read_b128 v[152:155], v130
	ds_read_b128 v[156:159], v130 offset:1024
	ds_read_b128 v[160:163], v130 offset:2048
	ds_read_b128 v[164:167], v130 offset:3072
	s_add_u32 s74, s6, 0x80000
	s_addc_u32 s75, s7, 0
	s_mov_b32 m0, s34
	ds_read_b128 v[168:171], v134 offset:32768
	ds_read_b128 v[172:175], v134 offset:33792
	ds_read_b128 v[176:179], v134 offset:34816
	ds_read_b128 v[180:183], v134 offset:35840
	ds_read_b128 v[184:187], v134 offset:36864
	ds_read_b128 v[188:191], v134 offset:37888
	ds_read_b128 v[192:195], v134 offset:38912
	ds_read_b128 v[196:199], v134 offset:39936
	global_load_lds_dwordx4 v0, s[74:75]
	s_add_u32 s74, s6, 0xc0000
	s_addc_u32 s75, s7, 0
	s_mov_b32 m0, s35
	s_nop 0
	global_load_lds_dwordx4 v0, s[74:75]
	s_waitcnt vmcnt(8) lgkmcnt(0)
	s_barrier
	v_mfma_f32_16x16x32_bf16 v[122:125], v[136:139], v[168:171], v[122:125]
	v_mfma_f32_16x16x32_bf16 v[114:117], v[144:147], v[168:171], v[114:117]
	v_mfma_f32_16x16x32_bf16 v[106:109], v[136:139], v[176:179], v[106:109]
	v_mfma_f32_16x16x32_bf16 v[98:101], v[144:147], v[176:179], v[98:101]
	v_mfma_f32_16x16x32_bf16 v[90:93], v[136:139], v[184:187], v[90:93]
	v_mfma_f32_16x16x32_bf16 v[82:85], v[144:147], v[184:187], v[82:85]
	v_mfma_f32_16x16x32_bf16 v[74:77], v[136:139], v[192:195], v[74:77]
	v_mfma_f32_16x16x32_bf16 v[66:69], v[144:147], v[192:195], v[66:69]
	v_mfma_f32_16x16x32_bf16 v[122:125], v[140:143], v[172:175], v[122:125]
	v_mfma_f32_16x16x32_bf16 v[114:117], v[148:151], v[172:175], v[114:117]
	v_mfma_f32_16x16x32_bf16 v[106:109], v[140:143], v[180:183], v[106:109]
	v_mfma_f32_16x16x32_bf16 v[98:101], v[148:151], v[180:183], v[98:101]
	v_mfma_f32_16x16x32_bf16 v[90:93], v[140:143], v[188:191], v[90:93]
	v_mfma_f32_16x16x32_bf16 v[82:85], v[148:151], v[188:191], v[82:85]
	v_mfma_f32_16x16x32_bf16 v[74:77], v[140:143], v[196:199], v[74:77]
	v_mfma_f32_16x16x32_bf16 v[66:69], v[148:151], v[196:199], v[66:69]
	v_mfma_f32_16x16x32_bf16 v[126:129], v[152:155], v[168:171], v[126:129]
	v_mfma_f32_16x16x32_bf16 v[118:121], v[160:163], v[168:171], v[118:121]
	v_mfma_f32_16x16x32_bf16 v[110:113], v[152:155], v[176:179], v[110:113]
	v_mfma_f32_16x16x32_bf16 v[102:105], v[160:163], v[176:179], v[102:105]
	v_mfma_f32_16x16x32_bf16 v[94:97], v[152:155], v[184:187], v[94:97]
	v_mfma_f32_16x16x32_bf16 v[86:89], v[160:163], v[184:187], v[86:89]
	v_mfma_f32_16x16x32_bf16 v[78:81], v[152:155], v[192:195], v[78:81]
	v_mfma_f32_16x16x32_bf16 v[70:73], v[160:163], v[192:195], v[70:73]
	v_mfma_f32_16x16x32_bf16 v[126:129], v[156:159], v[172:175], v[126:129]
	v_mfma_f32_16x16x32_bf16 v[118:121], v[164:167], v[172:175], v[118:121]
	v_mfma_f32_16x16x32_bf16 v[110:113], v[156:159], v[180:183], v[110:113]
	v_mfma_f32_16x16x32_bf16 v[102:105], v[164:167], v[180:183], v[102:105]
	v_mfma_f32_16x16x32_bf16 v[94:97], v[156:159], v[188:191], v[94:97]
	v_mfma_f32_16x16x32_bf16 v[86:89], v[164:167], v[188:191], v[86:89]
	v_mfma_f32_16x16x32_bf16 v[78:81], v[156:159], v[196:199], v[78:81]
	v_mfma_f32_16x16x32_bf16 v[70:73], v[164:167], v[196:199], v[70:73]
	s_barrier
	s_add_u32 s74, s22, 0x80
	s_addc_u32 s75, s23, 0
	s_mov_b32 m0, s38
	ds_read_b128 v[168:171], v134 offset:49152
	ds_read_b128 v[172:175], v134 offset:50176
	ds_read_b128 v[176:179], v134 offset:51200
	ds_read_b128 v[180:183], v134 offset:52224
	ds_read_b128 v[184:187], v134 offset:53248
	ds_read_b128 v[188:191], v134 offset:54272
	ds_read_b128 v[192:195], v134 offset:55296
	ds_read_b128 v[196:199], v134 offset:56320
	global_load_lds_dwordx4 v132, s[74:75]
	s_add_u32 s74, s22, 0x40080
	s_addc_u32 s75, s23, 0
	s_mov_b32 m0, s39
	s_nop 0
	global_load_lds_dwordx4 v132, s[74:75]
	s_add_u32 s74, s22, 0x80080
	s_addc_u32 s75, s23, 0
	s_mov_b32 m0, s43
	s_add_u32 s22, s22, 0xc0080
	global_load_lds_dwordx4 v132, s[74:75]
	s_addc_u32 s23, s23, 0
	s_mov_b32 m0, s48
	s_add_u32 s6, s6, 0x40080
	global_load_lds_dwordx4 v132, s[22:23]
	s_mov_b32 m0, s41
	s_addc_u32 s7, s7, 0
	global_load_lds_dwordx4 v0, s[16:17]
	s_mov_b32 m0, s42
	s_nop 0
	global_load_lds_dwordx4 v0, s[6:7]
	s_waitcnt vmcnt(8) lgkmcnt(0)
	s_barrier
	v_mfma_f32_16x16x32_bf16 v[58:61], v[136:139], v[168:171], v[58:61]
	v_mfma_f32_16x16x32_bf16 v[50:53], v[144:147], v[168:171], v[50:53]
	v_mfma_f32_16x16x32_bf16 v[42:45], v[136:139], v[176:179], v[42:45]
	v_mfma_f32_16x16x32_bf16 v[34:37], v[144:147], v[176:179], v[34:37]
	v_mfma_f32_16x16x32_bf16 v[26:29], v[136:139], v[184:187], v[26:29]
	v_mfma_f32_16x16x32_bf16 v[18:21], v[144:147], v[184:187], v[18:21]
	v_mfma_f32_16x16x32_bf16 v[10:13], v[136:139], v[192:195], v[10:13]
	v_mfma_f32_16x16x32_bf16 v[2:5], v[144:147], v[192:195], v[2:5]
	v_mfma_f32_16x16x32_bf16 v[58:61], v[140:143], v[172:175], v[58:61]
	v_mfma_f32_16x16x32_bf16 v[50:53], v[148:151], v[172:175], v[50:53]
	v_mfma_f32_16x16x32_bf16 v[42:45], v[140:143], v[180:183], v[42:45]
	v_mfma_f32_16x16x32_bf16 v[34:37], v[148:151], v[180:183], v[34:37]
	v_mfma_f32_16x16x32_bf16 v[26:29], v[140:143], v[188:191], v[26:29]
	v_mfma_f32_16x16x32_bf16 v[18:21], v[148:151], v[188:191], v[18:21]
	v_mfma_f32_16x16x32_bf16 v[10:13], v[140:143], v[196:199], v[10:13]
	v_mfma_f32_16x16x32_bf16 v[2:5], v[148:151], v[196:199], v[2:5]
	v_mfma_f32_16x16x32_bf16 v[62:65], v[152:155], v[168:171], v[62:65]
	v_mfma_f32_16x16x32_bf16 v[54:57], v[160:163], v[168:171], v[54:57]
	v_mfma_f32_16x16x32_bf16 v[46:49], v[152:155], v[176:179], v[46:49]
	v_mfma_f32_16x16x32_bf16 v[38:41], v[160:163], v[176:179], v[38:41]
	v_mfma_f32_16x16x32_bf16 v[30:33], v[152:155], v[184:187], v[30:33]
	v_mfma_f32_16x16x32_bf16 v[22:25], v[160:163], v[184:187], v[22:25]
	v_mfma_f32_16x16x32_bf16 v[14:17], v[152:155], v[192:195], v[14:17]
	v_mfma_f32_16x16x32_bf16 v[6:9], v[160:163], v[192:195], v[6:9]
	v_mfma_f32_16x16x32_bf16 v[62:65], v[156:159], v[172:175], v[62:65]
	v_mfma_f32_16x16x32_bf16 v[54:57], v[164:167], v[172:175], v[54:57]
	v_mfma_f32_16x16x32_bf16 v[46:49], v[156:159], v[180:183], v[46:49]
	v_mfma_f32_16x16x32_bf16 v[38:41], v[164:167], v[180:183], v[38:41]
	v_mfma_f32_16x16x32_bf16 v[30:33], v[156:159], v[188:191], v[30:33]
	v_mfma_f32_16x16x32_bf16 v[22:25], v[164:167], v[188:191], v[22:25]
	v_mfma_f32_16x16x32_bf16 v[14:17], v[156:159], v[196:199], v[14:17]
	v_mfma_f32_16x16x32_bf16 v[6:9], v[164:167], v[196:199], v[6:9]
	s_barrier
	s_add_i32 s70, s70, 2
	s_add_u32 s62, s62, 0x100
	s_addc_u32 s64, s64, 0
	s_add_u32 s66, s66, 0x100
	s_addc_u32 s68, s68, 0
	s_cmp_gt_u32 s70, 29
	s_cbranch_scc0 .LBB0_1654
	s_and_b64 vcc, exec, s[10:11]
	s_cbranch_vccz .LBB0_1657
	s_barrier

.LBB0_1789:
	v_add_u32_e32 v174, 0x14000, v244
	v_add_u32_e32 v190, 0x18000, v244
	ds_read_b128 v[162:165], v174
	ds_read_b128 v[166:169], v174 offset:1024
	ds_read_b128 v[170:173], v174 offset:2048
	ds_read_b128 v[174:177], v174 offset:3072
	ds_read_b128 v[178:181], v190
	ds_read_b128 v[182:185], v190 offset:1024
	ds_read_b128 v[186:189], v190 offset:2048
	ds_read_b128 v[190:193], v190 offset:3072
	s_add_u32 s16, s14, 0xffe52080
	s_addc_u32 s17, s15, -1
	s_cmpk_eq_i32 s66, 0x52
	s_cselect_b32 s16, s6, s16
	s_cselect_b32 s17, s7, s17
	s_cselect_b32 s20, s12, s62
	s_cselect_b32 s21, s13, s64
	s_add_u32 s18, s16, 0x80
	s_addc_u32 s19, s17, 0
	s_mov_b64 s[74:75], s[14:15]
	ds_read_b128 v[194:197], v242
	ds_read_b128 v[198:201], v242 offset:1024
	ds_read_b128 v[202:205], v242 offset:2048
	ds_read_b128 v[206:209], v242 offset:3072
	ds_read_b128 v[210:213], v242 offset:4096
	ds_read_b128 v[214:217], v242 offset:5120
	ds_read_b128 v[218:221], v242 offset:6144
	ds_read_b128 v[228:231], v242 offset:7168
	ds_read_b128 v[236:239], v242 offset:8192
	ds_read_b128 v[246:249], v242 offset:9216
	s_add_i32 m0, s26, 0xf000
	s_nop 0
	global_load_lds_dwordx4 v0, s[74:75]
	s_add_u32 s74, s14, 0xac000
	s_addc_u32 s75, s15, 0
	s_mov_b32 m0, s48
	s_nop 0
	global_load_lds_dwordx4 v0, s[74:75]
	s_waitcnt vmcnt(8) lgkmcnt(0)
	s_barrier
	v_mfma_f32_16x16x32_bf16 v[158:161], v[162:165], v[194:197], v[158:161]
	v_mfma_f32_16x16x32_bf16 v[154:157], v[170:173], v[194:197], v[154:157]
	v_mfma_f32_16x16x32_bf16 v[142:145], v[162:165], v[202:205], v[142:145]
	v_mfma_f32_16x16x32_bf16 v[138:141], v[170:173], v[202:205], v[138:141]
	v_mfma_f32_16x16x32_bf16 v[126:129], v[162:165], v[210:213], v[126:129]
	v_mfma_f32_16x16x32_bf16 v[122:125], v[170:173], v[210:213], v[122:125]
	v_mfma_f32_16x16x32_bf16 v[110:113], v[162:165], v[218:221], v[110:113]
	v_mfma_f32_16x16x32_bf16 v[106:109], v[170:173], v[218:221], v[106:109]
	v_mfma_f32_16x16x32_bf16 v[94:97], v[162:165], v[236:239], v[94:97]
	v_mfma_f32_16x16x32_bf16 v[90:93], v[170:173], v[236:239], v[90:93]
	v_mfma_f32_16x16x32_bf16 v[158:161], v[166:169], v[198:201], v[158:161]
	v_mfma_f32_16x16x32_bf16 v[154:157], v[174:177], v[198:201], v[154:157]
	v_mfma_f32_16x16x32_bf16 v[142:145], v[166:169], v[206:209], v[142:145]
	v_mfma_f32_16x16x32_bf16 v[138:141], v[174:177], v[206:209], v[138:141]
	v_mfma_f32_16x16x32_bf16 v[126:129], v[166:169], v[214:217], v[126:129]
	v_mfma_f32_16x16x32_bf16 v[122:125], v[174:177], v[214:217], v[122:125]
	v_mfma_f32_16x16x32_bf16 v[110:113], v[166:169], v[228:231], v[110:113]
	v_mfma_f32_16x16x32_bf16 v[106:109], v[174:177], v[228:231], v[106:109]
	v_mfma_f32_16x16x32_bf16 v[94:97], v[166:169], v[246:249], v[94:97]
	v_mfma_f32_16x16x32_bf16 v[90:93], v[174:177], v[246:249], v[90:93]
	v_mfma_f32_16x16x32_bf16 v[150:153], v[178:181], v[194:197], v[150:153]
	v_mfma_f32_16x16x32_bf16 v[146:149], v[186:189], v[194:197], v[146:149]
	v_mfma_f32_16x16x32_bf16 v[134:137], v[178:181], v[202:205], v[134:137]
	v_mfma_f32_16x16x32_bf16 v[130:133], v[186:189], v[202:205], v[130:133]
	v_mfma_f32_16x16x32_bf16 v[118:121], v[178:181], v[210:213], v[118:121]
	v_mfma_f32_16x16x32_bf16 v[114:117], v[186:189], v[210:213], v[114:117]
	v_mfma_f32_16x16x32_bf16 v[102:105], v[178:181], v[218:221], v[102:105]
	v_mfma_f32_16x16x32_bf16 v[98:101], v[186:189], v[218:221], v[98:101]
	v_mfma_f32_16x16x32_bf16 v[86:89], v[178:181], v[236:239], v[86:89]
	v_mfma_f32_16x16x32_bf16 v[82:85], v[186:189], v[236:239], v[82:85]
	v_mfma_f32_16x16x32_bf16 v[150:153], v[182:185], v[198:201], v[150:153]
	v_mfma_f32_16x16x32_bf16 v[146:149], v[190:193], v[198:201], v[146:149]
	v_mfma_f32_16x16x32_bf16 v[134:137], v[182:185], v[206:209], v[134:137]
	v_mfma_f32_16x16x32_bf16 v[130:133], v[190:193], v[206:209], v[130:133]
	v_mfma_f32_16x16x32_bf16 v[118:121], v[182:185], v[214:217], v[118:121]
	v_mfma_f32_16x16x32_bf16 v[114:117], v[190:193], v[214:217], v[114:117]
	v_mfma_f32_16x16x32_bf16 v[102:105], v[182:185], v[228:231], v[102:105]
	v_mfma_f32_16x16x32_bf16 v[98:101], v[190:193], v[228:231], v[98:101]
	v_mfma_f32_16x16x32_bf16 v[86:89], v[182:185], v[246:249], v[86:89]
	v_mfma_f32_16x16x32_bf16 v[82:85], v[190:193], v[246:249], v[82:85]
	s_barrier
	s_mov_b64 s[74:75], s[20:21]
	s_mov_b32 m0, s27
	ds_read_b128 v[194:197], v242 offset:20480
	ds_read_b128 v[198:201], v242 offset:21504
	ds_read_b128 v[202:205], v242 offset:22528
	ds_read_b128 v[206:209], v242 offset:23552
	ds_read_b128 v[210:213], v242 offset:24576
	ds_read_b128 v[214:217], v242 offset:25600
	ds_read_b128 v[218:221], v242 offset:26624
	ds_read_b128 v[228:231], v242 offset:27648
	ds_read_b128 v[236:239], v242 offset:28672
	ds_read_b128 v[246:249], v242 offset:29696
	global_load_lds_dwordx4 v241, s[74:75]
	s_add_u32 s74, s20, 0xac000
	s_addc_u32 s75, s21, 0
	s_mov_b32 m0, s28
	s_nop 0
	global_load_lds_dwordx4 v241, s[74:75]
	s_add_u32 s74, s20, 0x158000
	s_addc_u32 s75, s21, 0
	s_mov_b32 m0, s29
	s_nop 0
	global_load_lds_dwordx4 v241, s[74:75]
	s_add_u32 s74, s20, 0x204000
	s_addc_u32 s75, s21, 0
	s_mov_b32 m0, s30
	s_nop 0
	global_load_lds_dwordx4 v241, s[74:75]
	s_mov_b64 s[74:75], s[16:17]
	s_mov_b32 m0, s26
	s_nop 0
	global_load_lds_dwordx4 v0, s[74:75]
	s_add_u32 s74, s16, 0xac000
	s_addc_u32 s75, s17, 0
	s_mov_b32 m0, s31
	s_nop 0
	global_load_lds_dwordx4 v0, s[74:75]
	s_waitcnt vmcnt(8) lgkmcnt(0)
	s_barrier
	v_mfma_f32_16x16x32_bf16 v[78:81], v[162:165], v[194:197], v[78:81]
	v_mfma_f32_16x16x32_bf16 v[74:77], v[170:173], v[194:197], v[74:77]
	v_mfma_f32_16x16x32_bf16 v[62:65], v[162:165], v[202:205], v[62:65]
	v_mfma_f32_16x16x32_bf16 v[58:61], v[170:173], v[202:205], v[58:61]
	v_mfma_f32_16x16x32_bf16 v[46:49], v[162:165], v[210:213], v[46:49]
	v_mfma_f32_16x16x32_bf16 v[42:45], v[170:173], v[210:213], v[42:45]
	v_mfma_f32_16x16x32_bf16 v[30:33], v[162:165], v[218:221], v[30:33]
	v_mfma_f32_16x16x32_bf16 v[26:29], v[170:173], v[218:221], v[26:29]
	v_mfma_f32_16x16x32_bf16 v[14:17], v[162:165], v[236:239], v[14:17]
	v_mfma_f32_16x16x32_bf16 v[10:13], v[170:173], v[236:239], v[10:13]
	v_mfma_f32_16x16x32_bf16 v[78:81], v[166:169], v[198:201], v[78:81]
	v_mfma_f32_16x16x32_bf16 v[74:77], v[174:177], v[198:201], v[74:77]
	v_mfma_f32_16x16x32_bf16 v[62:65], v[166:169], v[206:209], v[62:65]
	v_mfma_f32_16x16x32_bf16 v[58:61], v[174:177], v[206:209], v[58:61]
	v_mfma_f32_16x16x32_bf16 v[46:49], v[166:169], v[214:217], v[46:49]
	v_mfma_f32_16x16x32_bf16 v[42:45], v[174:177], v[214:217], v[42:45]
	v_mfma_f32_16x16x32_bf16 v[30:33], v[166:169], v[228:231], v[30:33]
	v_mfma_f32_16x16x32_bf16 v[26:29], v[174:177], v[228:231], v[26:29]
	v_mfma_f32_16x16x32_bf16 v[14:17], v[166:169], v[246:249], v[14:17]
	v_mfma_f32_16x16x32_bf16 v[10:13], v[174:177], v[246:249], v[10:13]
	v_mfma_f32_16x16x32_bf16 v[70:73], v[178:181], v[194:197], v[70:73]
	v_mfma_f32_16x16x32_bf16 v[66:69], v[186:189], v[194:197], v[66:69]
	v_mfma_f32_16x16x32_bf16 v[54:57], v[178:181], v[202:205], v[54:57]
	v_mfma_f32_16x16x32_bf16 v[50:53], v[186:189], v[202:205], v[50:53]
	v_mfma_f32_16x16x32_bf16 v[38:41], v[178:181], v[210:213], v[38:41]
	v_mfma_f32_16x16x32_bf16 v[34:37], v[186:189], v[210:213], v[34:37]
	v_mfma_f32_16x16x32_bf16 v[22:25], v[178:181], v[218:221], v[22:25]
	v_mfma_f32_16x16x32_bf16 v[18:21], v[186:189], v[218:221], v[18:21]
	v_mfma_f32_16x16x32_bf16 v[6:9], v[178:181], v[236:239], v[6:9]
	v_mfma_f32_16x16x32_bf16 v[2:5], v[186:189], v[236:239], v[2:5]
	v_mfma_f32_16x16x32_bf16 v[70:73], v[182:185], v[198:201], v[70:73]
	v_mfma_f32_16x16x32_bf16 v[66:69], v[190:193], v[198:201], v[66:69]
	v_mfma_f32_16x16x32_bf16 v[54:57], v[182:185], v[206:209], v[54:57]
	v_mfma_f32_16x16x32_bf16 v[50:53], v[190:193], v[206:209], v[50:53]
	v_mfma_f32_16x16x32_bf16 v[38:41], v[182:185], v[214:217], v[38:41]
	v_mfma_f32_16x16x32_bf16 v[34:37], v[190:193], v[214:217], v[34:37]
	v_mfma_f32_16x16x32_bf16 v[22:25], v[182:185], v[228:231], v[22:25]
	v_mfma_f32_16x16x32_bf16 v[18:21], v[190:193], v[228:231], v[18:21]
	v_mfma_f32_16x16x32_bf16 v[6:9], v[182:185], v[246:249], v[6:9]
	v_mfma_f32_16x16x32_bf16 v[2:5], v[190:193], v[246:249], v[2:5]
	s_barrier
	v_add_u32_e32 v174, 0x1c000, v244
	v_add_u32_e32 v190, 0x20000, v244
	ds_read_b128 v[162:165], v174
	ds_read_b128 v[166:169], v174 offset:1024
	ds_read_b128 v[170:173], v174 offset:2048
	ds_read_b128 v[174:177], v174 offset:3072
	ds_read_b128 v[178:181], v190
	ds_read_b128 v[182:185], v190 offset:1024
	ds_read_b128 v[186:189], v190 offset:2048
	ds_read_b128 v[190:193], v190 offset:3072
	s_add_u32 s74, s16, 0x1ae000
	s_addc_u32 s75, s17, 0
	s_mov_b32 m0, s34
	ds_read_b128 v[194:197], v242 offset:40960
	ds_read_b128 v[198:201], v242 offset:41984
	ds_read_b128 v[202:205], v242 offset:43008
	ds_read_b128 v[206:209], v242 offset:44032
	ds_read_b128 v[210:213], v242 offset:45056
	ds_read_b128 v[214:217], v242 offset:46080
	ds_read_b128 v[218:221], v242 offset:47104
	ds_read_b128 v[228:231], v242 offset:48128
	ds_read_b128 v[236:239], v242 offset:49152
	ds_read_b128 v[246:249], v242 offset:50176
	global_load_lds_dwordx4 v0, s[74:75]
	s_add_u32 s74, s16, 0x25a000
	s_addc_u32 s75, s17, 0
	s_mov_b32 m0, s35
	s_nop 0
	global_load_lds_dwordx4 v0, s[74:75]
	s_waitcnt vmcnt(8) lgkmcnt(0)
	s_barrier
	v_mfma_f32_16x16x32_bf16 v[158:161], v[162:165], v[194:197], v[158:161]
	v_mfma_f32_16x16x32_bf16 v[154:157], v[170:173], v[194:197], v[154:157]
	v_mfma_f32_16x16x32_bf16 v[142:145], v[162:165], v[202:205], v[142:145]
	v_mfma_f32_16x16x32_bf16 v[138:141], v[170:173], v[202:205], v[138:141]
	v_mfma_f32_16x16x32_bf16 v[126:129], v[162:165], v[210:213], v[126:129]
	v_mfma_f32_16x16x32_bf16 v[122:125], v[170:173], v[210:213], v[122:125]
	v_mfma_f32_16x16x32_bf16 v[110:113], v[162:165], v[218:221], v[110:113]
	v_mfma_f32_16x16x32_bf16 v[106:109], v[170:173], v[218:221], v[106:109]
	v_mfma_f32_16x16x32_bf16 v[94:97], v[162:165], v[236:239], v[94:97]
	v_mfma_f32_16x16x32_bf16 v[90:93], v[170:173], v[236:239], v[90:93]
	v_mfma_f32_16x16x32_bf16 v[158:161], v[166:169], v[198:201], v[158:161]
	v_mfma_f32_16x16x32_bf16 v[154:157], v[174:177], v[198:201], v[154:157]
	v_mfma_f32_16x16x32_bf16 v[142:145], v[166:169], v[206:209], v[142:145]
	v_mfma_f32_16x16x32_bf16 v[138:141], v[174:177], v[206:209], v[138:141]
	v_mfma_f32_16x16x32_bf16 v[126:129], v[166:169], v[214:217], v[126:129]
	v_mfma_f32_16x16x32_bf16 v[122:125], v[174:177], v[214:217], v[122:125]
	v_mfma_f32_16x16x32_bf16 v[110:113], v[166:169], v[228:231], v[110:113]
	v_mfma_f32_16x16x32_bf16 v[106:109], v[174:177], v[228:231], v[106:109]
	v_mfma_f32_16x16x32_bf16 v[94:97], v[166:169], v[246:249], v[94:97]
	v_mfma_f32_16x16x32_bf16 v[90:93], v[174:177], v[246:249], v[90:93]
	v_mfma_f32_16x16x32_bf16 v[150:153], v[178:181], v[194:197], v[150:153]
	v_mfma_f32_16x16x32_bf16 v[146:149], v[186:189], v[194:197], v[146:149]
	v_mfma_f32_16x16x32_bf16 v[134:137], v[178:181], v[202:205], v[134:137]
	v_mfma_f32_16x16x32_bf16 v[130:133], v[186:189], v[202:205], v[130:133]
	v_mfma_f32_16x16x32_bf16 v[118:121], v[178:181], v[210:213], v[118:121]
	v_mfma_f32_16x16x32_bf16 v[114:117], v[186:189], v[210:213], v[114:117]
	v_mfma_f32_16x16x32_bf16 v[102:105], v[178:181], v[218:221], v[102:105]
	v_mfma_f32_16x16x32_bf16 v[98:101], v[186:189], v[218:221], v[98:101]
	v_mfma_f32_16x16x32_bf16 v[86:89], v[178:181], v[236:239], v[86:89]
	v_mfma_f32_16x16x32_bf16 v[82:85], v[186:189], v[236:239], v[82:85]
	v_mfma_f32_16x16x32_bf16 v[150:153], v[182:185], v[198:201], v[150:153]
	v_mfma_f32_16x16x32_bf16 v[146:149], v[190:193], v[198:201], v[146:149]
	v_mfma_f32_16x16x32_bf16 v[134:137], v[182:185], v[206:209], v[134:137]
	v_mfma_f32_16x16x32_bf16 v[130:133], v[190:193], v[206:209], v[130:133]
	v_mfma_f32_16x16x32_bf16 v[118:121], v[182:185], v[214:217], v[118:121]
	v_mfma_f32_16x16x32_bf16 v[114:117], v[190:193], v[214:217], v[114:117]
	v_mfma_f32_16x16x32_bf16 v[102:105], v[182:185], v[228:231], v[102:105]
	v_mfma_f32_16x16x32_bf16 v[98:101], v[190:193], v[228:231], v[98:101]
	v_mfma_f32_16x16x32_bf16 v[86:89], v[182:185], v[246:249], v[86:89]
	v_mfma_f32_16x16x32_bf16 v[82:85], v[190:193], v[246:249], v[82:85]
	s_barrier
	s_add_u32 s74, s20, 0x80
	s_addc_u32 s75, s21, 0
	s_mov_b32 m0, s38
	ds_read_b128 v[194:197], v242 offset:61440
	ds_read_b128 v[198:201], v242 offset:62464
	ds_read_b128 v[202:205], v242 offset:63488
	ds_read_b128 v[206:209], v242 offset:64512
	ds_read_b128 v[210:213], v243 offset:4096
	ds_read_b128 v[214:217], v243 offset:5120
	ds_read_b128 v[218:221], v243 offset:6144
	ds_read_b128 v[228:231], v243 offset:7168
	ds_read_b128 v[236:239], v243 offset:8192
	ds_read_b128 v[246:249], v243 offset:9216
	global_load_lds_dwordx4 v241, s[74:75]
	s_add_u32 s74, s20, 0xac080
	s_addc_u32 s75, s21, 0
	s_mov_b32 m0, s39
	s_nop 0
	global_load_lds_dwordx4 v241, s[74:75]
	s_add_u32 s74, s20, 0x158080
	s_addc_u32 s75, s21, 0
	s_mov_b32 m0, s42
	s_add_u32 s20, s20, 0x204080
	global_load_lds_dwordx4 v241, s[74:75]
	s_addc_u32 s21, s21, 0
	s_mov_b32 m0, s43
	s_add_u32 s16, s16, 0xac080
	global_load_lds_dwordx4 v241, s[20:21]
	s_mov_b32 m0, s40
	s_addc_u32 s17, s17, 0
	global_load_lds_dwordx4 v0, s[18:19]
	s_mov_b32 m0, s41
	s_nop 0
	global_load_lds_dwordx4 v0, s[16:17]
	s_waitcnt vmcnt(8) lgkmcnt(0)
	s_barrier
	v_mfma_f32_16x16x32_bf16 v[78:81], v[162:165], v[194:197], v[78:81]
	v_mfma_f32_16x16x32_bf16 v[74:77], v[170:173], v[194:197], v[74:77]
	v_mfma_f32_16x16x32_bf16 v[62:65], v[162:165], v[202:205], v[62:65]
	v_mfma_f32_16x16x32_bf16 v[58:61], v[170:173], v[202:205], v[58:61]
	v_mfma_f32_16x16x32_bf16 v[46:49], v[162:165], v[210:213], v[46:49]
	v_mfma_f32_16x16x32_bf16 v[42:45], v[170:173], v[210:213], v[42:45]
	v_mfma_f32_16x16x32_bf16 v[30:33], v[162:165], v[218:221], v[30:33]
	v_mfma_f32_16x16x32_bf16 v[26:29], v[170:173], v[218:221], v[26:29]
	v_mfma_f32_16x16x32_bf16 v[14:17], v[162:165], v[236:239], v[14:17]
	v_mfma_f32_16x16x32_bf16 v[10:13], v[170:173], v[236:239], v[10:13]
	v_mfma_f32_16x16x32_bf16 v[78:81], v[166:169], v[198:201], v[78:81]
	v_mfma_f32_16x16x32_bf16 v[74:77], v[174:177], v[198:201], v[74:77]
	v_mfma_f32_16x16x32_bf16 v[62:65], v[166:169], v[206:209], v[62:65]
	v_mfma_f32_16x16x32_bf16 v[58:61], v[174:177], v[206:209], v[58:61]
	v_mfma_f32_16x16x32_bf16 v[46:49], v[166:169], v[214:217], v[46:49]
	v_mfma_f32_16x16x32_bf16 v[42:45], v[174:177], v[214:217], v[42:45]
	v_mfma_f32_16x16x32_bf16 v[30:33], v[166:169], v[228:231], v[30:33]
	v_mfma_f32_16x16x32_bf16 v[26:29], v[174:177], v[228:231], v[26:29]
	v_mfma_f32_16x16x32_bf16 v[14:17], v[166:169], v[246:249], v[14:17]
	v_mfma_f32_16x16x32_bf16 v[10:13], v[174:177], v[246:249], v[10:13]
	v_mfma_f32_16x16x32_bf16 v[70:73], v[178:181], v[194:197], v[70:73]
	v_mfma_f32_16x16x32_bf16 v[66:69], v[186:189], v[194:197], v[66:69]
	v_mfma_f32_16x16x32_bf16 v[54:57], v[178:181], v[202:205], v[54:57]
	v_mfma_f32_16x16x32_bf16 v[50:53], v[186:189], v[202:205], v[50:53]
	v_mfma_f32_16x16x32_bf16 v[38:41], v[178:181], v[210:213], v[38:41]
	v_mfma_f32_16x16x32_bf16 v[34:37], v[186:189], v[210:213], v[34:37]
	v_mfma_f32_16x16x32_bf16 v[22:25], v[178:181], v[218:221], v[22:25]
	v_mfma_f32_16x16x32_bf16 v[18:21], v[186:189], v[218:221], v[18:21]
	v_mfma_f32_16x16x32_bf16 v[6:9], v[178:181], v[236:239], v[6:9]
	v_mfma_f32_16x16x32_bf16 v[2:5], v[186:189], v[236:239], v[2:5]
	v_mfma_f32_16x16x32_bf16 v[70:73], v[182:185], v[198:201], v[70:73]
	v_mfma_f32_16x16x32_bf16 v[66:69], v[190:193], v[198:201], v[66:69]
	v_mfma_f32_16x16x32_bf16 v[54:57], v[182:185], v[206:209], v[54:57]
	v_mfma_f32_16x16x32_bf16 v[50:53], v[190:193], v[206:209], v[50:53]
	v_mfma_f32_16x16x32_bf16 v[38:41], v[182:185], v[214:217], v[38:41]
	v_mfma_f32_16x16x32_bf16 v[34:37], v[190:193], v[214:217], v[34:37]
	v_mfma_f32_16x16x32_bf16 v[22:25], v[182:185], v[228:231], v[22:25]
	v_mfma_f32_16x16x32_bf16 v[18:21], v[190:193], v[228:231], v[18:21]
	v_mfma_f32_16x16x32_bf16 v[6:9], v[182:185], v[246:249], v[6:9]
	v_mfma_f32_16x16x32_bf16 v[2:5], v[190:193], v[246:249], v[2:5]
	s_barrier
	s_add_i32 s66, s66, 2
	s_add_u32 s14, s14, 0x100
	s_addc_u32 s15, s15, 0
	s_add_u32 s62, s62, 0x100
	s_addc_u32 s64, s64, 0
	s_cmpk_gt_u32 s66, 0x53
	s_cbranch_scc0 .LBB0_1789
	s_and_b64 vcc, exec, s[10:11]
	s_cbranch_vccz .LBB0_1792
	s_barrier

.LBB0_1815:
	v_add_u32_e32 v174, 0x14000, v244
	v_add_u32_e32 v190, 0x18000, v244
	ds_read_b128 v[162:165], v174
	ds_read_b128 v[166:169], v174 offset:1024
	ds_read_b128 v[170:173], v174 offset:2048
	ds_read_b128 v[174:177], v174 offset:3072
	ds_read_b128 v[178:181], v190
	ds_read_b128 v[182:185], v190 offset:1024
	ds_read_b128 v[186:189], v190 offset:2048
	ds_read_b128 v[190:193], v190 offset:3072
	s_add_u32 s16, s14, 0xffe52080
	s_addc_u32 s17, s15, -1
	s_cmpk_eq_i32 s84, 0x52
	s_cselect_b32 s16, s4, s16
	s_cselect_b32 s17, s5, s17
	s_cselect_b32 s20, s12, s70
	s_cselect_b32 s21, s13, s72
	s_add_u32 s18, s16, 0x80
	s_addc_u32 s19, s17, 0
	s_mov_b64 s[74:75], s[14:15]
	ds_read_b128 v[194:197], v242
	ds_read_b128 v[198:201], v242 offset:1024
	ds_read_b128 v[202:205], v242 offset:2048
	ds_read_b128 v[206:209], v242 offset:3072
	ds_read_b128 v[210:213], v242 offset:4096
	ds_read_b128 v[214:217], v242 offset:5120
	ds_read_b128 v[218:221], v242 offset:6144
	ds_read_b128 v[228:231], v242 offset:7168
	ds_read_b128 v[246:249], v242 offset:8192
	ds_read_b128 v[236:239], v242 offset:9216
	s_add_i32 m0, s26, 0xf000
	s_nop 0
	global_load_lds_dwordx4 v0, s[74:75]
	s_add_u32 s74, s14, 0xac000
	s_addc_u32 s75, s15, 0
	s_mov_b32 m0, s56
	s_nop 0
	global_load_lds_dwordx4 v0, s[74:75]
	s_add_u32 s74, s14, 0x158000
	s_addc_u32 s75, s15, 0
	s_mov_b32 m0, s58
	s_nop 0
	global_load_lds_dwordx4 v0, s[74:75]
	s_waitcnt vmcnt(10) lgkmcnt(0)
	s_barrier
	v_mfma_f32_16x16x32_bf16 v[158:161], v[162:165], v[194:197], v[158:161]
	v_mfma_f32_16x16x32_bf16 v[154:157], v[170:173], v[194:197], v[154:157]
	v_mfma_f32_16x16x32_bf16 v[142:145], v[162:165], v[202:205], v[142:145]
	v_mfma_f32_16x16x32_bf16 v[138:141], v[170:173], v[202:205], v[138:141]
	v_mfma_f32_16x16x32_bf16 v[126:129], v[162:165], v[210:213], v[126:129]
	v_mfma_f32_16x16x32_bf16 v[122:125], v[170:173], v[210:213], v[122:125]
	v_mfma_f32_16x16x32_bf16 v[110:113], v[162:165], v[218:221], v[110:113]
	v_mfma_f32_16x16x32_bf16 v[106:109], v[170:173], v[218:221], v[106:109]
	v_mfma_f32_16x16x32_bf16 v[94:97], v[162:165], v[246:249], v[94:97]
	v_mfma_f32_16x16x32_bf16 v[90:93], v[170:173], v[246:249], v[90:93]
	v_mfma_f32_16x16x32_bf16 v[158:161], v[166:169], v[198:201], v[158:161]
	v_mfma_f32_16x16x32_bf16 v[154:157], v[174:177], v[198:201], v[154:157]
	v_mfma_f32_16x16x32_bf16 v[142:145], v[166:169], v[206:209], v[142:145]
	v_mfma_f32_16x16x32_bf16 v[138:141], v[174:177], v[206:209], v[138:141]
	v_mfma_f32_16x16x32_bf16 v[126:129], v[166:169], v[214:217], v[126:129]
	v_mfma_f32_16x16x32_bf16 v[122:125], v[174:177], v[214:217], v[122:125]
	v_mfma_f32_16x16x32_bf16 v[110:113], v[166:169], v[228:231], v[110:113]
	v_mfma_f32_16x16x32_bf16 v[106:109], v[174:177], v[228:231], v[106:109]
	v_mfma_f32_16x16x32_bf16 v[94:97], v[166:169], v[236:239], v[94:97]
	v_mfma_f32_16x16x32_bf16 v[90:93], v[174:177], v[236:239], v[90:93]
	v_mfma_f32_16x16x32_bf16 v[150:153], v[178:181], v[194:197], v[150:153]
	v_mfma_f32_16x16x32_bf16 v[146:149], v[186:189], v[194:197], v[146:149]
	v_mfma_f32_16x16x32_bf16 v[134:137], v[178:181], v[202:205], v[134:137]
	v_mfma_f32_16x16x32_bf16 v[130:133], v[186:189], v[202:205], v[130:133]
	v_mfma_f32_16x16x32_bf16 v[118:121], v[178:181], v[210:213], v[118:121]
	v_mfma_f32_16x16x32_bf16 v[114:117], v[186:189], v[210:213], v[114:117]
	v_mfma_f32_16x16x32_bf16 v[102:105], v[178:181], v[218:221], v[102:105]
	v_mfma_f32_16x16x32_bf16 v[98:101], v[186:189], v[218:221], v[98:101]
	v_mfma_f32_16x16x32_bf16 v[86:89], v[178:181], v[246:249], v[86:89]
	v_mfma_f32_16x16x32_bf16 v[82:85], v[186:189], v[246:249], v[82:85]
	v_mfma_f32_16x16x32_bf16 v[150:153], v[182:185], v[198:201], v[150:153]
	v_mfma_f32_16x16x32_bf16 v[146:149], v[190:193], v[198:201], v[146:149]
	v_mfma_f32_16x16x32_bf16 v[134:137], v[182:185], v[206:209], v[134:137]
	v_mfma_f32_16x16x32_bf16 v[130:133], v[190:193], v[206:209], v[130:133]
	v_mfma_f32_16x16x32_bf16 v[118:121], v[182:185], v[214:217], v[118:121]
	v_mfma_f32_16x16x32_bf16 v[114:117], v[190:193], v[214:217], v[114:117]
	v_mfma_f32_16x16x32_bf16 v[102:105], v[182:185], v[228:231], v[102:105]
	v_mfma_f32_16x16x32_bf16 v[98:101], v[190:193], v[228:231], v[98:101]
	v_mfma_f32_16x16x32_bf16 v[86:89], v[182:185], v[236:239], v[86:89]
	v_mfma_f32_16x16x32_bf16 v[82:85], v[190:193], v[236:239], v[82:85]
	s_barrier
	s_mov_b64 s[74:75], s[20:21]
	s_mov_b32 m0, s27
	ds_read_b128 v[194:197], v242 offset:20480
	ds_read_b128 v[198:201], v242 offset:21504
	ds_read_b128 v[202:205], v242 offset:22528
	ds_read_b128 v[206:209], v242 offset:23552
	ds_read_b128 v[210:213], v242 offset:24576
	ds_read_b128 v[214:217], v242 offset:25600
	ds_read_b128 v[218:221], v242 offset:26624
	ds_read_b128 v[228:231], v242 offset:27648
	ds_read_b128 v[236:239], v242 offset:28672
	ds_read_b128 v[246:249], v242 offset:29696
	global_load_lds_dwordx4 v241, s[74:75]
	s_add_u32 s74, s20, 0xac000
	s_addc_u32 s75, s21, 0
	s_mov_b32 m0, s28
	s_nop 0
	global_load_lds_dwordx4 v241, s[74:75]
	s_add_u32 s74, s20, 0x158000
	s_addc_u32 s75, s21, 0
	s_mov_b32 m0, s29
	s_nop 0
	global_load_lds_dwordx4 v241, s[74:75]
	s_add_u32 s74, s20, 0x204000
	s_addc_u32 s75, s21, 0
	s_mov_b32 m0, s30
	s_nop 0
	global_load_lds_dwordx4 v241, s[74:75]
	s_mov_b64 s[74:75], s[16:17]
	s_mov_b32 m0, s26
	s_nop 0
	global_load_lds_dwordx4 v0, s[74:75]
	s_add_u32 s74, s16, 0xac000
	s_addc_u32 s75, s17, 0
	s_mov_b32 m0, s31
	s_nop 0
	global_load_lds_dwordx4 v0, s[74:75]
	s_add_u32 s74, s16, 0x158000
	s_addc_u32 s75, s17, 0
	s_mov_b32 m0, s34
	s_nop 0
	global_load_lds_dwordx4 v0, s[74:75]
	s_waitcnt vmcnt(10) lgkmcnt(0)
	s_barrier
	v_mfma_f32_16x16x32_bf16 v[78:81], v[162:165], v[194:197], v[78:81]
	v_mfma_f32_16x16x32_bf16 v[74:77], v[170:173], v[194:197], v[74:77]
	v_mfma_f32_16x16x32_bf16 v[62:65], v[162:165], v[202:205], v[62:65]
	v_mfma_f32_16x16x32_bf16 v[58:61], v[170:173], v[202:205], v[58:61]
	v_mfma_f32_16x16x32_bf16 v[46:49], v[162:165], v[210:213], v[46:49]
	v_mfma_f32_16x16x32_bf16 v[42:45], v[170:173], v[210:213], v[42:45]
	v_mfma_f32_16x16x32_bf16 v[30:33], v[162:165], v[218:221], v[30:33]
	v_mfma_f32_16x16x32_bf16 v[26:29], v[170:173], v[218:221], v[26:29]
	v_mfma_f32_16x16x32_bf16 v[14:17], v[162:165], v[236:239], v[14:17]
	v_mfma_f32_16x16x32_bf16 v[10:13], v[170:173], v[236:239], v[10:13]
	v_mfma_f32_16x16x32_bf16 v[78:81], v[166:169], v[198:201], v[78:81]
	v_mfma_f32_16x16x32_bf16 v[74:77], v[174:177], v[198:201], v[74:77]
	v_mfma_f32_16x16x32_bf16 v[62:65], v[166:169], v[206:209], v[62:65]
	v_mfma_f32_16x16x32_bf16 v[58:61], v[174:177], v[206:209], v[58:61]
	v_mfma_f32_16x16x32_bf16 v[46:49], v[166:169], v[214:217], v[46:49]
	v_mfma_f32_16x16x32_bf16 v[42:45], v[174:177], v[214:217], v[42:45]
	v_mfma_f32_16x16x32_bf16 v[30:33], v[166:169], v[228:231], v[30:33]
	v_mfma_f32_16x16x32_bf16 v[26:29], v[174:177], v[228:231], v[26:29]
	v_mfma_f32_16x16x32_bf16 v[14:17], v[166:169], v[246:249], v[14:17]
	v_mfma_f32_16x16x32_bf16 v[10:13], v[174:177], v[246:249], v[10:13]
	v_mfma_f32_16x16x32_bf16 v[70:73], v[178:181], v[194:197], v[70:73]
	v_mfma_f32_16x16x32_bf16 v[66:69], v[186:189], v[194:197], v[66:69]
	v_mfma_f32_16x16x32_bf16 v[54:57], v[178:181], v[202:205], v[54:57]
	v_mfma_f32_16x16x32_bf16 v[50:53], v[186:189], v[202:205], v[50:53]
	v_mfma_f32_16x16x32_bf16 v[38:41], v[178:181], v[210:213], v[38:41]
	v_mfma_f32_16x16x32_bf16 v[34:37], v[186:189], v[210:213], v[34:37]
	v_mfma_f32_16x16x32_bf16 v[22:25], v[178:181], v[218:221], v[22:25]
	v_mfma_f32_16x16x32_bf16 v[18:21], v[186:189], v[218:221], v[18:21]
	v_mfma_f32_16x16x32_bf16 v[6:9], v[178:181], v[236:239], v[6:9]
	v_mfma_f32_16x16x32_bf16 v[2:5], v[186:189], v[236:239], v[2:5]
	v_mfma_f32_16x16x32_bf16 v[70:73], v[182:185], v[198:201], v[70:73]
	v_mfma_f32_16x16x32_bf16 v[66:69], v[190:193], v[198:201], v[66:69]
	v_mfma_f32_16x16x32_bf16 v[54:57], v[182:185], v[206:209], v[54:57]
	v_mfma_f32_16x16x32_bf16 v[50:53], v[190:193], v[206:209], v[50:53]
	v_mfma_f32_16x16x32_bf16 v[38:41], v[182:185], v[214:217], v[38:41]
	v_mfma_f32_16x16x32_bf16 v[34:37], v[190:193], v[214:217], v[34:37]
	v_mfma_f32_16x16x32_bf16 v[22:25], v[182:185], v[228:231], v[22:25]
	v_mfma_f32_16x16x32_bf16 v[18:21], v[190:193], v[228:231], v[18:21]
	v_mfma_f32_16x16x32_bf16 v[6:9], v[182:185], v[246:249], v[6:9]
	v_mfma_f32_16x16x32_bf16 v[2:5], v[190:193], v[246:249], v[2:5]
	s_barrier
	v_add_u32_e32 v174, 0x1c000, v244
	v_add_u32_e32 v190, 0x20000, v244
	ds_read_b128 v[162:165], v174
	ds_read_b128 v[166:169], v174 offset:1024
	ds_read_b128 v[170:173], v174 offset:2048
	ds_read_b128 v[174:177], v174 offset:3072
	ds_read_b128 v[178:181], v190
	ds_read_b128 v[182:185], v190 offset:1024
	ds_read_b128 v[186:189], v190 offset:2048
	ds_read_b128 v[190:193], v190 offset:3072
	s_add_u32 s74, s16, 0x1ae000
	s_addc_u32 s75, s17, 0
	s_mov_b32 m0, s35
	ds_read_b128 v[194:197], v242 offset:40960
	ds_read_b128 v[198:201], v242 offset:41984
	ds_read_b128 v[202:205], v242 offset:43008
	ds_read_b128 v[206:209], v242 offset:44032
	ds_read_b128 v[210:213], v242 offset:45056
	ds_read_b128 v[214:217], v242 offset:46080
	ds_read_b128 v[218:221], v242 offset:47104
	ds_read_b128 v[228:231], v242 offset:48128
	ds_read_b128 v[236:239], v242 offset:49152
	ds_read_b128 v[246:249], v242 offset:50176
	global_load_lds_dwordx4 v0, s[74:75]
	s_add_u32 s74, s16, 0x25a000
	s_addc_u32 s75, s17, 0
	s_mov_b32 m0, s36
	s_nop 0
	global_load_lds_dwordx4 v0, s[74:75]
	s_add_u32 s74, s16, 0x306000
	s_addc_u32 s75, s17, 0
	s_mov_b32 m0, s37
	s_nop 0
	global_load_lds_dwordx4 v0, s[74:75]
	s_waitcnt vmcnt(10) lgkmcnt(0)
	s_barrier
	v_mfma_f32_16x16x32_bf16 v[158:161], v[162:165], v[194:197], v[158:161]
	v_mfma_f32_16x16x32_bf16 v[154:157], v[170:173], v[194:197], v[154:157]
	v_mfma_f32_16x16x32_bf16 v[142:145], v[162:165], v[202:205], v[142:145]
	v_mfma_f32_16x16x32_bf16 v[138:141], v[170:173], v[202:205], v[138:141]
	v_mfma_f32_16x16x32_bf16 v[126:129], v[162:165], v[210:213], v[126:129]
	v_mfma_f32_16x16x32_bf16 v[122:125], v[170:173], v[210:213], v[122:125]
	v_mfma_f32_16x16x32_bf16 v[110:113], v[162:165], v[218:221], v[110:113]
	v_mfma_f32_16x16x32_bf16 v[106:109], v[170:173], v[218:221], v[106:109]
	v_mfma_f32_16x16x32_bf16 v[94:97], v[162:165], v[236:239], v[94:97]
	v_mfma_f32_16x16x32_bf16 v[90:93], v[170:173], v[236:239], v[90:93]
	v_mfma_f32_16x16x32_bf16 v[158:161], v[166:169], v[198:201], v[158:161]
	v_mfma_f32_16x16x32_bf16 v[154:157], v[174:177], v[198:201], v[154:157]
	v_mfma_f32_16x16x32_bf16 v[142:145], v[166:169], v[206:209], v[142:145]
	v_mfma_f32_16x16x32_bf16 v[138:141], v[174:177], v[206:209], v[138:141]
	v_mfma_f32_16x16x32_bf16 v[126:129], v[166:169], v[214:217], v[126:129]
	v_mfma_f32_16x16x32_bf16 v[122:125], v[174:177], v[214:217], v[122:125]
	v_mfma_f32_16x16x32_bf16 v[110:113], v[166:169], v[228:231], v[110:113]
	v_mfma_f32_16x16x32_bf16 v[106:109], v[174:177], v[228:231], v[106:109]
	v_mfma_f32_16x16x32_bf16 v[94:97], v[166:169], v[246:249], v[94:97]
	v_mfma_f32_16x16x32_bf16 v[90:93], v[174:177], v[246:249], v[90:93]
	v_mfma_f32_16x16x32_bf16 v[150:153], v[178:181], v[194:197], v[150:153]
	v_mfma_f32_16x16x32_bf16 v[146:149], v[186:189], v[194:197], v[146:149]
	v_mfma_f32_16x16x32_bf16 v[134:137], v[178:181], v[202:205], v[134:137]
	v_mfma_f32_16x16x32_bf16 v[130:133], v[186:189], v[202:205], v[130:133]
	v_mfma_f32_16x16x32_bf16 v[118:121], v[178:181], v[210:213], v[118:121]
	v_mfma_f32_16x16x32_bf16 v[114:117], v[186:189], v[210:213], v[114:117]
	v_mfma_f32_16x16x32_bf16 v[102:105], v[178:181], v[218:221], v[102:105]
	v_mfma_f32_16x16x32_bf16 v[98:101], v[186:189], v[218:221], v[98:101]
	v_mfma_f32_16x16x32_bf16 v[86:89], v[178:181], v[236:239], v[86:89]
	v_mfma_f32_16x16x32_bf16 v[82:85], v[186:189], v[236:239], v[82:85]
	v_mfma_f32_16x16x32_bf16 v[150:153], v[182:185], v[198:201], v[150:153]
	v_mfma_f32_16x16x32_bf16 v[146:149], v[190:193], v[198:201], v[146:149]
	v_mfma_f32_16x16x32_bf16 v[134:137], v[182:185], v[206:209], v[134:137]
	v_mfma_f32_16x16x32_bf16 v[130:133], v[190:193], v[206:209], v[130:133]
	v_mfma_f32_16x16x32_bf16 v[118:121], v[182:185], v[214:217], v[118:121]
	v_mfma_f32_16x16x32_bf16 v[114:117], v[190:193], v[214:217], v[114:117]
	v_mfma_f32_16x16x32_bf16 v[102:105], v[182:185], v[228:231], v[102:105]
	v_mfma_f32_16x16x32_bf16 v[98:101], v[190:193], v[228:231], v[98:101]
	v_mfma_f32_16x16x32_bf16 v[86:89], v[182:185], v[246:249], v[86:89]
	v_mfma_f32_16x16x32_bf16 v[82:85], v[190:193], v[246:249], v[82:85]
	s_barrier
	s_add_u32 s74, s20, 0x80
	s_addc_u32 s75, s21, 0
	s_mov_b32 m0, s40
	ds_read_b128 v[194:197], v242 offset:61440
	ds_read_b128 v[198:201], v242 offset:62464
	ds_read_b128 v[202:205], v242 offset:63488
	ds_read_b128 v[206:209], v242 offset:64512
	ds_read_b128 v[210:213], v243 offset:4096
	ds_read_b128 v[214:217], v243 offset:5120
	ds_read_b128 v[218:221], v243 offset:6144
	ds_read_b128 v[228:231], v243 offset:7168
	ds_read_b128 v[236:239], v243 offset:8192
	ds_read_b128 v[246:249], v243 offset:9216
	global_load_lds_dwordx4 v241, s[74:75]
	s_add_u32 s74, s20, 0xac080
	s_addc_u32 s75, s21, 0
	s_mov_b32 m0, s41
	s_nop 0
	global_load_lds_dwordx4 v241, s[74:75]
	s_add_u32 s74, s20, 0x158080
	s_addc_u32 s75, s21, 0
	s_mov_b32 m0, s50
	s_add_u32 s20, s20, 0x204080
	global_load_lds_dwordx4 v241, s[74:75]
	s_addc_u32 s21, s21, 0
	s_mov_b32 m0, s51
	s_nop 0
	global_load_lds_dwordx4 v241, s[20:21]
	s_mov_b32 m0, s42
	s_nop 0
	global_load_lds_dwordx4 v0, s[18:19]
	s_add_u32 s18, s16, 0xac080
	s_addc_u32 s19, s17, 0
	s_mov_b32 m0, s43
	s_add_u32 s16, s16, 0x158080
	global_load_lds_dwordx4 v0, s[18:19]
	s_addc_u32 s17, s17, 0
	s_mov_b32 m0, s48
	s_nop 0
	global_load_lds_dwordx4 v0, s[16:17]
	s_waitcnt vmcnt(10) lgkmcnt(0)
	s_barrier
	v_mfma_f32_16x16x32_bf16 v[78:81], v[162:165], v[194:197], v[78:81]
	v_mfma_f32_16x16x32_bf16 v[74:77], v[170:173], v[194:197], v[74:77]
	v_mfma_f32_16x16x32_bf16 v[62:65], v[162:165], v[202:205], v[62:65]
	v_mfma_f32_16x16x32_bf16 v[58:61], v[170:173], v[202:205], v[58:61]
	v_mfma_f32_16x16x32_bf16 v[46:49], v[162:165], v[210:213], v[46:49]
	v_mfma_f32_16x16x32_bf16 v[42:45], v[170:173], v[210:213], v[42:45]
	v_mfma_f32_16x16x32_bf16 v[30:33], v[162:165], v[218:221], v[30:33]
	v_mfma_f32_16x16x32_bf16 v[26:29], v[170:173], v[218:221], v[26:29]
	v_mfma_f32_16x16x32_bf16 v[14:17], v[162:165], v[236:239], v[14:17]
	v_mfma_f32_16x16x32_bf16 v[10:13], v[170:173], v[236:239], v[10:13]
	v_mfma_f32_16x16x32_bf16 v[78:81], v[166:169], v[198:201], v[78:81]
	v_mfma_f32_16x16x32_bf16 v[74:77], v[174:177], v[198:201], v[74:77]
	v_mfma_f32_16x16x32_bf16 v[62:65], v[166:169], v[206:209], v[62:65]
	v_mfma_f32_16x16x32_bf16 v[58:61], v[174:177], v[206:209], v[58:61]
	v_mfma_f32_16x16x32_bf16 v[46:49], v[166:169], v[214:217], v[46:49]
	v_mfma_f32_16x16x32_bf16 v[42:45], v[174:177], v[214:217], v[42:45]
	v_mfma_f32_16x16x32_bf16 v[30:33], v[166:169], v[228:231], v[30:33]
	v_mfma_f32_16x16x32_bf16 v[26:29], v[174:177], v[228:231], v[26:29]
	v_mfma_f32_16x16x32_bf16 v[14:17], v[166:169], v[246:249], v[14:17]
	v_mfma_f32_16x16x32_bf16 v[10:13], v[174:177], v[246:249], v[10:13]
	v_mfma_f32_16x16x32_bf16 v[70:73], v[178:181], v[194:197], v[70:73]
	v_mfma_f32_16x16x32_bf16 v[66:69], v[186:189], v[194:197], v[66:69]
	v_mfma_f32_16x16x32_bf16 v[54:57], v[178:181], v[202:205], v[54:57]
	v_mfma_f32_16x16x32_bf16 v[50:53], v[186:189], v[202:205], v[50:53]
	v_mfma_f32_16x16x32_bf16 v[38:41], v[178:181], v[210:213], v[38:41]
	v_mfma_f32_16x16x32_bf16 v[34:37], v[186:189], v[210:213], v[34:37]
	v_mfma_f32_16x16x32_bf16 v[22:25], v[178:181], v[218:221], v[22:25]
	v_mfma_f32_16x16x32_bf16 v[18:21], v[186:189], v[218:221], v[18:21]
	v_mfma_f32_16x16x32_bf16 v[6:9], v[178:181], v[236:239], v[6:9]
	v_mfma_f32_16x16x32_bf16 v[2:5], v[186:189], v[236:239], v[2:5]
	v_mfma_f32_16x16x32_bf16 v[70:73], v[182:185], v[198:201], v[70:73]
	v_mfma_f32_16x16x32_bf16 v[66:69], v[190:193], v[198:201], v[66:69]
	v_mfma_f32_16x16x32_bf16 v[54:57], v[182:185], v[206:209], v[54:57]
	v_mfma_f32_16x16x32_bf16 v[50:53], v[190:193], v[206:209], v[50:53]
	v_mfma_f32_16x16x32_bf16 v[38:41], v[182:185], v[214:217], v[38:41]
	v_mfma_f32_16x16x32_bf16 v[34:37], v[190:193], v[214:217], v[34:37]
	v_mfma_f32_16x16x32_bf16 v[22:25], v[182:185], v[228:231], v[22:25]
	v_mfma_f32_16x16x32_bf16 v[18:21], v[190:193], v[228:231], v[18:21]
	v_mfma_f32_16x16x32_bf16 v[6:9], v[182:185], v[246:249], v[6:9]
	v_mfma_f32_16x16x32_bf16 v[2:5], v[190:193], v[246:249], v[2:5]
	s_barrier
	s_add_i32 s84, s84, 2
	s_add_u32 s14, s14, 0x100
	s_addc_u32 s15, s15, 0
	s_add_u32 s70, s70, 0x100
	s_addc_u32 s72, s72, 0
	s_cmpk_gt_u32 s84, 0x53
	s_cbranch_scc0 .LBB0_1815
	s_and_b64 vcc, exec, s[10:11]
	s_cbranch_vccz .LBB0_1818
	s_barrier
